# scan GM prefetch + out-unit mo/gn prefetch (de-serialized ladders) + nt hint on up-proj U stores
# speedup vs baseline: 1.0056x; 1.0056x over previous
; __device__ __forceinline__ float bflo(unsigned w) { return __uint_as_float(w << 16); }
; __device__ __forceinline__ float bfhi(unsigned w) { return __uint_as_float(w & 0xffff0000u); }
; #define PACK_CARRY() (u32x4){cvt_pk_bf16(c0, c1), cvt_pk_bf16(c2, c3), cvt_pk_bf16(c4, c5), cvt_pk_bf16(c6, c7)}
; __device__ __forceinline__ void mlstm_scan_item(const Params& P, int item) {
;     ...
;         for (int j = 0; j < 16; ++j) { const int n = n0 + j; const float g = GM[n * 2], ml = GM[n * 2 + 1];
;             *(u32x4*)(p + (size_t)n * 32768) = PACK_CARRY();
;             if (hasn) np[(size_t)n * 128] = ncar;
;             if (wm) MPREV[n] = m;
;             const float mn = fmaxf(g + m, ml), sp = __expf(g + m - mn), sq = __expf(ml - mn);
;             c0 = sp * c0 + sq * bflo(cl[j].x); c1 = sp * c1 + sq * bfhi(cl[j].x); c2 = sp * c2 + sq * bflo(cl[j].y); c3 = sp * c3 + sq * bfhi(cl[j].y);
;             c4 = sp * c4 + sq * bflo(cl[j].z); c5 = sp * c5 + sq * bfhi(cl[j].z); c6 = sp * c6 + sq * bflo(cl[j].w); c7 = sp * c7 + sq * bfhi(cl[j].w);
;             ncar = sp * ncar + sq * nl[j]; m = mn; }
.LBB0_606:
	s_or_b64 exec, exec, s[18:19]
	v_lshl_add_u64 v[84:85], s[10:11], 0, v[74:75]
	s_mov_b32 s3, 0x60000
	v_add_co_u32_e32 v82, vcc, s3, v84
	v_lshl_add_u64 v[96:97], v[76:77], 0, s[50:51]
	s_nop 0
	v_addc_co_u32_e32 v83, vcc, 0, v85, vcc
	flat_load_dwordx2 v[94:95], v[82:83]
	global_load_dwordx2 v[214:215], v[82:83], off offset:8
	global_load_dwordx2 v[216:217], v[82:83], off offset:16
	global_load_dwordx2 v[218:219], v[82:83], off offset:24
	global_load_dwordx2 v[220:221], v[82:83], off offset:32
	global_load_dwordx2 v[222:223], v[82:83], off offset:40
	global_load_dwordx2 v[224:225], v[82:83], off offset:48
	global_load_dwordx2 v[226:227], v[82:83], off offset:56
	global_load_dwordx2 v[228:229], v[82:83], off offset:64
	global_load_dwordx2 v[230:231], v[82:83], off offset:72
	global_load_dwordx2 v[232:233], v[82:83], off offset:80
	global_load_dwordx2 v[234:235], v[82:83], off offset:88
	global_load_dwordx2 v[236:237], v[82:83], off offset:96
	global_load_dwordx2 v[238:239], v[82:83], off offset:104
	global_load_dwordx2 v[240:241], v[82:83], off offset:112
	global_load_dwordx2 v[242:243], v[82:83], off offset:120
	v_cvt_pk_bf16_f32 v100, v92, v93
	v_cvt_pk_bf16_f32 v101, v90, v91
	v_cvt_pk_bf16_f32 v102, v88, v89
	v_cvt_pk_bf16_f32 v103, v86, v87
	flat_store_dwordx4 v[96:97], v[100:103]
	s_and_saveexec_b64 s[18:19], s[14:15]
	s_cbranch_execz .LBB0_608
	v_add_co_u32_e32 v96, vcc, 0x100000, v80
	s_nop 1
	v_addc_co_u32_e32 v97, vcc, 0, v81, vcc
	flat_store_dword v[96:97], v117

; __device__ __forceinline__ float bflo(unsigned w) { return __uint_as_float(w << 16); }
; __device__ __forceinline__ float bfhi(unsigned w) { return __uint_as_float(w & 0xffff0000u); }
; #define PACK_CARRY() (u32x4){cvt_pk_bf16(c0, c1), cvt_pk_bf16(c2, c3), cvt_pk_bf16(c4, c5), cvt_pk_bf16(c6, c7)}
; __device__ __forceinline__ void mlstm_scan_item(const Params& P, int item) {
;     ...
;         for (int j = 0; j < 16; ++j) { const int n = n0 + j; const float g = GM[n * 2], ml = GM[n * 2 + 1];
;             *(u32x4*)(p + (size_t)n * 32768) = PACK_CARRY();
;             if (hasn) np[(size_t)n * 128] = ncar;
;             if (wm) MPREV[n] = m;
;             const float mn = fmaxf(g + m, ml), sp = __expf(g + m - mn), sq = __expf(ml - mn);
;             c0 = sp * c0 + sq * bflo(cl[j].x); c1 = sp * c1 + sq * bfhi(cl[j].x); c2 = sp * c2 + sq * bflo(cl[j].y); c3 = sp * c3 + sq * bfhi(cl[j].y);
;             c4 = sp * c4 + sq * bflo(cl[j].z); c5 = sp * c5 + sq * bfhi(cl[j].z); c6 = sp * c6 + sq * bflo(cl[j].w); c7 = sp * c7 + sq * bfhi(cl[j].w);
;             ncar = sp * ncar + sq * nl[j]; m = mn; }
.LBB0_610:
	s_or_b64 exec, exec, s[18:19]
	v_add_co_u32_e32 v96, vcc, 0x60000, v84
	s_waitcnt vmcnt(0) lgkmcnt(0)
	v_add_f32_e32 v94, v98, v94
	v_addc_co_u32_e32 v97, vcc, 0, v85, vcc
	v_mov_b32_e32 v96, v214
	v_mov_b32_e32 v97, v215
	v_max_f32_e32 v98, v95, v95
	v_max_f32_e32 v119, v94, v98
	v_sub_f32_e32 v95, v95, v119
	v_sub_f32_e32 v94, v94, v119
	v_mul_f32_e32 v95, 0x3fb8aa3b, v95
	v_mul_f32_e32 v94, 0x3fb8aa3b, v94
	v_exp_f32_e32 v123, v95
	v_exp_f32_e32 v124, v94
	v_lshlrev_b32_e32 v125, 16, v62
	v_mov_b32_e32 v122, v92
	v_mul_f32_e32 v92, v123, v125
	v_pk_fma_f32 v[94:95], v[122:123], v[124:125], v[92:93] op_sel_hi:[1,1,0]
	v_and_b32_e32 v125, 0xffff0000, v62
	v_mov_b32_e32 v122, v93
	v_mul_f32_e32 v62, v123, v125
	v_pk_fma_f32 v[102:103], v[122:123], v[124:125], v[62:63] op_sel_hi:[1,1,0]
	v_lshlrev_b32_e32 v125, 16, v63
	v_mov_b32_e32 v122, v90
	v_mul_f32_e32 v62, v123, v125
	v_pk_fma_f32 v[100:101], v[122:123], v[124:125], v[62:63] op_sel_hi:[1,1,0]
	v_and_b32_e32 v125, 0xffff0000, v63
	v_mov_b32_e32 v122, v91
	v_mul_f32_e32 v62, v123, v125
	v_pk_fma_f32 v[98:99], v[122:123], v[124:125], v[62:63] op_sel_hi:[1,1,0]
	v_lshlrev_b32_e32 v125, 16, v64
	v_mov_b32_e32 v122, v88
	v_mul_f32_e32 v62, v123, v125
	v_pk_fma_f32 v[92:93], v[122:123], v[124:125], v[62:63] op_sel_hi:[1,1,0]
	v_and_b32_e32 v125, 0xffff0000, v64
	v_mov_b32_e32 v122, v89
	v_mul_f32_e32 v62, v123, v125
	v_pk_fma_f32 v[90:91], v[122:123], v[124:125], v[62:63] op_sel_hi:[1,1,0]
	v_lshlrev_b32_e32 v125, 16, v65
	v_mov_b32_e32 v122, v86
	v_mul_f32_e32 v62, v123, v125
	v_pk_fma_f32 v[88:89], v[122:123], v[124:125], v[62:63] op_sel_hi:[1,1,0]
	v_and_b32_e32 v125, 0xffff0000, v65
	s_mov_b64 s[18:19], 0x1ae10000
	v_mov_b32_e32 v122, v87
	v_mul_f32_e32 v62, v123, v125
	v_mul_f32_e32 v118, v118, v123
	v_lshl_add_u64 v[120:121], v[76:77], 0, s[18:19]
	v_pk_fma_f32 v[86:87], v[122:123], v[124:125], v[62:63] op_sel_hi:[1,1,0]
	v_fmac_f32_e32 v118, v117, v124
	v_cvt_pk_bf16_f32 v62, v94, v102
	v_cvt_pk_bf16_f32 v63, v100, v98
	v_cvt_pk_bf16_f32 v64, v92, v90
	v_cvt_pk_bf16_f32 v65, v88, v86
	flat_store_dwordx4 v[120:121], v[62:65]
	s_and_saveexec_b64 s[18:19], s[14:15]
	s_cbranch_execz .LBB0_612
	v_add_co_u32_e32 v62, vcc, 0x100000, v80
	s_nop 1
	v_addc_co_u32_e32 v63, vcc, 0, v81, vcc
	flat_store_dword v[62:63], v118 offset:512

; __device__ __forceinline__ float bflo(unsigned w) { return __uint_as_float(w << 16); }
; __device__ __forceinline__ float bfhi(unsigned w) { return __uint_as_float(w & 0xffff0000u); }
; #define PACK_CARRY() (u32x4){cvt_pk_bf16(c0, c1), cvt_pk_bf16(c2, c3), cvt_pk_bf16(c4, c5), cvt_pk_bf16(c6, c7)}
; __device__ __forceinline__ void mlstm_scan_item(const Params& P, int item) {
;     ...
;         for (int j = 0; j < 16; ++j) { const int n = n0 + j; const float g = GM[n * 2], ml = GM[n * 2 + 1];
;             *(u32x4*)(p + (size_t)n * 32768) = PACK_CARRY();
;             if (hasn) np[(size_t)n * 128] = ncar;
;             if (wm) MPREV[n] = m;
;             const float mn = fmaxf(g + m, ml), sp = __expf(g + m - mn), sq = __expf(ml - mn);
;             c0 = sp * c0 + sq * bflo(cl[j].x); c1 = sp * c1 + sq * bfhi(cl[j].x); c2 = sp * c2 + sq * bflo(cl[j].y); c3 = sp * c3 + sq * bfhi(cl[j].y);
;             c4 = sp * c4 + sq * bflo(cl[j].z); c5 = sp * c5 + sq * bfhi(cl[j].z); c6 = sp * c6 + sq * bflo(cl[j].w); c7 = sp * c7 + sq * bfhi(cl[j].w);
;             ncar = sp * ncar + sq * nl[j]; m = mn; }
.LBB0_614:
	s_or_b64 exec, exec, s[18:19]
	v_add_co_u32_e32 v62, vcc, 0x60000, v84
	v_lshlrev_b32_e32 v121, 16, v58
	s_nop 0
	v_addc_co_u32_e32 v63, vcc, 0, v85, vcc
	v_mov_b32_e32 v64, v216
	v_mov_b32_e32 v65, v217
	v_add_f32_e32 v62, v119, v96
	v_max_f32_e32 v63, v97, v97
	v_max_f32_e32 v117, v62, v63
	v_sub_f32_e32 v63, v97, v117
	v_sub_f32_e32 v62, v62, v117
	v_mul_f32_e32 v63, 0x3fb8aa3b, v63
	v_mul_f32_e32 v62, 0x3fb8aa3b, v62
	v_exp_f32_e32 v95, v63
	v_exp_f32_e32 v120, v62
	s_mov_b64 s[18:19], 0x1ae20000
	v_lshl_add_u64 v[122:123], v[76:77], 0, s[18:19]
	v_mul_f32_e32 v62, v95, v121
	v_pk_fma_f32 v[62:63], v[94:95], v[120:121], v[62:63] op_sel_hi:[1,1,0]
	v_and_b32_e32 v121, 0xffff0000, v58
	v_mov_b32_e32 v103, v95
	v_mul_f32_e32 v58, v95, v121
	v_pk_fma_f32 v[102:103], v[102:103], v[120:121], v[58:59] op_sel_hi:[1,1,0]
	v_lshlrev_b32_e32 v121, 16, v59
	v_mov_b32_e32 v101, v95
	v_mul_f32_e32 v58, v95, v121
	v_pk_fma_f32 v[100:101], v[100:101], v[120:121], v[58:59] op_sel_hi:[1,1,0]
	v_and_b32_e32 v121, 0xffff0000, v59
	v_mov_b32_e32 v99, v95
	v_mul_f32_e32 v58, v95, v121
	v_pk_fma_f32 v[96:97], v[98:99], v[120:121], v[58:59] op_sel_hi:[1,1,0]
	v_lshlrev_b32_e32 v121, 16, v60
	v_mov_b32_e32 v93, v95
	v_mul_f32_e32 v58, v95, v121
	v_pk_fma_f32 v[98:99], v[92:93], v[120:121], v[58:59] op_sel_hi:[1,1,0]
	v_and_b32_e32 v121, 0xffff0000, v60
	v_mov_b32_e32 v91, v95
	v_mul_f32_e32 v58, v95, v121
	v_pk_fma_f32 v[92:93], v[90:91], v[120:121], v[58:59] op_sel_hi:[1,1,0]
	v_lshlrev_b32_e32 v121, 16, v61
	v_mov_b32_e32 v89, v95
	v_mul_f32_e32 v58, v95, v121
	v_pk_fma_f32 v[90:91], v[88:89], v[120:121], v[58:59] op_sel_hi:[1,1,0]
	v_and_b32_e32 v121, 0xffff0000, v61
	v_mov_b32_e32 v87, v95
	v_mul_f32_e32 v58, v95, v121
	v_mul_f32_e32 v116, v116, v95
	v_pk_fma_f32 v[86:87], v[86:87], v[120:121], v[58:59] op_sel_hi:[1,1,0]
	v_fmac_f32_e32 v116, v118, v120
	v_cvt_pk_bf16_f32 v58, v62, v102
	v_cvt_pk_bf16_f32 v59, v100, v96
	v_cvt_pk_bf16_f32 v60, v98, v92
	v_cvt_pk_bf16_f32 v61, v90, v86
	flat_store_dwordx4 v[122:123], v[58:61]
	s_and_saveexec_b64 s[18:19], s[14:15]
	s_cbranch_execz .LBB0_616
	v_add_co_u32_e32 v58, vcc, 0x100000, v80
	s_nop 1
	v_addc_co_u32_e32 v59, vcc, 0, v81, vcc
	flat_store_dword v[58:59], v116 offset:1024

; __device__ __forceinline__ float bflo(unsigned w) { return __uint_as_float(w << 16); }
; __device__ __forceinline__ float bfhi(unsigned w) { return __uint_as_float(w & 0xffff0000u); }
; #define PACK_CARRY() (u32x4){cvt_pk_bf16(c0, c1), cvt_pk_bf16(c2, c3), cvt_pk_bf16(c4, c5), cvt_pk_bf16(c6, c7)}
; __device__ __forceinline__ void mlstm_scan_item(const Params& P, int item) {
;     ...
;         for (int j = 0; j < 16; ++j) { const int n = n0 + j; const float g = GM[n * 2], ml = GM[n * 2 + 1];
;             *(u32x4*)(p + (size_t)n * 32768) = PACK_CARRY();
;             if (hasn) np[(size_t)n * 128] = ncar;
;             if (wm) MPREV[n] = m;
;             const float mn = fmaxf(g + m, ml), sp = __expf(g + m - mn), sq = __expf(ml - mn);
;             c0 = sp * c0 + sq * bflo(cl[j].x); c1 = sp * c1 + sq * bfhi(cl[j].x); c2 = sp * c2 + sq * bflo(cl[j].y); c3 = sp * c3 + sq * bfhi(cl[j].y);
;             c4 = sp * c4 + sq * bflo(cl[j].z); c5 = sp * c5 + sq * bfhi(cl[j].z); c6 = sp * c6 + sq * bflo(cl[j].w); c7 = sp * c7 + sq * bfhi(cl[j].w);
;             ncar = sp * ncar + sq * nl[j]; m = mn; }
.LBB0_618:
	s_or_b64 exec, exec, s[18:19]
	v_add_co_u32_e32 v58, vcc, 0x60000, v84
	v_lshlrev_b32_e32 v119, 16, v54
	s_nop 0
	v_addc_co_u32_e32 v59, vcc, 0, v85, vcc
	v_mov_b32_e32 v60, v218
	v_mov_b32_e32 v61, v219
	v_add_f32_e32 v58, v117, v64
	v_max_f32_e32 v59, v65, v65
	v_max_f32_e32 v117, v58, v59
	v_sub_f32_e32 v59, v65, v117
	v_sub_f32_e32 v58, v58, v117
	v_mul_f32_e32 v59, 0x3fb8aa3b, v59
	v_mul_f32_e32 v58, 0x3fb8aa3b, v58
	v_exp_f32_e32 v63, v59
	v_exp_f32_e32 v118, v58
	s_mov_b64 s[18:19], 0x1ae30000
	v_lshl_add_u64 v[120:121], v[76:77], 0, s[18:19]
	v_mul_f32_e32 v58, v63, v119
	v_pk_fma_f32 v[58:59], v[62:63], v[118:119], v[58:59] op_sel_hi:[1,1,0]
	v_and_b32_e32 v119, 0xffff0000, v54
	v_mov_b32_e32 v103, v63
	v_mul_f32_e32 v54, v63, v119
	v_pk_fma_f32 v[88:89], v[102:103], v[118:119], v[54:55] op_sel_hi:[1,1,0]
	v_lshlrev_b32_e32 v119, 16, v55
	v_mov_b32_e32 v101, v63
	v_mul_f32_e32 v54, v63, v119
	v_pk_fma_f32 v[64:65], v[100:101], v[118:119], v[54:55] op_sel_hi:[1,1,0]
	v_and_b32_e32 v119, 0xffff0000, v55
	v_mov_b32_e32 v97, v63
	v_mul_f32_e32 v54, v63, v119
	v_pk_fma_f32 v[96:97], v[96:97], v[118:119], v[54:55] op_sel_hi:[1,1,0]
	v_lshlrev_b32_e32 v119, 16, v56
	v_mov_b32_e32 v99, v63
	v_mul_f32_e32 v54, v63, v119
	v_pk_fma_f32 v[94:95], v[98:99], v[118:119], v[54:55] op_sel_hi:[1,1,0]
	v_and_b32_e32 v119, 0xffff0000, v56
	v_mov_b32_e32 v93, v63
	v_mul_f32_e32 v54, v63, v119
	v_pk_fma_f32 v[92:93], v[92:93], v[118:119], v[54:55] op_sel_hi:[1,1,0]
	v_lshlrev_b32_e32 v119, 16, v57
	v_mov_b32_e32 v91, v63
	v_mul_f32_e32 v54, v63, v119
	v_pk_fma_f32 v[90:91], v[90:91], v[118:119], v[54:55] op_sel_hi:[1,1,0]
	v_and_b32_e32 v119, 0xffff0000, v57
	v_mov_b32_e32 v87, v63
	v_mul_f32_e32 v54, v63, v119
	v_mul_f32_e32 v98, v115, v63
	v_pk_fma_f32 v[86:87], v[86:87], v[118:119], v[54:55] op_sel_hi:[1,1,0]
	v_fmac_f32_e32 v98, v116, v118
	v_cvt_pk_bf16_f32 v54, v58, v88
	v_cvt_pk_bf16_f32 v55, v64, v96
	v_cvt_pk_bf16_f32 v56, v94, v92
	v_cvt_pk_bf16_f32 v57, v90, v86
	flat_store_dwordx4 v[120:121], v[54:57]
	s_and_saveexec_b64 s[18:19], s[14:15]
	s_cbranch_execz .LBB0_620
	v_add_co_u32_e32 v54, vcc, 0x100000, v80
	s_nop 1
	v_addc_co_u32_e32 v55, vcc, 0, v81, vcc
	flat_store_dword v[54:55], v98 offset:1536

; __device__ __forceinline__ float bflo(unsigned w) { return __uint_as_float(w << 16); }
; __device__ __forceinline__ float bfhi(unsigned w) { return __uint_as_float(w & 0xffff0000u); }
; #define PACK_CARRY() (u32x4){cvt_pk_bf16(c0, c1), cvt_pk_bf16(c2, c3), cvt_pk_bf16(c4, c5), cvt_pk_bf16(c6, c7)}
; __device__ __forceinline__ void mlstm_scan_item(const Params& P, int item) {
;     ...
;         for (int j = 0; j < 16; ++j) { const int n = n0 + j; const float g = GM[n * 2], ml = GM[n * 2 + 1];
;             *(u32x4*)(p + (size_t)n * 32768) = PACK_CARRY();
;             if (hasn) np[(size_t)n * 128] = ncar;
;             if (wm) MPREV[n] = m;
;             const float mn = fmaxf(g + m, ml), sp = __expf(g + m - mn), sq = __expf(ml - mn);
;             c0 = sp * c0 + sq * bflo(cl[j].x); c1 = sp * c1 + sq * bfhi(cl[j].x); c2 = sp * c2 + sq * bflo(cl[j].y); c3 = sp * c3 + sq * bfhi(cl[j].y);
;             c4 = sp * c4 + sq * bflo(cl[j].z); c5 = sp * c5 + sq * bfhi(cl[j].z); c6 = sp * c6 + sq * bflo(cl[j].w); c7 = sp * c7 + sq * bfhi(cl[j].w);
;             ncar = sp * ncar + sq * nl[j]; m = mn; }
.LBB0_622:
	s_or_b64 exec, exec, s[18:19]
	v_add_co_u32_e32 v54, vcc, 0x60000, v84
	v_lshlrev_b32_e32 v101, 16, v50
	s_nop 0
	v_addc_co_u32_e32 v55, vcc, 0, v85, vcc
	v_mov_b32_e32 v56, v220
	v_mov_b32_e32 v57, v221
	v_add_f32_e32 v54, v117, v60
	v_max_f32_e32 v55, v61, v61
	v_max_f32_e32 v99, v54, v55
	v_sub_f32_e32 v55, v61, v99
	v_sub_f32_e32 v54, v54, v99
	v_mul_f32_e32 v55, 0x3fb8aa3b, v55
	v_mul_f32_e32 v54, 0x3fb8aa3b, v54
	v_exp_f32_e32 v59, v55
	v_exp_f32_e32 v100, v54
	s_mov_b64 s[18:19], 0x1ae40000
	v_lshl_add_u64 v[102:103], v[76:77], 0, s[18:19]
	v_mul_f32_e32 v54, v59, v101
	v_pk_fma_f32 v[54:55], v[58:59], v[100:101], v[54:55] op_sel_hi:[1,1,0]
	v_and_b32_e32 v101, 0xffff0000, v50
	v_mov_b32_e32 v89, v59
	v_mul_f32_e32 v50, v59, v101
	v_pk_fma_f32 v[88:89], v[88:89], v[100:101], v[50:51] op_sel_hi:[1,1,0]
	v_lshlrev_b32_e32 v101, 16, v51
	v_mov_b32_e32 v65, v59
	v_mul_f32_e32 v50, v59, v101
	v_pk_fma_f32 v[64:65], v[64:65], v[100:101], v[50:51] op_sel_hi:[1,1,0]
	v_and_b32_e32 v101, 0xffff0000, v51
	v_mov_b32_e32 v97, v59
	v_mul_f32_e32 v50, v59, v101
	v_pk_fma_f32 v[62:63], v[96:97], v[100:101], v[50:51] op_sel_hi:[1,1,0]
	v_lshlrev_b32_e32 v101, 16, v52
	v_mov_b32_e32 v95, v59
	v_mul_f32_e32 v50, v59, v101
	v_pk_fma_f32 v[60:61], v[94:95], v[100:101], v[50:51] op_sel_hi:[1,1,0]
	v_and_b32_e32 v101, 0xffff0000, v52
	v_mov_b32_e32 v93, v59
	v_mul_f32_e32 v50, v59, v101
	v_pk_fma_f32 v[92:93], v[92:93], v[100:101], v[50:51] op_sel_hi:[1,1,0]
	v_lshlrev_b32_e32 v101, 16, v53
	v_mov_b32_e32 v91, v59
	v_mul_f32_e32 v50, v59, v101
	v_pk_fma_f32 v[90:91], v[90:91], v[100:101], v[50:51] op_sel_hi:[1,1,0]
	v_and_b32_e32 v101, 0xffff0000, v53
	v_mov_b32_e32 v87, v59
	v_mul_f32_e32 v50, v59, v101
	v_mul_f32_e32 v94, v114, v59
	v_pk_fma_f32 v[86:87], v[86:87], v[100:101], v[50:51] op_sel_hi:[1,1,0]
	v_fmac_f32_e32 v94, v98, v100
	v_cvt_pk_bf16_f32 v50, v54, v88
	v_cvt_pk_bf16_f32 v51, v64, v62
	v_cvt_pk_bf16_f32 v52, v60, v92
	v_cvt_pk_bf16_f32 v53, v90, v86
	flat_store_dwordx4 v[102:103], v[50:53]
	s_and_saveexec_b64 s[18:19], s[14:15]
	s_cbranch_execz .LBB0_624
	v_add_co_u32_e32 v50, vcc, 0x100000, v80
	s_nop 1
	v_addc_co_u32_e32 v51, vcc, 0, v81, vcc
	flat_store_dword v[50:51], v94 offset:2048

; __device__ __forceinline__ float bflo(unsigned w) { return __uint_as_float(w << 16); }
; __device__ __forceinline__ float bfhi(unsigned w) { return __uint_as_float(w & 0xffff0000u); }
; #define PACK_CARRY() (u32x4){cvt_pk_bf16(c0, c1), cvt_pk_bf16(c2, c3), cvt_pk_bf16(c4, c5), cvt_pk_bf16(c6, c7)}
; __device__ __forceinline__ void mlstm_scan_item(const Params& P, int item) {
;     ...
;         for (int j = 0; j < 16; ++j) { const int n = n0 + j; const float g = GM[n * 2], ml = GM[n * 2 + 1];
;             *(u32x4*)(p + (size_t)n * 32768) = PACK_CARRY();
;             if (hasn) np[(size_t)n * 128] = ncar;
;             if (wm) MPREV[n] = m;
;             const float mn = fmaxf(g + m, ml), sp = __expf(g + m - mn), sq = __expf(ml - mn);
;             c0 = sp * c0 + sq * bflo(cl[j].x); c1 = sp * c1 + sq * bfhi(cl[j].x); c2 = sp * c2 + sq * bflo(cl[j].y); c3 = sp * c3 + sq * bfhi(cl[j].y);
;             c4 = sp * c4 + sq * bflo(cl[j].z); c5 = sp * c5 + sq * bfhi(cl[j].z); c6 = sp * c6 + sq * bflo(cl[j].w); c7 = sp * c7 + sq * bfhi(cl[j].w);
;             ncar = sp * ncar + sq * nl[j]; m = mn; }
.LBB0_626:
	s_or_b64 exec, exec, s[18:19]
	v_add_co_u32_e32 v50, vcc, 0x60000, v84
	v_lshlrev_b32_e32 v97, 16, v46
	s_nop 0
	v_addc_co_u32_e32 v51, vcc, 0, v85, vcc
	v_mov_b32_e32 v52, v222
	v_mov_b32_e32 v53, v223
	v_add_f32_e32 v50, v99, v56
	v_max_f32_e32 v51, v57, v57
	v_max_f32_e32 v95, v50, v51
	v_sub_f32_e32 v51, v57, v95
	v_sub_f32_e32 v50, v50, v95
	v_mul_f32_e32 v51, 0x3fb8aa3b, v51
	v_mul_f32_e32 v50, 0x3fb8aa3b, v50
	v_exp_f32_e32 v55, v51
	v_exp_f32_e32 v96, v50
	s_mov_b64 s[18:19], 0x1ae50000
	v_lshl_add_u64 v[98:99], v[76:77], 0, s[18:19]
	v_mul_f32_e32 v50, v55, v97
	v_pk_fma_f32 v[50:51], v[54:55], v[96:97], v[50:51] op_sel_hi:[1,1,0]
	v_and_b32_e32 v97, 0xffff0000, v46
	v_mov_b32_e32 v89, v55
	v_mul_f32_e32 v46, v55, v97
	v_pk_fma_f32 v[88:89], v[88:89], v[96:97], v[46:47] op_sel_hi:[1,1,0]
	v_lshlrev_b32_e32 v97, 16, v47
	v_mov_b32_e32 v65, v55
	v_mul_f32_e32 v46, v55, v97
	v_pk_fma_f32 v[64:65], v[64:65], v[96:97], v[46:47] op_sel_hi:[1,1,0]
	v_and_b32_e32 v97, 0xffff0000, v47
	v_mov_b32_e32 v63, v55
	v_mul_f32_e32 v46, v55, v97
	v_pk_fma_f32 v[62:63], v[62:63], v[96:97], v[46:47] op_sel_hi:[1,1,0]
	v_lshlrev_b32_e32 v97, 16, v48
	v_mov_b32_e32 v61, v55
	v_mul_f32_e32 v46, v55, v97
	v_pk_fma_f32 v[60:61], v[60:61], v[96:97], v[46:47] op_sel_hi:[1,1,0]
	v_and_b32_e32 v97, 0xffff0000, v48
	v_mov_b32_e32 v93, v55
	v_mul_f32_e32 v46, v55, v97
	v_pk_fma_f32 v[58:59], v[92:93], v[96:97], v[46:47] op_sel_hi:[1,1,0]
	v_lshlrev_b32_e32 v97, 16, v49
	v_mov_b32_e32 v91, v55
	v_mul_f32_e32 v46, v55, v97
	v_pk_fma_f32 v[56:57], v[90:91], v[96:97], v[46:47] op_sel_hi:[1,1,0]
	v_and_b32_e32 v97, 0xffff0000, v49
	v_mov_b32_e32 v87, v55
	v_mul_f32_e32 v46, v55, v97
	v_mul_f32_e32 v90, v113, v55
	v_pk_fma_f32 v[86:87], v[86:87], v[96:97], v[46:47] op_sel_hi:[1,1,0]
	v_fmac_f32_e32 v90, v94, v96
	v_cvt_pk_bf16_f32 v46, v50, v88
	v_cvt_pk_bf16_f32 v47, v64, v62
	v_cvt_pk_bf16_f32 v48, v60, v58
	v_cvt_pk_bf16_f32 v49, v56, v86
	flat_store_dwordx4 v[98:99], v[46:49]
	s_and_saveexec_b64 s[18:19], s[14:15]
	s_cbranch_execz .LBB0_628
	v_add_co_u32_e32 v46, vcc, 0x100000, v80
	s_nop 1
	v_addc_co_u32_e32 v47, vcc, 0, v81, vcc
	flat_store_dword v[46:47], v90 offset:2560

; __device__ __forceinline__ float bflo(unsigned w) { return __uint_as_float(w << 16); }
; __device__ __forceinline__ float bfhi(unsigned w) { return __uint_as_float(w & 0xffff0000u); }
; #define PACK_CARRY() (u32x4){cvt_pk_bf16(c0, c1), cvt_pk_bf16(c2, c3), cvt_pk_bf16(c4, c5), cvt_pk_bf16(c6, c7)}
; __device__ __forceinline__ void mlstm_scan_item(const Params& P, int item) {
;     ...
;         for (int j = 0; j < 16; ++j) { const int n = n0 + j; const float g = GM[n * 2], ml = GM[n * 2 + 1];
;             *(u32x4*)(p + (size_t)n * 32768) = PACK_CARRY();
;             if (hasn) np[(size_t)n * 128] = ncar;
;             if (wm) MPREV[n] = m;
;             const float mn = fmaxf(g + m, ml), sp = __expf(g + m - mn), sq = __expf(ml - mn);
;             c0 = sp * c0 + sq * bflo(cl[j].x); c1 = sp * c1 + sq * bfhi(cl[j].x); c2 = sp * c2 + sq * bflo(cl[j].y); c3 = sp * c3 + sq * bfhi(cl[j].y);
;             c4 = sp * c4 + sq * bflo(cl[j].z); c5 = sp * c5 + sq * bfhi(cl[j].z); c6 = sp * c6 + sq * bflo(cl[j].w); c7 = sp * c7 + sq * bfhi(cl[j].w);
;             ncar = sp * ncar + sq * nl[j]; m = mn; }
.LBB0_630:
	s_or_b64 exec, exec, s[18:19]
	v_add_co_u32_e32 v46, vcc, 0x60000, v84
	v_lshlrev_b32_e32 v93, 16, v42
	s_nop 0
	v_addc_co_u32_e32 v47, vcc, 0, v85, vcc
	v_mov_b32_e32 v48, v224
	v_mov_b32_e32 v49, v225
	v_add_f32_e32 v46, v95, v52
	v_max_f32_e32 v47, v53, v53
	v_max_f32_e32 v91, v46, v47
	v_sub_f32_e32 v47, v53, v91
	v_sub_f32_e32 v46, v46, v91
	v_mul_f32_e32 v47, 0x3fb8aa3b, v47
	v_mul_f32_e32 v46, 0x3fb8aa3b, v46
	v_exp_f32_e32 v51, v47
	v_exp_f32_e32 v92, v46
	s_mov_b64 s[18:19], 0x1ae60000
	v_lshl_add_u64 v[94:95], v[76:77], 0, s[18:19]
	v_mul_f32_e32 v46, v51, v93
	v_pk_fma_f32 v[46:47], v[50:51], v[92:93], v[46:47] op_sel_hi:[1,1,0]
	v_and_b32_e32 v93, 0xffff0000, v42
	v_mov_b32_e32 v89, v51
	v_mul_f32_e32 v42, v51, v93
	v_pk_fma_f32 v[52:53], v[88:89], v[92:93], v[42:43] op_sel_hi:[1,1,0]
	v_lshlrev_b32_e32 v93, 16, v43
	v_mov_b32_e32 v65, v51
	v_mul_f32_e32 v42, v51, v93
	v_pk_fma_f32 v[64:65], v[64:65], v[92:93], v[42:43] op_sel_hi:[1,1,0]
	v_and_b32_e32 v93, 0xffff0000, v43
	v_mov_b32_e32 v63, v51
	v_mul_f32_e32 v42, v51, v93
	v_pk_fma_f32 v[62:63], v[62:63], v[92:93], v[42:43] op_sel_hi:[1,1,0]
	v_lshlrev_b32_e32 v93, 16, v44
	v_mov_b32_e32 v61, v51
	v_mul_f32_e32 v42, v51, v93
	v_pk_fma_f32 v[60:61], v[60:61], v[92:93], v[42:43] op_sel_hi:[1,1,0]
	v_and_b32_e32 v93, 0xffff0000, v44
	v_mov_b32_e32 v59, v51
	v_mul_f32_e32 v42, v51, v93
	v_pk_fma_f32 v[58:59], v[58:59], v[92:93], v[42:43] op_sel_hi:[1,1,0]
	v_lshlrev_b32_e32 v93, 16, v45
	v_mov_b32_e32 v57, v51
	v_mul_f32_e32 v42, v51, v93
	v_pk_fma_f32 v[56:57], v[56:57], v[92:93], v[42:43] op_sel_hi:[1,1,0]
	v_and_b32_e32 v93, 0xffff0000, v45
	v_mov_b32_e32 v87, v51
	v_mul_f32_e32 v42, v51, v93
	v_pk_fma_f32 v[54:55], v[86:87], v[92:93], v[42:43] op_sel_hi:[1,1,0]
	v_mul_f32_e32 v86, v112, v51
	v_fmac_f32_e32 v86, v90, v92
	v_cvt_pk_bf16_f32 v42, v46, v52
	v_cvt_pk_bf16_f32 v43, v64, v62
	v_cvt_pk_bf16_f32 v44, v60, v58
	v_cvt_pk_bf16_f32 v45, v56, v54
	flat_store_dwordx4 v[94:95], v[42:45]
	s_and_saveexec_b64 s[18:19], s[14:15]
	s_cbranch_execz .LBB0_632
	v_add_co_u32_e32 v42, vcc, 0x100000, v80
	s_nop 1
	v_addc_co_u32_e32 v43, vcc, 0, v81, vcc
	flat_store_dword v[42:43], v86 offset:3072

; __device__ __forceinline__ float bflo(unsigned w) { return __uint_as_float(w << 16); }
; __device__ __forceinline__ float bfhi(unsigned w) { return __uint_as_float(w & 0xffff0000u); }
; #define PACK_CARRY() (u32x4){cvt_pk_bf16(c0, c1), cvt_pk_bf16(c2, c3), cvt_pk_bf16(c4, c5), cvt_pk_bf16(c6, c7)}
; __device__ __forceinline__ void mlstm_scan_item(const Params& P, int item) {
;     ...
;         for (int j = 0; j < 16; ++j) { const int n = n0 + j; const float g = GM[n * 2], ml = GM[n * 2 + 1];
;             *(u32x4*)(p + (size_t)n * 32768) = PACK_CARRY();
;             if (hasn) np[(size_t)n * 128] = ncar;
;             if (wm) MPREV[n] = m;
;             const float mn = fmaxf(g + m, ml), sp = __expf(g + m - mn), sq = __expf(ml - mn);
;             c0 = sp * c0 + sq * bflo(cl[j].x); c1 = sp * c1 + sq * bfhi(cl[j].x); c2 = sp * c2 + sq * bflo(cl[j].y); c3 = sp * c3 + sq * bfhi(cl[j].y);
;             c4 = sp * c4 + sq * bflo(cl[j].z); c5 = sp * c5 + sq * bfhi(cl[j].z); c6 = sp * c6 + sq * bflo(cl[j].w); c7 = sp * c7 + sq * bfhi(cl[j].w);
;             ncar = sp * ncar + sq * nl[j]; m = mn; }
.LBB0_634:
	s_or_b64 exec, exec, s[18:19]
	v_add_co_u32_e32 v42, vcc, 0x60000, v84
	v_lshlrev_b32_e32 v89, 16, v38
	s_nop 0
	v_addc_co_u32_e32 v43, vcc, 0, v85, vcc
	v_mov_b32_e32 v44, v226
	v_mov_b32_e32 v45, v227
	v_add_f32_e32 v42, v91, v48
	v_max_f32_e32 v43, v49, v49
	v_max_f32_e32 v87, v42, v43
	v_sub_f32_e32 v43, v49, v87
	v_sub_f32_e32 v42, v42, v87
	v_mul_f32_e32 v43, 0x3fb8aa3b, v43
	v_mul_f32_e32 v42, 0x3fb8aa3b, v42
	v_exp_f32_e32 v47, v43
	v_exp_f32_e32 v88, v42
	s_mov_b64 s[18:19], 0x1ae70000
	v_lshl_add_u64 v[90:91], v[76:77], 0, s[18:19]
	v_mul_f32_e32 v42, v47, v89
	v_pk_fma_f32 v[42:43], v[46:47], v[88:89], v[42:43] op_sel_hi:[1,1,0]
	v_and_b32_e32 v89, 0xffff0000, v38
	v_mov_b32_e32 v53, v47
	v_mul_f32_e32 v38, v47, v89
	v_pk_fma_f32 v[52:53], v[52:53], v[88:89], v[38:39] op_sel_hi:[1,1,0]
	v_lshlrev_b32_e32 v89, 16, v39
	v_mov_b32_e32 v65, v47
	v_mul_f32_e32 v38, v47, v89
	v_pk_fma_f32 v[50:51], v[64:65], v[88:89], v[38:39] op_sel_hi:[1,1,0]
	v_and_b32_e32 v89, 0xffff0000, v39
	v_mov_b32_e32 v63, v47
	v_mul_f32_e32 v38, v47, v89
	v_pk_fma_f32 v[48:49], v[62:63], v[88:89], v[38:39] op_sel_hi:[1,1,0]
	v_lshlrev_b32_e32 v89, 16, v40
	v_mov_b32_e32 v61, v47
	v_mul_f32_e32 v38, v47, v89
	v_pk_fma_f32 v[60:61], v[60:61], v[88:89], v[38:39] op_sel_hi:[1,1,0]
	v_and_b32_e32 v89, 0xffff0000, v40
	v_mov_b32_e32 v59, v47
	v_mul_f32_e32 v38, v47, v89
	v_pk_fma_f32 v[58:59], v[58:59], v[88:89], v[38:39] op_sel_hi:[1,1,0]
	v_lshlrev_b32_e32 v89, 16, v41
	v_mov_b32_e32 v57, v47
	v_mul_f32_e32 v38, v47, v89
	v_pk_fma_f32 v[56:57], v[56:57], v[88:89], v[38:39] op_sel_hi:[1,1,0]
	v_and_b32_e32 v89, 0xffff0000, v41
	v_mov_b32_e32 v55, v47
	v_mul_f32_e32 v38, v47, v89
	v_mul_f32_e32 v62, v111, v47
	v_pk_fma_f32 v[54:55], v[54:55], v[88:89], v[38:39] op_sel_hi:[1,1,0]
	v_fmac_f32_e32 v62, v86, v88
	v_cvt_pk_bf16_f32 v38, v42, v52
	v_cvt_pk_bf16_f32 v39, v50, v48
	v_cvt_pk_bf16_f32 v40, v60, v58
	v_cvt_pk_bf16_f32 v41, v56, v54
	flat_store_dwordx4 v[90:91], v[38:41]
	s_and_saveexec_b64 s[18:19], s[14:15]
	s_cbranch_execz .LBB0_636
	v_add_co_u32_e32 v38, vcc, 0x100000, v80
	s_nop 1
	v_addc_co_u32_e32 v39, vcc, 0, v81, vcc
	flat_store_dword v[38:39], v62 offset:3584

; __device__ __forceinline__ float bflo(unsigned w) { return __uint_as_float(w << 16); }
; __device__ __forceinline__ float bfhi(unsigned w) { return __uint_as_float(w & 0xffff0000u); }
; #define PACK_CARRY() (u32x4){cvt_pk_bf16(c0, c1), cvt_pk_bf16(c2, c3), cvt_pk_bf16(c4, c5), cvt_pk_bf16(c6, c7)}
; __device__ __forceinline__ void mlstm_scan_item(const Params& P, int item) {
;     ...
;         for (int j = 0; j < 16; ++j) { const int n = n0 + j; const float g = GM[n * 2], ml = GM[n * 2 + 1];
;             *(u32x4*)(p + (size_t)n * 32768) = PACK_CARRY();
;             if (hasn) np[(size_t)n * 128] = ncar;
;             if (wm) MPREV[n] = m;
;             const float mn = fmaxf(g + m, ml), sp = __expf(g + m - mn), sq = __expf(ml - mn);
;             c0 = sp * c0 + sq * bflo(cl[j].x); c1 = sp * c1 + sq * bfhi(cl[j].x); c2 = sp * c2 + sq * bflo(cl[j].y); c3 = sp * c3 + sq * bfhi(cl[j].y);
;             c4 = sp * c4 + sq * bflo(cl[j].z); c5 = sp * c5 + sq * bfhi(cl[j].z); c6 = sp * c6 + sq * bflo(cl[j].w); c7 = sp * c7 + sq * bfhi(cl[j].w);
;             ncar = sp * ncar + sq * nl[j]; m = mn; }
.LBB0_638:
	s_or_b64 exec, exec, s[18:19]
	v_add_co_u32_e32 v38, vcc, 0x60000, v84
	v_lshlrev_b32_e32 v65, 16, v34
	s_nop 0
	v_addc_co_u32_e32 v39, vcc, 0, v85, vcc
	v_mov_b32_e32 v40, v228
	v_mov_b32_e32 v41, v229
	v_add_f32_e32 v38, v87, v44
	v_max_f32_e32 v39, v45, v45
	v_max_f32_e32 v63, v38, v39
	v_sub_f32_e32 v39, v45, v63
	v_sub_f32_e32 v38, v38, v63
	v_mul_f32_e32 v39, 0x3fb8aa3b, v39
	v_mul_f32_e32 v38, 0x3fb8aa3b, v38
	v_exp_f32_e32 v43, v39
	v_exp_f32_e32 v64, v38
	s_mov_b64 s[18:19], 0x1ae80000
	v_lshl_add_u64 v[86:87], v[76:77], 0, s[18:19]
	v_mul_f32_e32 v38, v43, v65
	v_pk_fma_f32 v[38:39], v[42:43], v[64:65], v[38:39] op_sel_hi:[1,1,0]
	v_and_b32_e32 v65, 0xffff0000, v34
	v_mov_b32_e32 v53, v43
	v_mul_f32_e32 v34, v43, v65
	v_pk_fma_f32 v[52:53], v[52:53], v[64:65], v[34:35] op_sel_hi:[1,1,0]
	v_lshlrev_b32_e32 v65, 16, v35
	v_mov_b32_e32 v51, v43
	v_mul_f32_e32 v34, v43, v65
	v_pk_fma_f32 v[50:51], v[50:51], v[64:65], v[34:35] op_sel_hi:[1,1,0]
	v_and_b32_e32 v65, 0xffff0000, v35
	v_mov_b32_e32 v49, v43
	v_mul_f32_e32 v34, v43, v65
	v_pk_fma_f32 v[48:49], v[48:49], v[64:65], v[34:35] op_sel_hi:[1,1,0]
	v_lshlrev_b32_e32 v65, 16, v36
	v_mov_b32_e32 v61, v43
	v_mul_f32_e32 v34, v43, v65
	v_pk_fma_f32 v[46:47], v[60:61], v[64:65], v[34:35] op_sel_hi:[1,1,0]
	v_and_b32_e32 v65, 0xffff0000, v36
	v_mov_b32_e32 v59, v43
	v_mul_f32_e32 v34, v43, v65
	v_pk_fma_f32 v[44:45], v[58:59], v[64:65], v[34:35] op_sel_hi:[1,1,0]
	v_lshlrev_b32_e32 v65, 16, v37
	v_mov_b32_e32 v57, v43
	v_mul_f32_e32 v34, v43, v65
	v_pk_fma_f32 v[56:57], v[56:57], v[64:65], v[34:35] op_sel_hi:[1,1,0]
	v_and_b32_e32 v65, 0xffff0000, v37
	v_mov_b32_e32 v55, v43
	v_mul_f32_e32 v34, v43, v65
	v_mul_f32_e32 v58, v110, v43
	v_pk_fma_f32 v[54:55], v[54:55], v[64:65], v[34:35] op_sel_hi:[1,1,0]
	v_fmac_f32_e32 v58, v62, v64
	v_cvt_pk_bf16_f32 v34, v38, v52
	v_cvt_pk_bf16_f32 v35, v50, v48
	v_cvt_pk_bf16_f32 v36, v46, v44
	v_cvt_pk_bf16_f32 v37, v56, v54
	flat_store_dwordx4 v[86:87], v[34:37]
	s_and_saveexec_b64 s[18:19], s[14:15]
	s_cbranch_execz .LBB0_640
	v_add_co_u32_e32 v34, vcc, 0x101000, v80
	s_nop 1
	v_addc_co_u32_e32 v35, vcc, 0, v81, vcc
	flat_store_dword v[34:35], v58

; __device__ __forceinline__ float bflo(unsigned w) { return __uint_as_float(w << 16); }
; __device__ __forceinline__ float bfhi(unsigned w) { return __uint_as_float(w & 0xffff0000u); }
; #define PACK_CARRY() (u32x4){cvt_pk_bf16(c0, c1), cvt_pk_bf16(c2, c3), cvt_pk_bf16(c4, c5), cvt_pk_bf16(c6, c7)}
; __device__ __forceinline__ void mlstm_scan_item(const Params& P, int item) {
;     ...
;         for (int j = 0; j < 16; ++j) { const int n = n0 + j; const float g = GM[n * 2], ml = GM[n * 2 + 1];
;             *(u32x4*)(p + (size_t)n * 32768) = PACK_CARRY();
;             if (hasn) np[(size_t)n * 128] = ncar;
;             if (wm) MPREV[n] = m;
;             const float mn = fmaxf(g + m, ml), sp = __expf(g + m - mn), sq = __expf(ml - mn);
;             c0 = sp * c0 + sq * bflo(cl[j].x); c1 = sp * c1 + sq * bfhi(cl[j].x); c2 = sp * c2 + sq * bflo(cl[j].y); c3 = sp * c3 + sq * bfhi(cl[j].y);
;             c4 = sp * c4 + sq * bflo(cl[j].z); c5 = sp * c5 + sq * bfhi(cl[j].z); c6 = sp * c6 + sq * bflo(cl[j].w); c7 = sp * c7 + sq * bfhi(cl[j].w);
;             ncar = sp * ncar + sq * nl[j]; m = mn; }
.LBB0_642:
	s_or_b64 exec, exec, s[18:19]
	v_add_co_u32_e32 v34, vcc, 0x60000, v84
	v_lshlrev_b32_e32 v61, 16, v30
	s_nop 0
	v_addc_co_u32_e32 v35, vcc, 0, v85, vcc
	v_mov_b32_e32 v36, v230
	v_mov_b32_e32 v37, v231
	v_add_f32_e32 v34, v63, v40
	v_max_f32_e32 v35, v41, v41
	v_max_f32_e32 v59, v34, v35
	v_sub_f32_e32 v35, v41, v59
	v_sub_f32_e32 v34, v34, v59
	v_mul_f32_e32 v35, 0x3fb8aa3b, v35
	v_mul_f32_e32 v34, 0x3fb8aa3b, v34
	v_exp_f32_e32 v39, v35
	v_exp_f32_e32 v60, v34
	s_mov_b64 s[18:19], 0x1ae90000
	v_lshl_add_u64 v[62:63], v[76:77], 0, s[18:19]
	v_mul_f32_e32 v34, v39, v61
	v_pk_fma_f32 v[34:35], v[38:39], v[60:61], v[34:35] op_sel_hi:[1,1,0]
	v_and_b32_e32 v61, 0xffff0000, v30
	v_mov_b32_e32 v53, v39
	v_mul_f32_e32 v30, v39, v61
	v_pk_fma_f32 v[52:53], v[52:53], v[60:61], v[30:31] op_sel_hi:[1,1,0]
	v_lshlrev_b32_e32 v61, 16, v31
	v_mov_b32_e32 v51, v39
	v_mul_f32_e32 v30, v39, v61
	v_pk_fma_f32 v[50:51], v[50:51], v[60:61], v[30:31] op_sel_hi:[1,1,0]
	v_and_b32_e32 v61, 0xffff0000, v31
	v_mov_b32_e32 v49, v39
	v_mul_f32_e32 v30, v39, v61
	v_pk_fma_f32 v[48:49], v[48:49], v[60:61], v[30:31] op_sel_hi:[1,1,0]
	v_lshlrev_b32_e32 v61, 16, v32
	v_mov_b32_e32 v47, v39
	v_mul_f32_e32 v30, v39, v61
	v_pk_fma_f32 v[46:47], v[46:47], v[60:61], v[30:31] op_sel_hi:[1,1,0]
	v_and_b32_e32 v61, 0xffff0000, v32
	v_mov_b32_e32 v45, v39
	v_mul_f32_e32 v30, v39, v61
	v_pk_fma_f32 v[44:45], v[44:45], v[60:61], v[30:31] op_sel_hi:[1,1,0]
	v_lshlrev_b32_e32 v61, 16, v33
	v_mov_b32_e32 v57, v39
	v_mul_f32_e32 v30, v39, v61
	v_pk_fma_f32 v[42:43], v[56:57], v[60:61], v[30:31] op_sel_hi:[1,1,0]
	v_and_b32_e32 v61, 0xffff0000, v33
	v_mov_b32_e32 v55, v39
	v_mul_f32_e32 v30, v39, v61
	v_pk_fma_f32 v[40:41], v[54:55], v[60:61], v[30:31] op_sel_hi:[1,1,0]
	v_mul_f32_e32 v54, v109, v39
	v_fmac_f32_e32 v54, v58, v60
	v_cvt_pk_bf16_f32 v30, v34, v52
	v_cvt_pk_bf16_f32 v31, v50, v48
	v_cvt_pk_bf16_f32 v32, v46, v44
	v_cvt_pk_bf16_f32 v33, v42, v40
	flat_store_dwordx4 v[62:63], v[30:33]
	s_and_saveexec_b64 s[18:19], s[14:15]
	s_cbranch_execz .LBB0_644
	v_add_co_u32_e32 v30, vcc, 0x101000, v80
	s_nop 1
	v_addc_co_u32_e32 v31, vcc, 0, v81, vcc
	flat_store_dword v[30:31], v54 offset:512

; __device__ __forceinline__ float bflo(unsigned w) { return __uint_as_float(w << 16); }
; __device__ __forceinline__ float bfhi(unsigned w) { return __uint_as_float(w & 0xffff0000u); }
; #define PACK_CARRY() (u32x4){cvt_pk_bf16(c0, c1), cvt_pk_bf16(c2, c3), cvt_pk_bf16(c4, c5), cvt_pk_bf16(c6, c7)}
; __device__ __forceinline__ void mlstm_scan_item(const Params& P, int item) {
;     ...
;         for (int j = 0; j < 16; ++j) { const int n = n0 + j; const float g = GM[n * 2], ml = GM[n * 2 + 1];
;             *(u32x4*)(p + (size_t)n * 32768) = PACK_CARRY();
;             if (hasn) np[(size_t)n * 128] = ncar;
;             if (wm) MPREV[n] = m;
;             const float mn = fmaxf(g + m, ml), sp = __expf(g + m - mn), sq = __expf(ml - mn);
;             c0 = sp * c0 + sq * bflo(cl[j].x); c1 = sp * c1 + sq * bfhi(cl[j].x); c2 = sp * c2 + sq * bflo(cl[j].y); c3 = sp * c3 + sq * bfhi(cl[j].y);
;             c4 = sp * c4 + sq * bflo(cl[j].z); c5 = sp * c5 + sq * bfhi(cl[j].z); c6 = sp * c6 + sq * bflo(cl[j].w); c7 = sp * c7 + sq * bfhi(cl[j].w);
;             ncar = sp * ncar + sq * nl[j]; m = mn; }
.LBB0_646:
	s_or_b64 exec, exec, s[18:19]
	v_add_co_u32_e32 v30, vcc, 0x60000, v84
	v_lshlrev_b32_e32 v57, 16, v26
	s_nop 0
	v_addc_co_u32_e32 v31, vcc, 0, v85, vcc
	v_mov_b32_e32 v32, v232
	v_mov_b32_e32 v33, v233
	v_add_f32_e32 v30, v59, v36
	v_max_f32_e32 v31, v37, v37
	v_max_f32_e32 v55, v30, v31
	v_sub_f32_e32 v31, v37, v55
	v_sub_f32_e32 v30, v30, v55
	v_mul_f32_e32 v31, 0x3fb8aa3b, v31
	v_mul_f32_e32 v30, 0x3fb8aa3b, v30
	v_exp_f32_e32 v35, v31
	v_exp_f32_e32 v56, v30
	s_mov_b64 s[18:19], 0x1aea0000
	v_lshl_add_u64 v[58:59], v[76:77], 0, s[18:19]
	v_mul_f32_e32 v30, v35, v57
	v_pk_fma_f32 v[30:31], v[34:35], v[56:57], v[30:31] op_sel_hi:[1,1,0]
	v_and_b32_e32 v57, 0xffff0000, v26
	v_mov_b32_e32 v53, v35
	v_mul_f32_e32 v26, v35, v57
	v_pk_fma_f32 v[38:39], v[52:53], v[56:57], v[26:27] op_sel_hi:[1,1,0]
	v_lshlrev_b32_e32 v57, 16, v27
	v_mov_b32_e32 v51, v35
	v_mul_f32_e32 v26, v35, v57
	v_pk_fma_f32 v[36:37], v[50:51], v[56:57], v[26:27] op_sel_hi:[1,1,0]
	v_and_b32_e32 v57, 0xffff0000, v27
	v_mov_b32_e32 v49, v35
	v_mul_f32_e32 v26, v35, v57
	v_pk_fma_f32 v[48:49], v[48:49], v[56:57], v[26:27] op_sel_hi:[1,1,0]
	v_lshlrev_b32_e32 v57, 16, v28
	v_mov_b32_e32 v47, v35
	v_mul_f32_e32 v26, v35, v57
	v_pk_fma_f32 v[46:47], v[46:47], v[56:57], v[26:27] op_sel_hi:[1,1,0]
	v_and_b32_e32 v57, 0xffff0000, v28
	v_mov_b32_e32 v45, v35
	v_mul_f32_e32 v26, v35, v57
	v_pk_fma_f32 v[44:45], v[44:45], v[56:57], v[26:27] op_sel_hi:[1,1,0]
	v_lshlrev_b32_e32 v57, 16, v29
	v_mov_b32_e32 v43, v35
	v_mul_f32_e32 v26, v35, v57
	v_pk_fma_f32 v[42:43], v[42:43], v[56:57], v[26:27] op_sel_hi:[1,1,0]
	v_and_b32_e32 v57, 0xffff0000, v29
	v_mov_b32_e32 v41, v35
	v_mul_f32_e32 v26, v35, v57
	v_mul_f32_e32 v50, v108, v35
	v_pk_fma_f32 v[40:41], v[40:41], v[56:57], v[26:27] op_sel_hi:[1,1,0]
	v_fmac_f32_e32 v50, v54, v56
	v_cvt_pk_bf16_f32 v26, v30, v38
	v_cvt_pk_bf16_f32 v27, v36, v48
	v_cvt_pk_bf16_f32 v28, v46, v44
	v_cvt_pk_bf16_f32 v29, v42, v40
	flat_store_dwordx4 v[58:59], v[26:29]
	s_and_saveexec_b64 s[18:19], s[14:15]
	s_cbranch_execz .LBB0_648
	v_add_co_u32_e32 v26, vcc, 0x101000, v80
	s_nop 1
	v_addc_co_u32_e32 v27, vcc, 0, v81, vcc
	flat_store_dword v[26:27], v50 offset:1024

; __device__ __forceinline__ float bflo(unsigned w) { return __uint_as_float(w << 16); }
; __device__ __forceinline__ float bfhi(unsigned w) { return __uint_as_float(w & 0xffff0000u); }
; #define PACK_CARRY() (u32x4){cvt_pk_bf16(c0, c1), cvt_pk_bf16(c2, c3), cvt_pk_bf16(c4, c5), cvt_pk_bf16(c6, c7)}
; __device__ __forceinline__ void mlstm_scan_item(const Params& P, int item) {
;     ...
;         for (int j = 0; j < 16; ++j) { const int n = n0 + j; const float g = GM[n * 2], ml = GM[n * 2 + 1];
;             *(u32x4*)(p + (size_t)n * 32768) = PACK_CARRY();
;             if (hasn) np[(size_t)n * 128] = ncar;
;             if (wm) MPREV[n] = m;
;             const float mn = fmaxf(g + m, ml), sp = __expf(g + m - mn), sq = __expf(ml - mn);
;             c0 = sp * c0 + sq * bflo(cl[j].x); c1 = sp * c1 + sq * bfhi(cl[j].x); c2 = sp * c2 + sq * bflo(cl[j].y); c3 = sp * c3 + sq * bfhi(cl[j].y);
;             c4 = sp * c4 + sq * bflo(cl[j].z); c5 = sp * c5 + sq * bfhi(cl[j].z); c6 = sp * c6 + sq * bflo(cl[j].w); c7 = sp * c7 + sq * bfhi(cl[j].w);
;             ncar = sp * ncar + sq * nl[j]; m = mn; }
.LBB0_650:
	s_or_b64 exec, exec, s[18:19]
	v_add_co_u32_e32 v26, vcc, 0x60000, v84
	v_lshlrev_b32_e32 v53, 16, v22
	s_nop 0
	v_addc_co_u32_e32 v27, vcc, 0, v85, vcc
	v_mov_b32_e32 v28, v234
	v_mov_b32_e32 v29, v235
	v_add_f32_e32 v26, v55, v32
	v_max_f32_e32 v27, v33, v33
	v_max_f32_e32 v51, v26, v27
	v_sub_f32_e32 v27, v33, v51
	v_sub_f32_e32 v26, v26, v51
	v_mul_f32_e32 v27, 0x3fb8aa3b, v27
	v_mul_f32_e32 v26, 0x3fb8aa3b, v26
	v_exp_f32_e32 v31, v27
	v_exp_f32_e32 v52, v26
	s_mov_b64 s[18:19], 0x1aeb0000
	v_lshl_add_u64 v[54:55], v[76:77], 0, s[18:19]
	v_mul_f32_e32 v26, v31, v53
	v_pk_fma_f32 v[26:27], v[30:31], v[52:53], v[26:27] op_sel_hi:[1,1,0]
	v_and_b32_e32 v53, 0xffff0000, v22
	v_mov_b32_e32 v39, v31
	v_mul_f32_e32 v22, v31, v53
	v_pk_fma_f32 v[38:39], v[38:39], v[52:53], v[22:23] op_sel_hi:[1,1,0]
	v_lshlrev_b32_e32 v53, 16, v23
	v_mov_b32_e32 v37, v31
	v_mul_f32_e32 v22, v31, v53
	v_pk_fma_f32 v[36:37], v[36:37], v[52:53], v[22:23] op_sel_hi:[1,1,0]
	v_and_b32_e32 v53, 0xffff0000, v23
	v_mov_b32_e32 v49, v31
	v_mul_f32_e32 v22, v31, v53
	v_pk_fma_f32 v[34:35], v[48:49], v[52:53], v[22:23] op_sel_hi:[1,1,0]
	v_lshlrev_b32_e32 v53, 16, v24
	v_mov_b32_e32 v47, v31
	v_mul_f32_e32 v22, v31, v53
	v_pk_fma_f32 v[32:33], v[46:47], v[52:53], v[22:23] op_sel_hi:[1,1,0]
	v_and_b32_e32 v53, 0xffff0000, v24
	v_mov_b32_e32 v45, v31
	v_mul_f32_e32 v22, v31, v53
	v_pk_fma_f32 v[44:45], v[44:45], v[52:53], v[22:23] op_sel_hi:[1,1,0]
	v_lshlrev_b32_e32 v53, 16, v25
	v_mov_b32_e32 v43, v31
	v_mul_f32_e32 v22, v31, v53
	v_pk_fma_f32 v[42:43], v[42:43], v[52:53], v[22:23] op_sel_hi:[1,1,0]
	v_and_b32_e32 v53, 0xffff0000, v25
	v_mov_b32_e32 v41, v31
	v_mul_f32_e32 v22, v31, v53
	v_mul_f32_e32 v46, v107, v31
	v_pk_fma_f32 v[40:41], v[40:41], v[52:53], v[22:23] op_sel_hi:[1,1,0]
	v_fmac_f32_e32 v46, v50, v52
	v_cvt_pk_bf16_f32 v22, v26, v38
	v_cvt_pk_bf16_f32 v23, v36, v34
	v_cvt_pk_bf16_f32 v24, v32, v44
	v_cvt_pk_bf16_f32 v25, v42, v40
	flat_store_dwordx4 v[54:55], v[22:25]
	s_and_saveexec_b64 s[18:19], s[14:15]
	s_cbranch_execz .LBB0_652
	v_add_co_u32_e32 v22, vcc, 0x101000, v80
	s_nop 1
	v_addc_co_u32_e32 v23, vcc, 0, v81, vcc
	flat_store_dword v[22:23], v46 offset:1536

; __device__ __forceinline__ float bflo(unsigned w) { return __uint_as_float(w << 16); }
; __device__ __forceinline__ float bfhi(unsigned w) { return __uint_as_float(w & 0xffff0000u); }
; #define PACK_CARRY() (u32x4){cvt_pk_bf16(c0, c1), cvt_pk_bf16(c2, c3), cvt_pk_bf16(c4, c5), cvt_pk_bf16(c6, c7)}
; __device__ __forceinline__ void mlstm_scan_item(const Params& P, int item) {
;     ...
;         for (int j = 0; j < 16; ++j) { const int n = n0 + j; const float g = GM[n * 2], ml = GM[n * 2 + 1];
;             *(u32x4*)(p + (size_t)n * 32768) = PACK_CARRY();
;             if (hasn) np[(size_t)n * 128] = ncar;
;             if (wm) MPREV[n] = m;
;             const float mn = fmaxf(g + m, ml), sp = __expf(g + m - mn), sq = __expf(ml - mn);
;             c0 = sp * c0 + sq * bflo(cl[j].x); c1 = sp * c1 + sq * bfhi(cl[j].x); c2 = sp * c2 + sq * bflo(cl[j].y); c3 = sp * c3 + sq * bfhi(cl[j].y);
;             c4 = sp * c4 + sq * bflo(cl[j].z); c5 = sp * c5 + sq * bfhi(cl[j].z); c6 = sp * c6 + sq * bflo(cl[j].w); c7 = sp * c7 + sq * bfhi(cl[j].w);
;             ncar = sp * ncar + sq * nl[j]; m = mn; }
.LBB0_654:
	s_or_b64 exec, exec, s[18:19]
	v_add_co_u32_e32 v22, vcc, 0x60000, v84
	v_lshlrev_b32_e32 v49, 16, v18
	s_nop 0
	v_addc_co_u32_e32 v23, vcc, 0, v85, vcc
	v_mov_b32_e32 v24, v236
	v_mov_b32_e32 v25, v237
	v_add_f32_e32 v22, v51, v28
	v_max_f32_e32 v23, v29, v29
	v_max_f32_e32 v47, v22, v23
	v_sub_f32_e32 v23, v29, v47
	v_sub_f32_e32 v22, v22, v47
	v_mul_f32_e32 v23, 0x3fb8aa3b, v23
	v_mul_f32_e32 v22, 0x3fb8aa3b, v22
	v_exp_f32_e32 v27, v23
	v_exp_f32_e32 v48, v22
	s_mov_b64 s[18:19], 0x1aec0000
	v_lshl_add_u64 v[50:51], v[76:77], 0, s[18:19]
	v_mul_f32_e32 v22, v27, v49
	v_pk_fma_f32 v[22:23], v[26:27], v[48:49], v[22:23] op_sel_hi:[1,1,0]
	v_and_b32_e32 v49, 0xffff0000, v18
	v_mov_b32_e32 v39, v27
	v_mul_f32_e32 v18, v27, v49
	v_pk_fma_f32 v[38:39], v[38:39], v[48:49], v[18:19] op_sel_hi:[1,1,0]
	v_lshlrev_b32_e32 v49, 16, v19
	v_mov_b32_e32 v37, v27
	v_mul_f32_e32 v18, v27, v49
	v_pk_fma_f32 v[36:37], v[36:37], v[48:49], v[18:19] op_sel_hi:[1,1,0]
	v_and_b32_e32 v49, 0xffff0000, v19
	v_mov_b32_e32 v35, v27
	v_mul_f32_e32 v18, v27, v49
	v_pk_fma_f32 v[34:35], v[34:35], v[48:49], v[18:19] op_sel_hi:[1,1,0]
	v_lshlrev_b32_e32 v49, 16, v20
	v_mov_b32_e32 v33, v27
	v_mul_f32_e32 v18, v27, v49
	v_pk_fma_f32 v[32:33], v[32:33], v[48:49], v[18:19] op_sel_hi:[1,1,0]
	v_and_b32_e32 v49, 0xffff0000, v20
	v_mov_b32_e32 v45, v27
	v_mul_f32_e32 v18, v27, v49
	v_pk_fma_f32 v[30:31], v[44:45], v[48:49], v[18:19] op_sel_hi:[1,1,0]
	v_lshlrev_b32_e32 v49, 16, v21
	v_mov_b32_e32 v43, v27
	v_mul_f32_e32 v18, v27, v49
	v_pk_fma_f32 v[28:29], v[42:43], v[48:49], v[18:19] op_sel_hi:[1,1,0]
	v_and_b32_e32 v49, 0xffff0000, v21
	v_mov_b32_e32 v41, v27
	v_mul_f32_e32 v18, v27, v49
	v_pk_fma_f32 v[18:19], v[40:41], v[48:49], v[18:19] op_sel_hi:[1,1,0]
	v_mul_f32_e32 v40, v106, v27
	v_fmac_f32_e32 v40, v46, v48
	v_cvt_pk_bf16_f32 v42, v22, v38
	v_cvt_pk_bf16_f32 v43, v36, v34
	v_cvt_pk_bf16_f32 v44, v32, v30
	v_cvt_pk_bf16_f32 v45, v28, v18
	flat_store_dwordx4 v[50:51], v[42:45]
	s_and_saveexec_b64 s[18:19], s[14:15]
	s_cbranch_execz .LBB0_656
	v_add_co_u32_e32 v20, vcc, 0x101000, v80
	s_nop 1
	v_addc_co_u32_e32 v21, vcc, 0, v81, vcc
	flat_store_dword v[20:21], v40 offset:2048

; __device__ __forceinline__ float bflo(unsigned w) { return __uint_as_float(w << 16); }
; __device__ __forceinline__ float bfhi(unsigned w) { return __uint_as_float(w & 0xffff0000u); }
; #define PACK_CARRY() (u32x4){cvt_pk_bf16(c0, c1), cvt_pk_bf16(c2, c3), cvt_pk_bf16(c4, c5), cvt_pk_bf16(c6, c7)}
; __device__ __forceinline__ void mlstm_scan_item(const Params& P, int item) {
;     ...
;         for (int j = 0; j < 16; ++j) { const int n = n0 + j; const float g = GM[n * 2], ml = GM[n * 2 + 1];
;             *(u32x4*)(p + (size_t)n * 32768) = PACK_CARRY();
;             if (hasn) np[(size_t)n * 128] = ncar;
;             if (wm) MPREV[n] = m;
;             const float mn = fmaxf(g + m, ml), sp = __expf(g + m - mn), sq = __expf(ml - mn);
;             c0 = sp * c0 + sq * bflo(cl[j].x); c1 = sp * c1 + sq * bfhi(cl[j].x); c2 = sp * c2 + sq * bflo(cl[j].y); c3 = sp * c3 + sq * bfhi(cl[j].y);
;             c4 = sp * c4 + sq * bflo(cl[j].z); c5 = sp * c5 + sq * bfhi(cl[j].z); c6 = sp * c6 + sq * bflo(cl[j].w); c7 = sp * c7 + sq * bfhi(cl[j].w);
;             ncar = sp * ncar + sq * nl[j]; m = mn; }
.LBB0_658:
	s_or_b64 exec, exec, s[18:19]
	v_add_co_u32_e32 v20, vcc, 0x60000, v84
	v_add_f32_e32 v19, v47, v24
	s_nop 0
	v_addc_co_u32_e32 v21, vcc, 0, v85, vcc
	v_mov_b32_e32 v26, v238
	v_mov_b32_e32 v27, v239
	v_max_f32_e32 v20, v25, v25
	v_max_f32_e32 v42, v19, v20
	v_sub_f32_e32 v20, v25, v42
	v_sub_f32_e32 v19, v19, v42
	v_mul_f32_e32 v20, 0x3fb8aa3b, v20
	v_mul_f32_e32 v19, 0x3fb8aa3b, v19
	v_exp_f32_e32 v23, v20
	v_exp_f32_e32 v44, v19
	v_lshlrev_b32_e32 v45, 16, v14
	s_mov_b64 s[18:19], 0x1aed0000
	v_mul_f32_e32 v20, v23, v45
	v_pk_fma_f32 v[20:21], v[22:23], v[44:45], v[20:21] op_sel_hi:[1,1,0]
	v_and_b32_e32 v45, 0xffff0000, v14
	v_mov_b32_e32 v39, v23
	v_mul_f32_e32 v14, v23, v45
	v_pk_fma_f32 v[38:39], v[38:39], v[44:45], v[14:15] op_sel_hi:[1,1,0]
	v_lshlrev_b32_e32 v45, 16, v15
	v_mov_b32_e32 v37, v23
	v_mul_f32_e32 v14, v23, v45
	v_pk_fma_f32 v[36:37], v[36:37], v[44:45], v[14:15] op_sel_hi:[1,1,0]
	v_and_b32_e32 v45, 0xffff0000, v15
	v_mov_b32_e32 v35, v23
	v_mul_f32_e32 v14, v23, v45
	v_pk_fma_f32 v[34:35], v[34:35], v[44:45], v[14:15] op_sel_hi:[1,1,0]
	v_lshlrev_b32_e32 v45, 16, v16
	v_mov_b32_e32 v33, v23
	v_mul_f32_e32 v14, v23, v45
	v_pk_fma_f32 v[32:33], v[32:33], v[44:45], v[14:15] op_sel_hi:[1,1,0]
	v_and_b32_e32 v45, 0xffff0000, v16
	v_mov_b32_e32 v31, v23
	v_mul_f32_e32 v14, v23, v45
	v_pk_fma_f32 v[30:31], v[30:31], v[44:45], v[14:15] op_sel_hi:[1,1,0]
	v_lshlrev_b32_e32 v45, 16, v17
	v_mov_b32_e32 v29, v23
	v_mul_f32_e32 v14, v23, v45
	v_pk_fma_f32 v[24:25], v[28:29], v[44:45], v[14:15] op_sel_hi:[1,1,0]
	v_and_b32_e32 v45, 0xffff0000, v17
	v_mov_b32_e32 v19, v23
	v_mul_f32_e32 v14, v23, v45
	v_mul_f32_e32 v41, v105, v23
	v_lshl_add_u64 v[46:47], v[76:77], 0, s[18:19]
	v_pk_fma_f32 v[14:15], v[18:19], v[44:45], v[14:15] op_sel_hi:[1,1,0]
	v_fmac_f32_e32 v41, v40, v44
	v_cvt_pk_bf16_f32 v16, v20, v38
	v_cvt_pk_bf16_f32 v17, v36, v34
	v_cvt_pk_bf16_f32 v18, v32, v30
	v_cvt_pk_bf16_f32 v19, v24, v14
	flat_store_dwordx4 v[46:47], v[16:19]
	s_and_saveexec_b64 s[18:19], s[14:15]
	s_cbranch_execz .LBB0_660
	v_add_co_u32_e32 v16, vcc, 0x101000, v80
	s_nop 1
	v_addc_co_u32_e32 v17, vcc, 0, v81, vcc
	flat_store_dword v[16:17], v41 offset:2560

; __device__ __forceinline__ float bflo(unsigned w) { return __uint_as_float(w << 16); }
; __device__ __forceinline__ float bfhi(unsigned w) { return __uint_as_float(w & 0xffff0000u); }
; #define PACK_CARRY() (u32x4){cvt_pk_bf16(c0, c1), cvt_pk_bf16(c2, c3), cvt_pk_bf16(c4, c5), cvt_pk_bf16(c6, c7)}
; __device__ __forceinline__ void mlstm_scan_item(const Params& P, int item) {
;     ...
;         for (int j = 0; j < 16; ++j) { const int n = n0 + j; const float g = GM[n * 2], ml = GM[n * 2 + 1];
;             *(u32x4*)(p + (size_t)n * 32768) = PACK_CARRY();
;             if (hasn) np[(size_t)n * 128] = ncar;
;             if (wm) MPREV[n] = m;
;             const float mn = fmaxf(g + m, ml), sp = __expf(g + m - mn), sq = __expf(ml - mn);
;             c0 = sp * c0 + sq * bflo(cl[j].x); c1 = sp * c1 + sq * bfhi(cl[j].x); c2 = sp * c2 + sq * bflo(cl[j].y); c3 = sp * c3 + sq * bfhi(cl[j].y);
;             c4 = sp * c4 + sq * bflo(cl[j].z); c5 = sp * c5 + sq * bfhi(cl[j].z); c6 = sp * c6 + sq * bflo(cl[j].w); c7 = sp * c7 + sq * bfhi(cl[j].w);
;             ncar = sp * ncar + sq * nl[j]; m = mn; }
.LBB0_662:
	s_or_b64 exec, exec, s[18:19]
	v_add_co_u32_e32 v16, vcc, 0x60000, v84
	v_add_f32_e32 v15, v42, v26
	v_addc_co_u32_e32 v17, vcc, 0, v85, vcc
	v_mov_b32_e32 v18, v240
	v_mov_b32_e32 v19, v241
	v_max_f32_e32 v16, v27, v27
	v_max_f32_e32 v40, v15, v16
	v_sub_f32_e32 v16, v27, v40
	v_sub_f32_e32 v15, v15, v40
	v_mul_f32_e32 v16, 0x3fb8aa3b, v16
	v_mul_f32_e32 v15, 0x3fb8aa3b, v15
	v_exp_f32_e32 v21, v16
	v_exp_f32_e32 v42, v15
	v_lshlrev_b32_e32 v43, 16, v10
	v_lshl_add_u64 v[44:45], v[76:77], 0, s[52:53]
	v_mul_f32_e32 v16, v21, v43
	v_pk_fma_f32 v[16:17], v[20:21], v[42:43], v[16:17] op_sel_hi:[1,1,0]
	v_and_b32_e32 v43, 0xffff0000, v10
	v_mov_b32_e32 v39, v21
	v_mul_f32_e32 v10, v21, v43
	v_pk_fma_f32 v[38:39], v[38:39], v[42:43], v[10:11] op_sel_hi:[1,1,0]
	v_lshlrev_b32_e32 v43, 16, v11
	v_mov_b32_e32 v37, v21
	v_mul_f32_e32 v10, v21, v43
	v_pk_fma_f32 v[28:29], v[36:37], v[42:43], v[10:11] op_sel_hi:[1,1,0]
	v_and_b32_e32 v43, 0xffff0000, v11
	v_mov_b32_e32 v35, v21
	v_mul_f32_e32 v10, v21, v43
	v_pk_fma_f32 v[34:35], v[34:35], v[42:43], v[10:11] op_sel_hi:[1,1,0]
	v_lshlrev_b32_e32 v43, 16, v12
	v_mov_b32_e32 v33, v21
	v_mul_f32_e32 v10, v21, v43
	v_pk_fma_f32 v[22:23], v[32:33], v[42:43], v[10:11] op_sel_hi:[1,1,0]
	v_and_b32_e32 v43, 0xffff0000, v12
	v_mov_b32_e32 v31, v21
	v_mul_f32_e32 v10, v21, v43
	v_pk_fma_f32 v[26:27], v[30:31], v[42:43], v[10:11] op_sel_hi:[1,1,0]
	v_lshlrev_b32_e32 v43, 16, v13
	v_mov_b32_e32 v25, v21
	v_mul_f32_e32 v10, v21, v43
	v_pk_fma_f32 v[10:11], v[24:25], v[42:43], v[10:11] op_sel_hi:[1,1,0]
	v_and_b32_e32 v43, 0xffff0000, v13
	v_mov_b32_e32 v15, v21
	v_mul_f32_e32 v12, v21, v43
	v_mul_f32_e32 v24, v104, v21
	v_pk_fma_f32 v[12:13], v[14:15], v[42:43], v[12:13] op_sel_hi:[1,1,0]
	v_fmac_f32_e32 v24, v41, v42
	v_cvt_pk_bf16_f32 v30, v16, v38
	v_cvt_pk_bf16_f32 v31, v28, v34
	v_cvt_pk_bf16_f32 v32, v22, v26
	v_cvt_pk_bf16_f32 v33, v10, v12
	flat_store_dwordx4 v[44:45], v[30:33]
	s_and_saveexec_b64 s[18:19], s[14:15]
	s_cbranch_execz .LBB0_664
	v_add_co_u32_e32 v14, vcc, 0x101000, v80
	s_nop 1
	v_addc_co_u32_e32 v15, vcc, 0, v81, vcc
	flat_store_dword v[14:15], v24 offset:3072

; __device__ __forceinline__ float bflo(unsigned w) { return __uint_as_float(w << 16); }
; __device__ __forceinline__ float bfhi(unsigned w) { return __uint_as_float(w & 0xffff0000u); }
; #define PACK_CARRY() (u32x4){cvt_pk_bf16(c0, c1), cvt_pk_bf16(c2, c3), cvt_pk_bf16(c4, c5), cvt_pk_bf16(c6, c7)}
; __device__ __forceinline__ void mlstm_scan_item(const Params& P, int item) {
;     ...
;         for (int j = 0; j < 16; ++j) { const int n = n0 + j; const float g = GM[n * 2], ml = GM[n * 2 + 1];
;             *(u32x4*)(p + (size_t)n * 32768) = PACK_CARRY();
;             if (hasn) np[(size_t)n * 128] = ncar;
;             if (wm) MPREV[n] = m;
;             const float mn = fmaxf(g + m, ml), sp = __expf(g + m - mn), sq = __expf(ml - mn);
;             c0 = sp * c0 + sq * bflo(cl[j].x); c1 = sp * c1 + sq * bfhi(cl[j].x); c2 = sp * c2 + sq * bflo(cl[j].y); c3 = sp * c3 + sq * bfhi(cl[j].y);
;             c4 = sp * c4 + sq * bflo(cl[j].z); c5 = sp * c5 + sq * bfhi(cl[j].z); c6 = sp * c6 + sq * bflo(cl[j].w); c7 = sp * c7 + sq * bfhi(cl[j].w);
;             ncar = sp * ncar + sq * nl[j]; m = mn; }
.LBB0_666:
	s_or_b64 exec, exec, s[18:19]
	v_mov_b32_e32 v14, v242
	v_mov_b32_e32 v15, v243
	v_add_f32_e32 v11, v40, v18
	v_max_f32_e32 v13, v19, v19
	v_max_f32_e32 v25, v11, v13
	v_sub_f32_e32 v11, v11, v25
	v_mul_f32_e32 v11, 0x3fb8aa3b, v11
	v_exp_f32_e32 v30, v11
	v_sub_f32_e32 v11, v19, v25
	v_mul_f32_e32 v11, 0x3fb8aa3b, v11
	v_exp_f32_e32 v17, v11
	v_lshlrev_b32_e32 v31, 16, v6
	v_lshl_add_u64 v[32:33], v[76:77], 0, s[54:55]
	v_pk_mul_f32 v[18:19], v[16:17], v[30:31]
	v_and_b32_e32 v31, 0xffff0000, v6
	v_mov_b32_e32 v39, v17
	v_pk_mul_f32 v[20:21], v[38:39], v[30:31]
	v_mov_b32_e32 v36, v18
	v_mov_b32_e32 v37, v20
	v_mov_b32_e32 v20, v19
	v_lshlrev_b32_e32 v31, 16, v7
	v_mov_b32_e32 v29, v17
	v_pk_add_f32 v[18:19], v[36:37], v[20:21]
	v_pk_mul_f32 v[20:21], v[28:29], v[30:31]
	v_and_b32_e32 v31, 0xffff0000, v7
	v_mov_b32_e32 v35, v17
	v_pk_mul_f32 v[6:7], v[34:35], v[30:31]
	v_lshlrev_b32_e32 v31, 16, v8
	v_mov_b32_e32 v23, v17
	v_mov_b32_e32 v28, v20
	v_mov_b32_e32 v29, v6
	v_mov_b32_e32 v6, v21
	v_pk_mul_f32 v[20:21], v[22:23], v[30:31]
	v_and_b32_e32 v31, 0xffff0000, v8
	v_mov_b32_e32 v27, v17
	v_pk_mul_f32 v[22:23], v[26:27], v[30:31]
	v_lshlrev_b32_e32 v31, 16, v9
	v_mov_b32_e32 v11, v17
	v_pk_mul_f32 v[10:11], v[10:11], v[30:31]
	v_and_b32_e32 v31, 0xffff0000, v9
	v_mov_b32_e32 v13, v17
	v_pk_mul_f32 v[8:9], v[12:13], v[30:31]
	v_mov_b32_e32 v26, v20
	v_mov_b32_e32 v27, v22
	v_mov_b32_e32 v22, v21
	v_mov_b32_e32 v12, v10
	v_mov_b32_e32 v13, v8
	v_mov_b32_e32 v8, v11
	v_mul_f32_e32 v78, v78, v17
	v_pk_add_f32 v[6:7], v[28:29], v[6:7]
	v_pk_add_f32 v[20:21], v[26:27], v[22:23]
	v_pk_add_f32 v[8:9], v[12:13], v[8:9]
	v_fmac_f32_e32 v78, v24, v30
	v_cvt_pk_bf16_f32 v10, v18, v19
	v_cvt_pk_bf16_f32 v11, v6, v7
	v_cvt_pk_bf16_f32 v12, v20, v21
	v_cvt_pk_bf16_f32 v13, v8, v9
	flat_store_dwordx4 v[32:33], v[10:13]
	s_and_saveexec_b64 s[18:19], s[14:15]
	s_cbranch_execz .LBB0_668
	v_add_co_u32_e32 v10, vcc, 0x101000, v80
	s_nop 1
	v_addc_co_u32_e32 v11, vcc, 0, v81, vcc
	flat_store_dword v[10:11], v78 offset:3584

; __device__ __forceinline__ int crow(int r, int hi) { return (r & 3) + 8 * (r >> 2) + 4 * hi; }
; __device__ __forceinline__ int tsw(int row, int t) { return ((((t >> 1) + 4 * ((row >> 3) & 7)) & 31) << 1) | (t & 1); }
; __device__ __forceinline__ void mlstm_out_unit(const Params& P, int l, int h, int n, char* lds) {
;     ...
;     f32x16 a1[2] = {}, a2[2] = {};
; #pragma unroll
;     for (int ks = 0; ks < 4; ++ks) { const bf16x8 B = *(const bf16x8*)(VT + (32 * wid + r32) * 72 + tsw(32 * wid + r32, 16 * ks + 8 * hi));
; #pragma unroll
;         for (int ti = 0; ti < 2; ++ti) { const bf16x8 A = *(const bf16x8*)(Wl + (32 * ti + r32) * 72 + 16 * ks + 8 * hi);
;             a1[ti] = __builtin_amdgcn_mfma_f32_32x32x16_bf16(A, B, a1[ti], 0, 0, 0); } }
; #pragma unroll
;     for (int ks = 0; ks < 8; ++ks) {
; #pragma unroll
;         for (int ti = 0; ti < 2; ++ti) { const bf16x8 A = *(const bf16x8*)(Ql + (32 * ti + r32) * 136 + 16 * ks + 8 * hi);
;             a2[ti] = __builtin_amdgcn_mfma_f32_32x32x16_bf16(A, cfr[ks], a2[ti], 0, 0, 0); } }
;     __syncthreads();
; #pragma unroll
;     for (int ti = 0; ti < 2; ++ti)
; #pragma unroll
;         for (int r = 0; r < 16; ++r) { const int t = 32 * ti + fox::crow(r, hi);
;             Hb[t * 260 + 32 * wid + r32] = (a1[ti][r] + sil[t] * a2[ti][r]) * rden[t]; }
.LBB0_970:
	s_or_b64 exec, exec, s[6:7]
	v_mul_lo_u32 v2, v18, s56
	v_add_u32_e32 v20, 0x100, v2
	v_lshlrev_b32_e32 v2, 1, v19
	v_mul_u32_u24_e32 v3, 0x90, v22
	v_add3_u32 v23, s58, v2, v3
	s_waitcnt lgkmcnt(0)
	ds_read_b128 v[2:5], v23
	v_add_u32_e32 v18, v18, v19
	v_and_b32_e32 v6, 56, v18
	v_lshl_add_u32 v6, v6, 1, v20
	ds_read_b128 v[24:27], v6 offset:34816
	ds_read_b128 v[28:31], v23 offset:32
	v_add_u32_e32 v19, 16, v18
	s_waitcnt lgkmcnt(0)
	v_mfma_f32_32x32x16_bf16 v[2:17], v[2:5], v[24:27], 0
	v_and_b32_e32 v19, 56, v19
	v_lshl_add_u32 v19, v19, 1, v20
	ds_read_b128 v[50:53], v19 offset:34816
	ds_read_b128 v[32:35], v23 offset:64
	ds_read_b128 v[54:57], v23 offset:4704
	v_bitop3_b32 v19, v18, 32, 56 bitop3:0x6c
	v_lshl_add_u32 v19, v19, 1, v20
	ds_read_b128 v[58:61], v19 offset:34816
	v_add_u32_e32 v18, 48, v18
	s_waitcnt lgkmcnt(0)
	v_mfma_f32_32x32x16_bf16 v[2:17], v[28:31], v[50:53], v[2:17]
	v_and_b32_e32 v18, 56, v18
	v_lshl_add_u32 v18, v18, 1, v20
	ds_read_b128 v[28:31], v23 offset:96
	ds_read_b128 v[114:117], v18 offset:34816
	v_mul_u32_u24_e32 v18, 0x110, v22
	v_add3_u32 v18, s3, v90, v18
	s_lshl_b32 s6, s8, 2
	v_mfma_f32_32x32x16_bf16 v[2:17], v[32:35], v[58:61], v[2:17]
	s_add_u32 s6, s42, s6
	s_addc_u32 s7, s43, 0
	s_lshl_b32 s9, s65, 7
	s_addk_i32 s9, 0x100
	s_add_i32 s10, s59, 0x100
	v_add_u32_e32 v20, s10, v90
	s_lshl_b32 s26, s8, 1
	s_waitcnt lgkmcnt(0)
	v_mfma_f32_32x32x16_bf16 v[2:17], v[28:31], v[114:117], v[2:17]
	ds_read_b128 v[28:31], v18
	ds_read_b128 v[118:121], v18 offset:32
	s_waitcnt vmcnt(0) lgkmcnt(0)
	v_mfma_f32_32x32x16_bf16 v[30:45], v[28:31], v[46:49], 0
	v_mfma_f32_32x32x16_bf16 v[30:45], v[118:121], v[86:89], v[30:45]
	ds_read_b128 v[118:121], v18 offset:64
	ds_read_b128 v[122:125], v18 offset:96
	s_waitcnt lgkmcnt(1)
	v_mfma_f32_32x32x16_bf16 v[30:45], v[118:121], v[82:85], v[30:45]
	ds_read_b128 v[118:121], v18 offset:128
	s_waitcnt lgkmcnt(1)
	v_mfma_f32_32x32x16_bf16 v[30:45], v[122:125], v[78:81], v[30:45]
	ds_read_b128 v[122:125], v23 offset:4608
	ds_read_b128 v[126:129], v23 offset:4640
	ds_read_b128 v[130:133], v23 offset:4672
	ds_read_b128 v[134:137], v18 offset:160
	s_waitcnt lgkmcnt(4)
	v_mfma_f32_32x32x16_bf16 v[30:45], v[118:121], v[74:77], v[30:45]
	ds_read_b128 v[118:121], v18 offset:8704
	ds_read_b128 v[138:141], v18 offset:8736
	ds_read_b128 v[142:145], v18 offset:8768
	ds_read_b128 v[146:149], v18 offset:8800
	ds_read_b128 v[150:153], v18 offset:8832
	ds_read_b128 v[154:157], v18 offset:8864
	ds_read_b128 v[158:161], v18 offset:192
	ds_read_b128 v[162:165], v18 offset:224
	s_waitcnt lgkmcnt(8)
	v_mfma_f32_32x32x16_bf16 v[30:45], v[134:137], v[70:73], v[30:45]
	ds_read_b128 v[134:137], v18 offset:8896
	ds_read_b128 v[166:169], v18 offset:8928
	v_lshl_add_u32 v18, v22, 2, s9
	s_add_i32 s9, s49, 0x100
	v_add_u32_e32 v19, s9, v90
	s_waitcnt lgkmcnt(0)
	s_barrier
	v_mfma_f32_32x32x16_bf16 v[30:45], v[158:161], v[66:69], v[30:45]
	ds_read_b32 v19, v19
	ds_read_b32 v20, v20
	v_mfma_f32_32x32x16_bf16 v[30:45], v[162:165], v[62:65], v[30:45]
	s_waitcnt lgkmcnt(1)
	s_nop 10
	v_fma_f32 v2, v30, v19, v2
	s_waitcnt lgkmcnt(0)
	v_mul_f32_e32 v2, v20, v2
	v_mad_u32_u24 v19, v21, s60, v18
	ds_write_b32 v19, v2
	v_lshl_or_b32 v2, v21, 2, 1
	v_lshlrev_b32_e32 v19, 2, v2
	v_add_u32_e32 v20, s9, v19
	v_add_u32_e32 v19, s10, v19
	ds_read_b32 v20, v20
	ds_read_b32 v19, v19
	v_mad_u32_u24 v2, v2, s61, v18
	s_waitcnt lgkmcnt(1)
	v_fma_f32 v3, v31, v20, v3
	s_waitcnt lgkmcnt(0)
	v_mul_f32_e32 v3, v19, v3
	ds_write_b32 v2, v3
	v_or_b32_e32 v3, 8, v90
	v_add_u32_e32 v18, s9, v3
	v_add_u32_e32 v3, s10, v3
	ds_read_b32 v18, v18
	ds_read_b32 v3, v3
	s_waitcnt lgkmcnt(1)
	v_fma_f32 v4, v32, v18, v4
	s_waitcnt lgkmcnt(0)
	v_mul_f32_e32 v3, v3, v4
	ds_write_b32 v2, v3 offset:1040
	v_or_b32_e32 v3, 12, v90
	v_add_u32_e32 v4, s9, v3
	v_add_u32_e32 v3, s10, v3
	ds_read_b32 v4, v4
	ds_read_b32 v3, v3
	s_waitcnt lgkmcnt(1)
	v_fma_f32 v4, v33, v4, v5
	s_waitcnt lgkmcnt(0)
	v_mul_f32_e32 v3, v3, v4
	ds_write_b32 v2, v3 offset:2080
	v_or_b32_e32 v3, 32, v90
	v_add_u32_e32 v4, s9, v3
	v_add_u32_e32 v3, s10, v3
	ds_read_b32 v4, v4
	ds_read_b32 v3, v3
	v_mfma_f32_32x32x16_bf16 v[18:33], v[122:125], v[24:27], 0
	s_waitcnt lgkmcnt(1)
	v_fma_f32 v4, v34, v4, v6
	s_waitcnt lgkmcnt(0)
	v_mul_f32_e32 v3, v3, v4
	ds_write_b32 v2, v3 offset:7280
	v_or_b32_e32 v3, 36, v90
	v_add_u32_e32 v4, s9, v3
	v_add_u32_e32 v3, s10, v3
	ds_read_b32 v4, v4
	ds_read_b32 v3, v3
	v_mfma_f32_32x32x16_bf16 v[18:33], v[126:129], v[50:53], v[18:33]
	s_waitcnt lgkmcnt(1)
	v_fma_f32 v4, v35, v4, v7
	s_waitcnt lgkmcnt(0)
	v_mul_f32_e32 v3, v3, v4
	ds_write_b32 v2, v3 offset:8320
	v_or_b32_e32 v3, 40, v90
	v_add_u32_e32 v4, s9, v3
	v_add_u32_e32 v3, s10, v3
	ds_read_b32 v4, v4
	ds_read_b32 v3, v3
	v_mfma_f32_32x32x16_bf16 v[18:33], v[130:133], v[58:61], v[18:33]
	s_waitcnt lgkmcnt(1)
	v_fma_f32 v4, v36, v4, v8
	s_waitcnt lgkmcnt(0)
	v_mul_f32_e32 v3, v3, v4
	ds_write_b32 v2, v3 offset:9360
	v_or_b32_e32 v3, 44, v90
	v_add_u32_e32 v4, s9, v3
	v_add_u32_e32 v3, s10, v3
	ds_read_b32 v4, v4
	ds_read_b32 v3, v3
	v_mfma_f32_32x32x16_bf16 v[18:33], v[54:57], v[114:117], v[18:33]
	v_add_u32_e32 v36, s64, v109
	s_waitcnt lgkmcnt(1)
	v_fma_f32 v4, v37, v4, v9
	s_waitcnt lgkmcnt(0)
	v_mul_f32_e32 v3, v3, v4
	ds_write_b32 v2, v3 offset:10400
	v_or_b32_e32 v3, 64, v90
	v_add_u32_e32 v4, s9, v3
	v_add_u32_e32 v3, s10, v3
	ds_read_b32 v4, v4
	ds_read_b32 v3, v3
	v_mfma_f32_32x32x16_bf16 v[46:61], v[118:121], v[46:49], 0
	v_mov_b64_e32 v[8:9], s[14:15]
	s_waitcnt lgkmcnt(1)
	v_fma_f32 v4, v38, v4, v10
	s_waitcnt lgkmcnt(0)
; __device__ __forceinline__ int crow(int r, int hi) { return (r & 3) + 8 * (r >> 2) + 4 * hi; }
; __device__ __forceinline__ void mlstm_out_unit(const Params& P, int l, int h, int n, char* lds) {
;     ...
; #pragma unroll
;     for (int ti = 0; ti < 2; ++ti)
; #pragma unroll
;         for (int r = 0; r < 16; ++r) { const int t = 32 * ti + fox::crow(r, hi);
;             Hb[t * 260 + 32 * wid + r32] = (a1[ti][r] + sil[t] * a2[ti][r]) * rden[t]; }
;     __syncthreads();
;     {
;         const int t = tid >> 3, p = tid & 7; f32x4 hv[8]; float ss = 0.f;
	v_mul_f32_e32 v3, v3, v4
	ds_write_b32 v2, v3 offset:15600
	v_or_b32_e32 v3, 0x44, v90
	v_add_u32_e32 v4, s9, v3
	v_add_u32_e32 v3, s10, v3
	ds_read_b32 v4, v4
	ds_read_b32 v3, v3
	v_mfma_f32_32x32x16_bf16 v[46:61], v[138:141], v[86:89], v[46:61]
	s_waitcnt lgkmcnt(1)
	v_fma_f32 v4, v39, v4, v11
	s_waitcnt lgkmcnt(0)
	v_mul_f32_e32 v3, v3, v4
	ds_write_b32 v2, v3 offset:16640
	v_or_b32_e32 v3, 0x48, v90
	v_add_u32_e32 v4, s9, v3
	v_add_u32_e32 v3, s10, v3
	ds_read_b32 v4, v4
	ds_read_b32 v3, v3
	v_mfma_f32_32x32x16_bf16 v[46:61], v[142:145], v[82:85], v[46:61]
	s_waitcnt lgkmcnt(1)
	v_fma_f32 v4, v40, v4, v12
	s_waitcnt lgkmcnt(0)
	v_mul_f32_e32 v3, v3, v4
	ds_write_b32 v2, v3 offset:17680
	v_or_b32_e32 v3, 0x4c, v90
	v_add_u32_e32 v4, s9, v3
	v_add_u32_e32 v3, s10, v3
	ds_read_b32 v4, v4
	ds_read_b32 v3, v3
	v_mfma_f32_32x32x16_bf16 v[46:61], v[146:149], v[78:81], v[46:61]
	s_waitcnt lgkmcnt(1)
	v_fma_f32 v4, v41, v4, v13
	s_waitcnt lgkmcnt(0)
	v_mul_f32_e32 v3, v3, v4
	ds_write_b32 v2, v3 offset:18720
	v_or_b32_e32 v3, 0x60, v90
	v_add_u32_e32 v4, s9, v3
	v_add_u32_e32 v3, s10, v3
	ds_read_b32 v4, v4
	ds_read_b32 v3, v3
	v_mfma_f32_32x32x16_bf16 v[46:61], v[150:153], v[74:77], v[46:61]
	s_waitcnt lgkmcnt(1)
	v_fma_f32 v4, v42, v4, v14
	s_waitcnt lgkmcnt(0)
	v_mul_f32_e32 v3, v3, v4
	ds_write_b32 v2, v3 offset:23920
	v_or_b32_e32 v3, 0x64, v90
	v_add_u32_e32 v4, s9, v3
	v_add_u32_e32 v3, s10, v3
	ds_read_b32 v4, v4
	ds_read_b32 v3, v3
	v_mfma_f32_32x32x16_bf16 v[46:61], v[154:157], v[70:73], v[46:61]
	s_waitcnt lgkmcnt(1)
	v_fma_f32 v4, v43, v4, v15
	s_waitcnt lgkmcnt(0)
	v_mul_f32_e32 v3, v3, v4
	ds_write_b32 v2, v3 offset:24960
	v_or_b32_e32 v3, 0x68, v90
	v_add_u32_e32 v4, s9, v3
	v_add_u32_e32 v3, s10, v3
	ds_read_b32 v4, v4
	ds_read_b32 v3, v3
	v_mfma_f32_32x32x16_bf16 v[46:61], v[134:137], v[66:69], v[46:61]
	s_waitcnt lgkmcnt(1)
	v_fma_f32 v4, v44, v4, v16
	s_waitcnt lgkmcnt(0)
	v_mul_f32_e32 v3, v3, v4
	ds_write_b32 v2, v3 offset:26000
	v_or_b32_e32 v3, 0x6c, v90
	v_add_u32_e32 v4, s9, v3
	v_add_u32_e32 v3, s10, v3
	ds_read_b32 v4, v4
	ds_read_b32 v3, v3
	v_mfma_f32_32x32x16_bf16 v[46:61], v[166:169], v[62:65], v[46:61]
	s_waitcnt lgkmcnt(1)
	v_fmac_f32_e32 v17, v45, v4
	s_waitcnt lgkmcnt(0)
	v_mul_f32_e32 v3, v3, v17
	ds_write_b32 v2, v3 offset:27040
	v_or_b32_e32 v3, 0x80, v90
	v_add_u32_e32 v4, s9, v3
	v_add_u32_e32 v3, s10, v3
	ds_read_b32 v4, v4
	ds_read_b32 v3, v3
	s_waitcnt lgkmcnt(1)
	s_nop 0
	v_fma_f32 v4, v46, v4, v18
	s_waitcnt lgkmcnt(0)
	v_mul_f32_e32 v3, v3, v4
	ds_write_b32 v2, v3 offset:32240
	v_or_b32_e32 v3, 0x84, v90
	v_add_u32_e32 v4, s9, v3
	v_add_u32_e32 v3, s10, v3
	ds_read_b32 v4, v4
	ds_read_b32 v3, v3
	s_waitcnt lgkmcnt(1)
	v_fma_f32 v4, v47, v4, v19
	s_waitcnt lgkmcnt(0)
	v_mul_f32_e32 v3, v3, v4
	ds_write_b32 v2, v3 offset:33280
	v_or_b32_e32 v3, 0x88, v90
	v_add_u32_e32 v4, s9, v3
	v_add_u32_e32 v3, s10, v3
	ds_read_b32 v4, v4
	ds_read_b32 v3, v3
	s_waitcnt lgkmcnt(1)
	v_fma_f32 v4, v48, v4, v20
	s_waitcnt lgkmcnt(0)
	v_mul_f32_e32 v3, v3, v4
	ds_write_b32 v2, v3 offset:34320
	v_or_b32_e32 v3, 0x8c, v90
	v_add_u32_e32 v4, s9, v3
	v_add_u32_e32 v3, s10, v3
	ds_read_b32 v4, v4
	ds_read_b32 v3, v3
	s_waitcnt lgkmcnt(1)
	v_fma_f32 v4, v49, v4, v21
	s_waitcnt lgkmcnt(0)
	v_mul_f32_e32 v3, v3, v4
	ds_write_b32 v2, v3 offset:35360
	v_or_b32_e32 v3, 0xa0, v90
	v_add_u32_e32 v4, s9, v3
	v_add_u32_e32 v3, s10, v3
	ds_read_b32 v4, v4
	ds_read_b32 v3, v3
	s_waitcnt lgkmcnt(1)
	v_fma_f32 v4, v50, v4, v22
	s_waitcnt lgkmcnt(0)
	v_mul_f32_e32 v3, v3, v4
	ds_write_b32 v2, v3 offset:40560
	v_or_b32_e32 v3, 0xa4, v90
	v_add_u32_e32 v4, s9, v3
	v_add_u32_e32 v3, s10, v3
	ds_read_b32 v4, v4
	ds_read_b32 v3, v3
	s_waitcnt lgkmcnt(1)
	v_fma_f32 v4, v51, v4, v23
	s_waitcnt lgkmcnt(0)
	v_mul_f32_e32 v3, v3, v4
	ds_write_b32 v2, v3 offset:41600
	v_or_b32_e32 v3, 0xa8, v90
	v_add_u32_e32 v4, s9, v3
	v_add_u32_e32 v3, s10, v3
	ds_read_b32 v4, v4
	ds_read_b32 v3, v3
	s_waitcnt lgkmcnt(1)
	v_fma_f32 v4, v52, v4, v24
	s_waitcnt lgkmcnt(0)
	v_mul_f32_e32 v3, v3, v4
	ds_write_b32 v2, v3 offset:42640
	v_or_b32_e32 v3, 0xac, v90
	v_add_u32_e32 v4, s9, v3
	v_add_u32_e32 v3, s10, v3
	ds_read_b32 v4, v4
	ds_read_b32 v3, v3
	s_waitcnt lgkmcnt(1)
	v_fma_f32 v4, v53, v4, v25
	s_waitcnt lgkmcnt(0)
	v_mul_f32_e32 v3, v3, v4
	ds_write_b32 v2, v3 offset:43680
	v_or_b32_e32 v3, 0xc0, v90
	v_add_u32_e32 v4, s9, v3
	v_add_u32_e32 v3, s10, v3
	ds_read_b32 v4, v4
	ds_read_b32 v3, v3
	s_waitcnt lgkmcnt(1)
	v_fma_f32 v4, v54, v4, v26
	s_waitcnt lgkmcnt(0)
	v_mul_f32_e32 v3, v3, v4
	ds_write_b32 v2, v3 offset:48880
	v_or_b32_e32 v3, 0xc4, v90
	v_add_u32_e32 v4, s9, v3
	v_add_u32_e32 v3, s10, v3
	ds_read_b32 v4, v4
	ds_read_b32 v3, v3
	s_waitcnt lgkmcnt(1)
	v_fma_f32 v4, v55, v4, v27
	s_waitcnt lgkmcnt(0)
	v_mul_f32_e32 v3, v3, v4
	ds_write_b32 v2, v3 offset:49920
	v_or_b32_e32 v3, 0xc8, v90
	v_add_u32_e32 v4, s9, v3
	v_add_u32_e32 v3, s10, v3
	ds_read_b32 v4, v4
	ds_read_b32 v3, v3
	s_waitcnt lgkmcnt(1)
	v_fma_f32 v4, v56, v4, v28
	s_waitcnt lgkmcnt(0)
	v_mul_f32_e32 v3, v3, v4
	ds_write_b32 v2, v3 offset:50960
	v_or_b32_e32 v3, 0xcc, v90
	v_add_u32_e32 v4, s9, v3
	v_add_u32_e32 v3, s10, v3
	ds_read_b32 v4, v4
	ds_read_b32 v3, v3
	s_waitcnt lgkmcnt(1)
	v_fma_f32 v4, v57, v4, v29
	s_waitcnt lgkmcnt(0)
	v_mul_f32_e32 v3, v3, v4
	ds_write_b32 v2, v3 offset:52000
	v_or_b32_e32 v3, 0xe0, v90
	v_add_u32_e32 v4, s9, v3
	v_add_u32_e32 v3, s10, v3
	ds_read_b32 v4, v4
	ds_read_b32 v3, v3
	s_waitcnt lgkmcnt(1)
	v_fma_f32 v4, v58, v4, v30
	s_waitcnt lgkmcnt(0)
	v_mul_f32_e32 v3, v3, v4
	ds_write_b32 v2, v3 offset:57200
	v_or_b32_e32 v3, 0xe4, v90
	v_add_u32_e32 v4, s9, v3
	v_add_u32_e32 v3, s10, v3
	ds_read_b32 v4, v4
	ds_read_b32 v3, v3
	s_waitcnt lgkmcnt(1)
	v_fma_f32 v4, v59, v4, v31
	s_waitcnt lgkmcnt(0)
	v_mul_f32_e32 v3, v3, v4
	ds_write_b32 v2, v3 offset:58240
	v_or_b32_e32 v3, 0xe8, v90
	v_add_u32_e32 v4, s9, v3
	v_add_u32_e32 v3, s10, v3
	ds_read_b32 v4, v4
	ds_read_b32 v3, v3
	s_waitcnt lgkmcnt(1)
	v_fma_f32 v4, v60, v4, v32
	s_waitcnt lgkmcnt(0)
	v_mul_f32_e32 v3, v3, v4
	ds_write_b32 v2, v3 offset:59280
	v_or_b32_e32 v3, 0xec, v90
	v_add_u32_e32 v4, s9, v3
	v_add_u32_e32 v3, s10, v3
	ds_read_b32 v4, v4
	ds_read_b32 v3, v3
	v_mad_i64_i32 v[8:9], s[10:11], v36, s50, v[8:9]
	v_lshl_add_u64 v[8:9], v[8:9], 0, s[26:27]
	s_waitcnt lgkmcnt(1)
	v_fmac_f32_e32 v33, v61, v4
	v_lshlrev_b32_e32 v90, 3, v93
	s_waitcnt lgkmcnt(0)
	v_mul_f32_e32 v3, v3, v33
	v_lshl_add_u64 v[44:45], v[8:9], 0, v[90:91]
	ds_write_b32 v2, v3 offset:60320
	v_mul_lo_u32 v2, v109, s61
	v_add_co_u32_e32 v8, vcc, s51, v44
	v_add3_u32 v37, s3, v2, v92
	s_nop 0
	v_addc_co_u32_e32 v9, vcc, 0, v45, vcc
	s_waitcnt lgkmcnt(0)
	s_barrier
; __device__ __forceinline__ unsigned cvt_pk_bf16(float lo, float hi) { unsigned r; asm volatile("v_cvt_pk_bf16_f32 %0, %1, %2" : "=v"(r) : "v"(lo), "v"(hi)); return r; }
; __device__ __forceinline__ float bflo(unsigned w) { return __uint_as_float(w << 16); }
; __device__ __forceinline__ float bfhi(unsigned w) { return __uint_as_float(w & 0xffff0000u); }
; __device__ __forceinline__ float sigmoidf(float x) { return 1.f / (1.f + __expf(-x)); }
; __device__ __forceinline__ void mlstm_out_unit(const Params& P, int l, int h, int n, char* lds) {
;     ...
;         const int t = tid >> 3, p = tid & 7; f32x4 hv[8]; float ss = 0.f;
; #pragma unroll
;         for (int j = 0; j < 8; ++j) { hv[j] = *(const f32x4*)(Hb + t * 260 + 32 * j + 4 * p); ss += (hv[j][0] * hv[j][0] + hv[j][1] * hv[j][1]) + (hv[j][2] * hv[j][2] + hv[j][3] * hv[j][3]); }
;         ss += __shfl_xor(ss, 1); ss += __shfl_xor(ss, 2); ss += __shfl_xor(ss, 4);
;         const float rs = rsqrtf(ss * (1.f / 256.f) + RMS_EPS);
;         const size_t row = (size_t)(t0 + t);
; #pragma unroll
;         for (int j = 0; j < 8; ++j) { const int e = 32 * j + 4 * p; const f32x4 gn = *(const f32x4*)(mnorm + e);
;             const u32x2 mo = *(const u32x2*)(PROJ + row * PW + C_MO + h * 256 + e);
;             const float o0 = hv[j][0] * rs * gn[0] * sigmoidf(bflo(mo.x)), o1 = hv[j][1] * rs * gn[1] * sigmoidf(bfhi(mo.x));
;             const float o2 = hv[j][2] * rs * gn[2] * sigmoidf(bflo(mo.y)), o3 = hv[j][3] * rs * gn[3] * sigmoidf(bfhi(mo.y));
;             u32x2 w; w.x = cvt_pk_bf16(o0, o1); w.y = cvt_pk_bf16(o2, o3);
;             *(u32x2*)(MIX + row * DM + h * 256 + e) = w; }
	ds_read_b128 v[30:33], v37
	ds_read_b128 v[26:29], v37 offset:128
	flat_load_dwordx2 v[46:47], v[8:9]
	global_load_dwordx2 v[196:197], v[8:9], off offset:64
	global_load_dwordx2 v[198:199], v[8:9], off offset:128
	global_load_dwordx2 v[200:201], v[8:9], off offset:192
	global_load_dwordx2 v[202:203], v[8:9], off offset:256
	global_load_dwordx2 v[204:205], v[8:9], off offset:320
	global_load_dwordx2 v[206:207], v[8:9], off offset:384
	global_load_dwordx2 v[208:209], v[8:9], off offset:448
	v_mov_b32_e32 v93, v91
	v_lshl_add_u64 v[34:35], s[6:7], 0, v[92:93]
	flat_load_dwordx4 v[40:43], v[34:35]
	global_load_dwordx4 v[212:215], v[34:35], off offset:128
	global_load_dwordx4 v[216:219], v[34:35], off offset:256
	global_load_dwordx4 v[220:223], v[34:35], off offset:384
	global_load_dwordx4 v[224:227], v[34:35], off offset:512
	global_load_dwordx4 v[228:231], v[34:35], off offset:640
	global_load_dwordx4 v[232:235], v[34:35], off offset:768
	global_load_dwordx4 v[236:239], v[34:35], off offset:896
	ds_read_b128 v[22:25], v37 offset:256
	ds_read_b128 v[18:21], v37 offset:384
	s_waitcnt lgkmcnt(0)
	v_mov_b32_e32 v4, v31
	v_mov_b32_e32 v5, v27
	v_mov_b32_e32 v2, v30
	v_mov_b32_e32 v3, v26
	v_pk_mul_f32 v[4:5], v[4:5], v[4:5]
	v_mov_b32_e32 v6, v33
	v_mov_b32_e32 v7, v29
	v_pk_fma_f32 v[2:3], v[2:3], v[2:3], v[4:5]
	v_mov_b32_e32 v4, v32
	v_mov_b32_e32 v5, v28
	v_pk_mul_f32 v[6:7], v[6:7], v[6:7]
	ds_read_b128 v[14:17], v37 offset:512
	ds_read_b128 v[10:13], v37 offset:640
	v_pk_fma_f32 v[4:5], v[4:5], v[4:5], v[6:7]
	v_pk_mul_f32 v[6:7], v[22:23], v[22:23]
	v_pk_add_f32 v[2:3], v[2:3], v[4:5]
	v_pk_mul_f32 v[4:5], v[24:25], v[24:25]
	v_pk_add_f32 v[2:3], v[2:3], v[2:3] op_sel:[0,1] op_sel_hi:[1,0]
	v_pk_mov_b32 v[8:9], v[6:7], v[4:5] op_sel:[1,0]
	v_mov_b32_e32 v7, v5
	v_pk_add_f32 v[4:5], v[8:9], v[6:7]
	s_waitcnt lgkmcnt(0)
	v_mul_f32_e32 v6, v14, v14
	v_mul_f32_e32 v7, v15, v15
	v_pk_add_f32 v[4:5], v[4:5], v[4:5] op_sel:[0,1] op_sel_hi:[1,0]
	v_mov_b32_e32 v3, v6
	v_mov_b32_e32 v5, v7
	v_pk_add_f32 v[2:3], v[2:3], v[4:5]
	v_mul_f32_e32 v4, v19, v19
	v_mul_f32_e32 v6, v21, v21
	v_mul_f32_e32 v8, v16, v16
	v_mul_f32_e32 v9, v17, v17
	v_pk_fma_f32 v[4:5], v[18:19], v[18:19], v[4:5] op_sel_hi:[1,1,0]
	v_pk_fma_f32 v[6:7], v[20:21], v[20:21], v[6:7] op_sel_hi:[1,1,0]
	v_mov_b32_e32 v5, v8
	v_mov_b32_e32 v7, v9
	v_pk_add_f32 v[4:5], v[4:5], v[6:7]
	v_pk_mul_f32 v[48:49], v[12:13], v[12:13]
	v_pk_add_f32 v[38:39], v[2:3], v[4:5]
	ds_read_b128 v[6:9], v37 offset:768
	ds_read_b128 v[2:5], v37 offset:896
	v_pk_mul_f32 v[50:51], v[10:11], v[10:11]
	v_pk_add_f32 v[38:39], v[38:39], v[38:39] op_sel:[0,1] op_sel_hi:[1,0]
	v_pk_mov_b32 v[52:53], v[50:51], v[48:49] op_sel:[1,0]
	v_mov_b32_e32 v51, v49
	v_pk_add_f32 v[48:49], v[52:53], v[50:51]
	s_waitcnt lgkmcnt(0)
	v_mul_f32_e32 v37, v2, v2
	v_mul_f32_e32 v50, v3, v3
	v_pk_add_f32 v[48:49], v[48:49], v[48:49] op_sel:[0,1] op_sel_hi:[1,0]
	v_mov_b32_e32 v39, v37
	v_mov_b32_e32 v49, v50
	v_pk_add_f32 v[38:39], v[38:39], v[48:49]
	v_mul_f32_e32 v48, v7, v7
	v_mul_f32_e32 v51, v4, v4
	v_pk_fma_f32 v[48:49], v[6:7], v[6:7], v[48:49] op_sel_hi:[1,1,0]
	v_mul_f32_e32 v50, v9, v9
	v_mul_f32_e32 v52, v5, v5
	v_mov_b32_e32 v49, v51
	v_pk_fma_f32 v[50:51], v[8:9], v[8:9], v[50:51] op_sel_hi:[1,1,0]
	s_add_u32 s6, s40, s26
	v_mov_b32_e32 v51, v52
	v_pk_add_f32 v[48:49], v[48:49], v[50:51]
	s_addc_u32 s7, s41, 0
	v_pk_add_f32 v[38:39], v[38:39], v[48:49]
	s_nop 0
	v_add_f32_e32 v37, v38, v39
	ds_bpermute_b32 v38, v110, v37
	s_waitcnt lgkmcnt(0)
	v_add_f32_e32 v37, v37, v38
	ds_bpermute_b32 v38, v111, v37
	s_waitcnt vmcnt(0)
	v_lshlrev_b32_e32 v39, 16, v46
	s_waitcnt lgkmcnt(0)
	v_add_f32_e32 v37, v37, v38
	ds_bpermute_b32 v38, v112, v37
	v_mul_f32_e32 v39, 0xbfb8aa3b, v39
	v_exp_f32_e32 v39, v39
	s_waitcnt lgkmcnt(0)
	v_add_f32_e32 v37, v37, v38
	v_fmamk_f32 v37, v37, 0x3b800000, v104
	v_mul_f32_e32 v38, 0x4b800000, v37
	v_cmp_gt_f32_e32 vcc, s62, v37
	v_add_f32_e32 v39, 1.0, v39
	s_nop 0
	v_cndmask_b32_e32 v37, v37, v38, vcc
	v_rsq_f32_e32 v37, v37
	s_nop 0
	v_mul_f32_e32 v38, 0x45800000, v37
	v_cndmask_b32_e32 v38, v37, v38, vcc
	v_ashrrev_i32_e32 v37, 31, v36
	v_lshlrev_b64 v[36:37], 12, v[36:37]
	v_lshl_add_u64 v[48:49], s[6:7], 0, v[36:37]
	v_div_scale_f32 v50, s[6:7], v39, v39, 1.0
	v_rcp_f32_e32 v51, v50
	v_mul_f32_e32 v30, v30, v38
	v_mul_f32_e32 v30, v40, v30
	v_lshl_add_u64 v[36:37], v[44:45], 0, s[34:35]
	v_fma_f32 v40, -v50, v51, 1.0
	v_fmac_f32_e32 v51, v40, v51
	v_div_scale_f32 v40, vcc, 1.0, v39, 1.0
	v_mul_f32_e32 v44, v40, v51
	v_fma_f32 v45, -v50, v44, v40
	v_fmac_f32_e32 v44, v45, v51
	v_and_b32_e32 v45, 0xffff0000, v46
	v_mul_f32_e32 v45, 0xbfb8aa3b, v45
	v_exp_f32_e32 v45, v45
	v_fma_f32 v40, -v50, v44, v40
	v_div_fmas_f32 v40, v40, v51, v44
	v_div_fixup_f32 v39, v40, v39, 1.0
	v_add_f32_e32 v40, 1.0, v45
	v_div_scale_f32 v44, s[6:7], v40, v40, 1.0
	v_rcp_f32_e32 v45, v44
	v_mul_f32_e32 v30, v39, v30
	v_mul_f32_e32 v31, v31, v38
	v_mul_f32_e32 v31, v41, v31
	v_fma_f32 v39, -v44, v45, 1.0
	v_fmac_f32_e32 v45, v39, v45
	v_div_scale_f32 v39, vcc, 1.0, v40, 1.0
	v_mul_f32_e32 v41, v39, v45
	v_fma_f32 v46, -v44, v41, v39
	v_fmac_f32_e32 v41, v46, v45
	v_fma_f32 v39, -v44, v41, v39
	v_lshlrev_b32_e32 v44, 16, v47
	v_mul_f32_e32 v44, 0xbfb8aa3b, v44
	v_exp_f32_e32 v44, v44
	v_div_fmas_f32 v39, v39, v45, v41
	v_div_fixup_f32 v39, v39, v40, 1.0
	v_mul_f32_e32 v31, v39, v31
	v_add_f32_e32 v40, 1.0, v44
	v_div_scale_f32 v41, s[6:7], v40, v40, 1.0
	v_rcp_f32_e32 v44, v41
	v_mul_f32_e32 v32, v32, v38
	v_mul_f32_e32 v32, v42, v32
	v_mul_f32_e32 v33, v33, v38
	v_fma_f32 v39, -v41, v44, 1.0
	v_fmac_f32_e32 v44, v39, v44
; __device__ __forceinline__ unsigned cvt_pk_bf16(float lo, float hi) { unsigned r; asm volatile("v_cvt_pk_bf16_f32 %0, %1, %2" : "=v"(r) : "v"(lo), "v"(hi)); return r; }
; __device__ __forceinline__ float bflo(unsigned w) { return __uint_as_float(w << 16); }
; __device__ __forceinline__ float bfhi(unsigned w) { return __uint_as_float(w & 0xffff0000u); }
; __device__ __forceinline__ float sigmoidf(float x) { return 1.f / (1.f + __expf(-x)); }
; __device__ __forceinline__ void mlstm_out_unit(const Params& P, int l, int h, int n, char* lds) {
;     ...
;         for (int j = 0; j < 8; ++j) { const int e = 32 * j + 4 * p; const f32x4 gn = *(const f32x4*)(mnorm + e);
;             const u32x2 mo = *(const u32x2*)(PROJ + row * PW + C_MO + h * 256 + e);
;             const float o0 = hv[j][0] * rs * gn[0] * sigmoidf(bflo(mo.x)), o1 = hv[j][1] * rs * gn[1] * sigmoidf(bfhi(mo.x));
;             const float o2 = hv[j][2] * rs * gn[2] * sigmoidf(bflo(mo.y)), o3 = hv[j][3] * rs * gn[3] * sigmoidf(bfhi(mo.y));
;             u32x2 w; w.x = cvt_pk_bf16(o0, o1); w.y = cvt_pk_bf16(o2, o3);
;             *(u32x2*)(MIX + row * DM + h * 256 + e) = w; }
	v_div_scale_f32 v39, vcc, 1.0, v40, 1.0
	v_mul_f32_e32 v42, v39, v44
	v_fma_f32 v45, -v41, v42, v39
	v_fmac_f32_e32 v42, v45, v44
	v_fma_f32 v39, -v41, v42, v39
	v_and_b32_e32 v41, 0xffff0000, v47
	v_mul_f32_e32 v41, 0xbfb8aa3b, v41
	v_exp_f32_e32 v41, v41
	v_div_fmas_f32 v39, v39, v44, v42
	v_div_fixup_f32 v39, v39, v40, 1.0
	v_mul_f32_e32 v32, v39, v32
	v_add_f32_e32 v40, 1.0, v41
	v_div_scale_f32 v41, s[6:7], v40, v40, 1.0
	v_rcp_f32_e32 v42, v41
	v_mul_f32_e32 v33, v43, v33
	v_cvt_pk_bf16_f32 v30, v30, v31
	v_mul_f32_e32 v26, v26, v38
	v_fma_f32 v39, -v41, v42, 1.0
	v_fmac_f32_e32 v42, v39, v42
	v_div_scale_f32 v39, vcc, 1.0, v40, 1.0
	v_mul_f32_e32 v43, v39, v42
	v_fma_f32 v44, -v41, v43, v39
	v_fmac_f32_e32 v43, v44, v42
	v_fma_f32 v39, -v41, v43, v39
	v_div_fmas_f32 v39, v39, v42, v43
	v_div_fixup_f32 v39, v39, v40, 1.0
	v_mul_f32_e32 v33, v39, v33
	v_cvt_pk_bf16_f32 v31, v32, v33
	v_lshl_add_u64 v[32:33], v[48:49], 0, v[90:91]
	v_add_co_u32_e32 v40, vcc, s63, v32
	v_mul_f32_e32 v27, v27, v38
	s_nop 0
	v_addc_co_u32_e32 v41, vcc, 0, v33, vcc
	flat_store_dwordx2 v[40:41], v[30:31]
	s_nop 0
	v_mul_f32_e32 v28, v28, v38
	v_mul_f32_e32 v29, v29, v38
	v_mul_f32_e32 v22, v22, v38
	v_mul_f32_e32 v23, v23, v38
	v_mul_f32_e32 v24, v24, v38
	v_mul_f32_e32 v25, v25, v38
	v_mul_f32_e32 v18, v18, v38
	v_mul_f32_e32 v19, v19, v38
	v_mul_f32_e32 v20, v20, v38
	v_mul_f32_e32 v21, v21, v38
	v_mul_f32_e32 v14, v14, v38
	v_mul_f32_e32 v15, v15, v38
	v_mul_f32_e32 v16, v16, v38
	v_mul_f32_e32 v17, v17, v38
	v_mul_f32_e32 v10, v10, v38
	v_mul_f32_e32 v11, v11, v38
	v_mul_f32_e32 v12, v12, v38
	v_mul_f32_e32 v13, v13, v38
	v_mul_f32_e32 v6, v6, v38
	v_mul_f32_e32 v7, v7, v38
	v_mul_f32_e32 v8, v8, v38
	v_mul_f32_e32 v9, v9, v38
	v_mul_f32_e32 v2, v2, v38
	v_mul_f32_e32 v3, v3, v38
	v_mul_f32_e32 v4, v4, v38
	v_mul_f32_e32 v5, v5, v38
	s_nop 1
	v_mov_b32_e32 v44, v196
	v_mov_b32_e32 v45, v197
	v_mov_b32_e32 v40, v212
	v_mov_b32_e32 v41, v213
	v_mov_b32_e32 v42, v214
	v_mov_b32_e32 v43, v215
	v_lshlrev_b32_e32 v30, 16, v44
	v_mul_f32_e32 v30, 0xbfb8aa3b, v30
	v_exp_f32_e32 v30, v30
	v_mul_f32_e32 v26, v40, v26
	v_mul_f32_e32 v27, v41, v27
	v_mul_f32_e32 v28, v42, v28
	v_add_f32_e32 v39, 1.0, v30
	v_div_scale_f32 v46, s[6:7], v39, v39, 1.0
	v_rcp_f32_e32 v47, v46
	v_lshl_add_u64 v[30:31], v[32:33], 0, s[36:37]
	v_mul_f32_e32 v29, v43, v29
	v_fma_f32 v32, -v46, v47, 1.0
	v_fmac_f32_e32 v47, v32, v47
	v_div_scale_f32 v32, vcc, 1.0, v39, 1.0
	v_mul_f32_e32 v33, v32, v47
	v_fma_f32 v40, -v46, v33, v32
	v_fmac_f32_e32 v33, v40, v47
	v_and_b32_e32 v40, 0xffff0000, v44
	v_mul_f32_e32 v40, 0xbfb8aa3b, v40
	v_exp_f32_e32 v40, v40
	v_fma_f32 v32, -v46, v33, v32
	v_div_fmas_f32 v32, v32, v47, v33
	v_div_fixup_f32 v32, v32, v39, 1.0
	v_add_f32_e32 v33, 1.0, v40
	v_div_scale_f32 v39, s[6:7], v33, v33, 1.0
	v_rcp_f32_e32 v40, v39
	v_mul_f32_e32 v26, v32, v26
	v_fma_f32 v32, -v39, v40, 1.0
	v_fmac_f32_e32 v40, v32, v40
	v_div_scale_f32 v32, vcc, 1.0, v33, 1.0
	v_mul_f32_e32 v41, v32, v40
	v_fma_f32 v44, -v39, v41, v32
	v_fmac_f32_e32 v41, v44, v40
	v_fma_f32 v32, -v39, v41, v32
	v_lshlrev_b32_e32 v39, 16, v45
	v_mul_f32_e32 v39, 0xbfb8aa3b, v39
	v_exp_f32_e32 v39, v39
	v_div_fmas_f32 v32, v32, v40, v41
	v_div_fixup_f32 v32, v32, v33, 1.0
	v_mul_f32_e32 v27, v32, v27
	v_add_f32_e32 v33, 1.0, v39
	v_div_scale_f32 v39, s[6:7], v33, v33, 1.0
	v_rcp_f32_e32 v40, v39
	v_cvt_pk_bf16_f32 v26, v26, v27
	s_nop 0
	v_fma_f32 v32, -v39, v40, 1.0
	v_fmac_f32_e32 v40, v32, v40
	v_div_scale_f32 v32, vcc, 1.0, v33, 1.0
	v_mul_f32_e32 v41, v32, v40
	v_fma_f32 v42, -v39, v41, v32
	v_fmac_f32_e32 v41, v42, v40
	v_fma_f32 v32, -v39, v41, v32
	v_and_b32_e32 v39, 0xffff0000, v45
	v_mul_f32_e32 v39, 0xbfb8aa3b, v39
	v_exp_f32_e32 v39, v39
	v_div_fmas_f32 v32, v32, v40, v41
	v_div_fixup_f32 v32, v32, v33, 1.0
	v_mul_f32_e32 v28, v32, v28
	v_add_f32_e32 v33, 1.0, v39
	v_div_scale_f32 v39, s[6:7], v33, v33, 1.0
	v_rcp_f32_e32 v40, v39
	s_nop 0
	v_fma_f32 v32, -v39, v40, 1.0
	v_fmac_f32_e32 v40, v32, v40
	v_div_scale_f32 v32, vcc, 1.0, v33, 1.0
	v_mul_f32_e32 v41, v32, v40
	v_fma_f32 v42, -v39, v41, v32
	v_fmac_f32_e32 v41, v42, v40
	v_fma_f32 v32, -v39, v41, v32
	v_div_fmas_f32 v32, v32, v40, v41
	v_div_fixup_f32 v32, v32, v33, 1.0
	v_mul_f32_e32 v29, v32, v29
	v_cvt_pk_bf16_f32 v27, v28, v29
	flat_store_dwordx2 v[30:31], v[26:27] offset:64
	s_nop 0
	s_nop 1
	v_mov_b32_e32 v32, v198
	v_mov_b32_e32 v33, v199
	v_mov_b32_e32 v26, v216
	v_mov_b32_e32 v27, v217
	v_mov_b32_e32 v28, v218
	v_mov_b32_e32 v29, v219
	v_lshlrev_b32_e32 v39, 16, v32
	v_mul_f32_e32 v39, 0xbfb8aa3b, v39
	v_exp_f32_e32 v39, v39
	v_mul_f32_e32 v22, v26, v22
	v_and_b32_e32 v32, 0xffff0000, v32
	v_mul_f32_e32 v32, 0xbfb8aa3b, v32
	v_add_f32_e32 v39, 1.0, v39
	v_div_scale_f32 v40, s[6:7], v39, v39, 1.0
	v_rcp_f32_e32 v41, v40
	v_exp_f32_e32 v32, v32
	v_mul_f32_e32 v23, v27, v23
	v_mul_f32_e32 v24, v28, v24
	v_fma_f32 v26, -v40, v41, 1.0
	v_fmac_f32_e32 v41, v26, v41
	v_div_scale_f32 v26, vcc, 1.0, v39, 1.0
	v_mul_f32_e32 v42, v26, v41
	v_fma_f32 v43, -v40, v42, v26
	v_fmac_f32_e32 v42, v43, v41
	v_fma_f32 v26, -v40, v42, v26
	v_div_fmas_f32 v26, v26, v41, v42
	v_add_f32_e32 v32, 1.0, v32
	v_div_fixup_f32 v26, v26, v39, 1.0
	v_div_scale_f32 v39, s[6:7], v32, v32, 1.0
	v_rcp_f32_e32 v40, v39
	v_mul_f32_e32 v22, v22, v26
	v_mul_f32_e32 v25, v29, v25
	v_fma_f32 v26, -v39, v40, 1.0
	v_fmac_f32_e32 v40, v26, v40
	v_div_scale_f32 v26, vcc, 1.0, v32, 1.0
	v_mul_f32_e32 v27, v26, v40
	v_fma_f32 v41, -v39, v27, v26
	v_fmac_f32_e32 v27, v41, v40
	v_fma_f32 v26, -v39, v27, v26
	v_lshlrev_b32_e32 v39, 16, v33
	v_mul_f32_e32 v39, 0xbfb8aa3b, v39
; __device__ __forceinline__ unsigned cvt_pk_bf16(float lo, float hi) { unsigned r; asm volatile("v_cvt_pk_bf16_f32 %0, %1, %2" : "=v"(r) : "v"(lo), "v"(hi)); return r; }
; __device__ __forceinline__ float bflo(unsigned w) { return __uint_as_float(w << 16); }
; __device__ __forceinline__ float bfhi(unsigned w) { return __uint_as_float(w & 0xffff0000u); }
; __device__ __forceinline__ float sigmoidf(float x) { return 1.f / (1.f + __expf(-x)); }
; __device__ __forceinline__ void mlstm_out_unit(const Params& P, int l, int h, int n, char* lds) {
;     ...
;         for (int j = 0; j < 8; ++j) { const int e = 32 * j + 4 * p; const f32x4 gn = *(const f32x4*)(mnorm + e);
;             const u32x2 mo = *(const u32x2*)(PROJ + row * PW + C_MO + h * 256 + e);
;             const float o0 = hv[j][0] * rs * gn[0] * sigmoidf(bflo(mo.x)), o1 = hv[j][1] * rs * gn[1] * sigmoidf(bfhi(mo.x));
;             const float o2 = hv[j][2] * rs * gn[2] * sigmoidf(bflo(mo.y)), o3 = hv[j][3] * rs * gn[3] * sigmoidf(bfhi(mo.y));
;             u32x2 w; w.x = cvt_pk_bf16(o0, o1); w.y = cvt_pk_bf16(o2, o3);
;             *(u32x2*)(MIX + row * DM + h * 256 + e) = w; }
	v_exp_f32_e32 v39, v39
	v_div_fmas_f32 v26, v26, v40, v27
	v_div_fixup_f32 v26, v26, v32, 1.0
	v_mul_f32_e32 v23, v23, v26
	v_add_f32_e32 v27, 1.0, v39
	v_div_scale_f32 v32, s[6:7], v27, v27, 1.0
	v_rcp_f32_e32 v39, v32
	v_cvt_pk_bf16_f32 v22, v22, v23
	s_nop 0
	v_fma_f32 v26, -v32, v39, 1.0
	v_fmac_f32_e32 v39, v26, v39
	v_div_scale_f32 v26, vcc, 1.0, v27, 1.0
	v_mul_f32_e32 v28, v26, v39
	v_fma_f32 v40, -v32, v28, v26
	v_fmac_f32_e32 v28, v40, v39
	v_fma_f32 v26, -v32, v28, v26
	v_and_b32_e32 v32, 0xffff0000, v33
	v_mul_f32_e32 v32, 0xbfb8aa3b, v32
	v_exp_f32_e32 v32, v32
	v_div_fmas_f32 v26, v26, v39, v28
	v_div_fixup_f32 v26, v26, v27, 1.0
	v_mul_f32_e32 v24, v24, v26
	v_add_f32_e32 v27, 1.0, v32
	v_div_scale_f32 v28, s[6:7], v27, v27, 1.0
	v_rcp_f32_e32 v32, v28
	s_nop 0
	v_fma_f32 v26, -v28, v32, 1.0
	v_fmac_f32_e32 v32, v26, v32
	v_div_scale_f32 v26, vcc, 1.0, v27, 1.0
	v_mul_f32_e32 v29, v26, v32
	v_fma_f32 v33, -v28, v29, v26
	v_fmac_f32_e32 v29, v33, v32
	v_fma_f32 v26, -v28, v29, v26
	v_div_fmas_f32 v26, v26, v32, v29
	v_div_fixup_f32 v26, v26, v27, 1.0
	v_mul_f32_e32 v25, v25, v26
	v_cvt_pk_bf16_f32 v23, v24, v25
	flat_store_dwordx2 v[30:31], v[22:23] offset:128
	s_nop 0
	s_nop 1
	v_mov_b32_e32 v22, v220
	v_mov_b32_e32 v23, v221
	v_mov_b32_e32 v24, v222
	v_mov_b32_e32 v25, v223
	v_mov_b32_e32 v26, v200
	v_mov_b32_e32 v27, v201
	v_mul_f32_e32 v18, v18, v22
	v_lshlrev_b32_e32 v22, 16, v26
	v_mul_f32_e32 v22, 0xbfb8aa3b, v22
	v_exp_f32_e32 v22, v22
	v_and_b32_e32 v26, 0xffff0000, v26
	v_mul_f32_e32 v26, 0xbfb8aa3b, v26
	v_exp_f32_e32 v26, v26
	v_add_f32_e32 v22, 1.0, v22
	v_div_scale_f32 v28, s[6:7], v22, v22, 1.0
	v_rcp_f32_e32 v29, v28
	v_div_scale_f32 v32, vcc, 1.0, v22, 1.0
	v_add_f32_e32 v26, 1.0, v26
	v_fma_f32 v33, -v28, v29, 1.0
	v_fmac_f32_e32 v29, v33, v29
	v_mul_f32_e32 v33, v32, v29
	v_fma_f32 v39, -v28, v33, v32
	v_fmac_f32_e32 v33, v39, v29
	v_fma_f32 v28, -v28, v33, v32
	v_div_fmas_f32 v28, v28, v29, v33
	v_div_fixup_f32 v22, v28, v22, 1.0
	v_div_scale_f32 v28, s[6:7], v26, v26, 1.0
	v_rcp_f32_e32 v29, v28
	v_mul_f32_e32 v18, v18, v22
	v_mul_f32_e32 v19, v19, v23
	v_mul_f32_e32 v20, v20, v24
	v_fma_f32 v22, -v28, v29, 1.0
	v_fmac_f32_e32 v29, v22, v29
	v_div_scale_f32 v22, vcc, 1.0, v26, 1.0
	v_mul_f32_e32 v23, v22, v29
	v_fma_f32 v32, -v28, v23, v22
	v_fmac_f32_e32 v23, v32, v29
	v_fma_f32 v22, -v28, v23, v22
	v_lshlrev_b32_e32 v28, 16, v27
	v_mul_f32_e32 v28, 0xbfb8aa3b, v28
	v_exp_f32_e32 v28, v28
	v_div_fmas_f32 v22, v22, v29, v23
	v_div_fixup_f32 v22, v22, v26, 1.0
	v_mul_f32_e32 v19, v19, v22
	v_add_f32_e32 v23, 1.0, v28
	v_div_scale_f32 v26, s[6:7], v23, v23, 1.0
	v_rcp_f32_e32 v28, v26
	v_mul_f32_e32 v21, v21, v25
	v_cvt_pk_bf16_f32 v18, v18, v19
	v_fma_f32 v22, -v26, v28, 1.0
	v_fmac_f32_e32 v28, v22, v28
	v_div_scale_f32 v22, vcc, 1.0, v23, 1.0
	v_mul_f32_e32 v24, v22, v28
	v_fma_f32 v29, -v26, v24, v22
	v_fmac_f32_e32 v24, v29, v28
	v_fma_f32 v22, -v26, v24, v22
	v_and_b32_e32 v26, 0xffff0000, v27
	v_mul_f32_e32 v26, 0xbfb8aa3b, v26
	v_exp_f32_e32 v26, v26
	v_div_fmas_f32 v22, v22, v28, v24
	v_div_fixup_f32 v22, v22, v23, 1.0
	v_mul_f32_e32 v20, v20, v22
	v_add_f32_e32 v23, 1.0, v26
	v_div_scale_f32 v24, s[6:7], v23, v23, 1.0
	v_rcp_f32_e32 v26, v24
	s_nop 0
	v_fma_f32 v22, -v24, v26, 1.0
	v_fmac_f32_e32 v26, v22, v26
	v_div_scale_f32 v22, vcc, 1.0, v23, 1.0
	v_mul_f32_e32 v25, v22, v26
	v_fma_f32 v27, -v24, v25, v22
	v_fmac_f32_e32 v25, v27, v26
	v_fma_f32 v22, -v24, v25, v22
	v_div_fmas_f32 v22, v22, v26, v25
	v_div_fixup_f32 v22, v22, v23, 1.0
	v_mul_f32_e32 v21, v21, v22
	v_cvt_pk_bf16_f32 v19, v20, v21
	flat_store_dwordx2 v[30:31], v[18:19] offset:192
	s_nop 0
	s_nop 1
	v_mov_b32_e32 v18, v224
	v_mov_b32_e32 v19, v225
	v_mov_b32_e32 v20, v226
	v_mov_b32_e32 v21, v227
	v_mov_b32_e32 v22, v202
	v_mov_b32_e32 v23, v203
	v_mul_f32_e32 v14, v14, v18
	v_lshlrev_b32_e32 v18, 16, v22
	v_mul_f32_e32 v15, v15, v19
	v_and_b32_e32 v19, 0xffff0000, v22
	v_mul_f32_e32 v18, 0xbfb8aa3b, v18
	v_mul_f32_e32 v19, 0xbfb8aa3b, v19
	v_exp_f32_e32 v18, v18
	v_exp_f32_e32 v19, v19
	v_lshlrev_b32_e32 v22, 16, v23
	v_mul_f32_e32 v22, 0xbfb8aa3b, v22
	v_add_f32_e32 v18, 1.0, v18
	v_add_f32_e32 v19, 1.0, v19
	v_div_scale_f32 v24, s[6:7], v18, v18, 1.0
	v_div_scale_f32 v26, s[6:7], v19, v19, 1.0
	v_rcp_f32_e32 v27, v24
	v_rcp_f32_e32 v28, v26
	v_div_scale_f32 v25, vcc, 1.0, v18, 1.0
	v_fma_f32 v32, -v24, v27, 1.0
	v_fma_f32 v33, -v26, v28, 1.0
	v_fmac_f32_e32 v27, v32, v27
	v_div_scale_f32 v29, s[6:7], 1.0, v19, 1.0
	v_fmac_f32_e32 v28, v33, v28
	v_mul_f32_e32 v32, v25, v27
	v_mul_f32_e32 v33, v29, v28
	v_fma_f32 v39, -v24, v32, v25
	v_exp_f32_e32 v22, v22
	v_fma_f32 v40, -v26, v33, v29
	v_fmac_f32_e32 v32, v39, v27
	v_fmac_f32_e32 v33, v40, v28
	v_fma_f32 v24, -v24, v32, v25
	v_fma_f32 v25, -v26, v33, v29
	v_div_fmas_f32 v24, v24, v27, v32
	s_mov_b64 vcc, s[6:7]
	v_div_fixup_f32 v18, v24, v18, 1.0
	v_div_fmas_f32 v24, v25, v28, v33
	v_mul_f32_e32 v14, v14, v18
	v_div_fixup_f32 v18, v24, v19, 1.0
	v_add_f32_e32 v19, 1.0, v22
	v_div_scale_f32 v22, s[6:7], v19, v19, 1.0
	v_rcp_f32_e32 v24, v22
	v_mul_f32_e32 v15, v15, v18
	v_mul_f32_e32 v16, v16, v20
	v_mul_f32_e32 v17, v17, v21
	v_fma_f32 v18, -v22, v24, 1.0
	v_fmac_f32_e32 v24, v18, v24
	v_div_scale_f32 v18, vcc, 1.0, v19, 1.0
	v_mul_f32_e32 v20, v18, v24
	v_fma_f32 v25, -v22, v20, v18
	v_fmac_f32_e32 v20, v25, v24
	v_fma_f32 v18, -v22, v20, v18
	v_and_b32_e32 v22, 0xffff0000, v23
	v_mul_f32_e32 v22, 0xbfb8aa3b, v22
	v_exp_f32_e32 v22, v22
	v_div_fmas_f32 v18, v18, v24, v20
	v_div_fixup_f32 v18, v18, v19, 1.0
	v_mul_f32_e32 v16, v16, v18
	v_add_f32_e32 v19, 1.0, v22
; __device__ __forceinline__ unsigned cvt_pk_bf16(float lo, float hi) { unsigned r; asm volatile("v_cvt_pk_bf16_f32 %0, %1, %2" : "=v"(r) : "v"(lo), "v"(hi)); return r; }
; __device__ __forceinline__ float bflo(unsigned w) { return __uint_as_float(w << 16); }
; __device__ __forceinline__ float bfhi(unsigned w) { return __uint_as_float(w & 0xffff0000u); }
; __device__ __forceinline__ float sigmoidf(float x) { return 1.f / (1.f + __expf(-x)); }
; __device__ __forceinline__ void mlstm_out_unit(const Params& P, int l, int h, int n, char* lds) {
;     ...
;         for (int j = 0; j < 8; ++j) { const int e = 32 * j + 4 * p; const f32x4 gn = *(const f32x4*)(mnorm + e);
;             const u32x2 mo = *(const u32x2*)(PROJ + row * PW + C_MO + h * 256 + e);
;             const float o0 = hv[j][0] * rs * gn[0] * sigmoidf(bflo(mo.x)), o1 = hv[j][1] * rs * gn[1] * sigmoidf(bfhi(mo.x));
;             const float o2 = hv[j][2] * rs * gn[2] * sigmoidf(bflo(mo.y)), o3 = hv[j][3] * rs * gn[3] * sigmoidf(bfhi(mo.y));
;             u32x2 w; w.x = cvt_pk_bf16(o0, o1); w.y = cvt_pk_bf16(o2, o3);
;             *(u32x2*)(MIX + row * DM + h * 256 + e) = w; }
	v_div_scale_f32 v20, s[6:7], v19, v19, 1.0
	v_rcp_f32_e32 v22, v20
	v_cvt_pk_bf16_f32 v14, v14, v15
	s_nop 0
	v_fma_f32 v18, -v20, v22, 1.0
	v_fmac_f32_e32 v22, v18, v22
	v_div_scale_f32 v18, vcc, 1.0, v19, 1.0
	v_mul_f32_e32 v21, v18, v22
	v_fma_f32 v23, -v20, v21, v18
	v_fmac_f32_e32 v21, v23, v22
	v_fma_f32 v18, -v20, v21, v18
	v_div_fmas_f32 v18, v18, v22, v21
	v_div_fixup_f32 v18, v18, v19, 1.0
	v_mul_f32_e32 v17, v17, v18
	v_cvt_pk_bf16_f32 v15, v16, v17
	flat_store_dwordx2 v[30:31], v[14:15] offset:256
	s_nop 0
	s_nop 1
	v_mov_b32_e32 v14, v228
	v_mov_b32_e32 v15, v229
	v_mov_b32_e32 v16, v230
	v_mov_b32_e32 v17, v231
	v_mov_b32_e32 v18, v204
	v_mov_b32_e32 v19, v205
	v_mul_f32_e32 v10, v10, v14
	v_lshlrev_b32_e32 v14, 16, v18
	v_mul_f32_e32 v11, v11, v15
	v_and_b32_e32 v15, 0xffff0000, v18
	v_mul_f32_e32 v14, 0xbfb8aa3b, v14
	v_mul_f32_e32 v15, 0xbfb8aa3b, v15
	v_exp_f32_e32 v14, v14
	v_exp_f32_e32 v15, v15
	v_mul_f32_e32 v12, v12, v16
	v_lshlrev_b32_e32 v16, 16, v19
	v_add_f32_e32 v14, 1.0, v14
	v_and_b32_e32 v18, 0xffff0000, v19
	v_add_f32_e32 v15, 1.0, v15
	v_div_scale_f32 v19, s[6:7], v14, v14, 1.0
	v_mul_f32_e32 v16, 0xbfb8aa3b, v16
	v_div_scale_f32 v21, s[6:7], v15, v15, 1.0
	v_rcp_f32_e32 v24, v19
	v_exp_f32_e32 v16, v16
	v_rcp_f32_e32 v25, v21
	v_div_scale_f32 v20, vcc, 1.0, v14, 1.0
	v_fma_f32 v28, -v19, v24, 1.0
	v_add_f32_e32 v16, 1.0, v16
	v_fma_f32 v29, -v21, v25, 1.0
	v_fmac_f32_e32 v24, v28, v24
	v_div_scale_f32 v22, s[6:7], 1.0, v15, 1.0
	v_div_scale_f32 v23, s[8:9], v16, v16, 1.0
	v_fmac_f32_e32 v25, v29, v25
	v_mul_f32_e32 v28, v20, v24
	v_rcp_f32_e32 v26, v23
	v_mul_f32_e32 v29, v22, v25
	v_fma_f32 v33, -v19, v28, v20
	v_fma_f32 v39, -v21, v29, v22
	v_fmac_f32_e32 v28, v33, v24
	v_fmac_f32_e32 v29, v39, v25
	v_fma_f32 v19, -v19, v28, v20
	v_fma_f32 v20, -v21, v29, v22
	v_div_fmas_f32 v19, v19, v24, v28
	s_mov_b64 vcc, s[6:7]
	v_fma_f32 v32, -v23, v26, 1.0
	v_div_fixup_f32 v14, v19, v14, 1.0
	v_div_fmas_f32 v19, v20, v25, v29
	v_mul_f32_e32 v18, 0xbfb8aa3b, v18
	v_div_scale_f32 v27, s[8:9], 1.0, v16, 1.0
	v_fmac_f32_e32 v26, v32, v26
	v_mul_f32_e32 v10, v10, v14
	v_div_fixup_f32 v14, v19, v15, 1.0
	v_mul_f32_e32 v32, v27, v26
	v_mul_f32_e32 v11, v11, v14
	v_exp_f32_e32 v14, v18
	v_fma_f32 v40, -v23, v32, v27
	v_fmac_f32_e32 v32, v40, v26
	v_fma_f32 v21, -v23, v32, v27
	s_mov_b64 vcc, s[8:9]
	v_div_fmas_f32 v15, v21, v26, v32
	v_add_f32_e32 v14, 1.0, v14
	v_div_fixup_f32 v15, v15, v16, 1.0
	v_div_scale_f32 v16, s[6:7], v14, v14, 1.0
	v_rcp_f32_e32 v18, v16
	v_mul_f32_e32 v12, v12, v15
	v_mul_f32_e32 v13, v13, v17
	v_cvt_pk_bf16_f32 v10, v10, v11
	v_fma_f32 v15, -v16, v18, 1.0
	v_fmac_f32_e32 v18, v15, v18
	v_div_scale_f32 v15, vcc, 1.0, v14, 1.0
	v_mul_f32_e32 v17, v15, v18
	v_fma_f32 v19, -v16, v17, v15
	v_fmac_f32_e32 v17, v19, v18
	v_fma_f32 v15, -v16, v17, v15
	v_div_fmas_f32 v15, v15, v18, v17
	v_div_fixup_f32 v14, v15, v14, 1.0
	v_mul_f32_e32 v13, v13, v14
	v_cvt_pk_bf16_f32 v11, v12, v13
	flat_store_dwordx2 v[30:31], v[10:11] offset:320
	s_nop 0
	s_nop 1
	v_mov_b32_e32 v10, v232
	v_mov_b32_e32 v11, v233
	v_mov_b32_e32 v12, v234
	v_mov_b32_e32 v13, v235
	v_mov_b32_e32 v14, v206
	v_mov_b32_e32 v15, v207
	v_mul_f32_e32 v6, v6, v10
	v_lshlrev_b32_e32 v10, 16, v14
	v_mul_f32_e32 v7, v7, v11
	v_and_b32_e32 v11, 0xffff0000, v14
	v_mul_f32_e32 v10, 0xbfb8aa3b, v10
	v_mul_f32_e32 v8, v8, v12
	v_lshlrev_b32_e32 v12, 16, v15
	v_mul_f32_e32 v11, 0xbfb8aa3b, v11
	v_exp_f32_e32 v10, v10
	v_mul_f32_e32 v12, 0xbfb8aa3b, v12
	v_exp_f32_e32 v11, v11
	v_exp_f32_e32 v12, v12
	v_mul_f32_e32 v9, v9, v13
	v_and_b32_e32 v13, 0xffff0000, v15
	v_mul_f32_e32 v13, 0xbfb8aa3b, v13
	v_add_f32_e32 v10, 1.0, v10
	v_exp_f32_e32 v13, v13
	v_add_f32_e32 v11, 1.0, v11
	v_div_scale_f32 v14, s[6:7], v10, v10, 1.0
	v_add_f32_e32 v12, 1.0, v12
	v_div_scale_f32 v16, s[6:7], v11, v11, 1.0
	v_rcp_f32_e32 v22, v14
	v_div_scale_f32 v18, s[8:9], v12, v12, 1.0
	v_rcp_f32_e32 v23, v16
	v_rcp_f32_e32 v24, v18
	v_add_f32_e32 v13, 1.0, v13
	v_div_scale_f32 v20, s[10:11], v13, v13, 1.0
; __device__ __forceinline__ unsigned cvt_pk_bf16(float lo, float hi) { unsigned r; asm volatile("v_cvt_pk_bf16_f32 %0, %1, %2" : "=v"(r) : "v"(lo), "v"(hi)); return r; }
; __device__ __forceinline__ float bflo(unsigned w) { return __uint_as_float(w << 16); }
; __device__ __forceinline__ float bfhi(unsigned w) { return __uint_as_float(w & 0xffff0000u); }
; __device__ __forceinline__ float sigmoidf(float x) { return 1.f / (1.f + __expf(-x)); }
; __device__ __forceinline__ void mlstm_out_unit(const Params& P, int l, int h, int n, char* lds) {
;     ...
;         for (int j = 0; j < 8; ++j) { const int e = 32 * j + 4 * p; const f32x4 gn = *(const f32x4*)(mnorm + e);
;             const u32x2 mo = *(const u32x2*)(PROJ + row * PW + C_MO + h * 256 + e);
;             const float o0 = hv[j][0] * rs * gn[0] * sigmoidf(bflo(mo.x)), o1 = hv[j][1] * rs * gn[1] * sigmoidf(bfhi(mo.x));
;             const float o2 = hv[j][2] * rs * gn[2] * sigmoidf(bflo(mo.y)), o3 = hv[j][3] * rs * gn[3] * sigmoidf(bfhi(mo.y));
;             u32x2 w; w.x = cvt_pk_bf16(o0, o1); w.y = cvt_pk_bf16(o2, o3);
;             *(u32x2*)(MIX + row * DM + h * 256 + e) = w; }
	v_fma_f32 v26, -v14, v22, 1.0
	v_div_scale_f32 v15, vcc, 1.0, v10, 1.0
	v_rcp_f32_e32 v25, v20
	v_fma_f32 v27, -v16, v23, 1.0
	v_fmac_f32_e32 v22, v26, v22
	v_div_scale_f32 v17, s[6:7], 1.0, v11, 1.0
	v_fma_f32 v28, -v18, v24, 1.0
	v_fmac_f32_e32 v23, v27, v23
	v_mul_f32_e32 v26, v15, v22
	v_div_scale_f32 v19, s[8:9], 1.0, v12, 1.0
	v_fmac_f32_e32 v24, v28, v24
	v_mul_f32_e32 v27, v17, v23
	v_fma_f32 v32, -v14, v26, v15
	v_mul_f32_e32 v28, v19, v24
	v_fma_f32 v33, -v16, v27, v17
	v_fmac_f32_e32 v26, v32, v22
	v_fma_f32 v29, -v20, v25, 1.0
	v_fma_f32 v39, -v18, v28, v19
	v_fmac_f32_e32 v27, v33, v23
	v_fma_f32 v14, -v14, v26, v15
	v_div_scale_f32 v21, s[10:11], 1.0, v13, 1.0
	v_fmac_f32_e32 v25, v29, v25
	v_fmac_f32_e32 v28, v39, v24
	v_fma_f32 v15, -v16, v27, v17
	v_div_fmas_f32 v14, v14, v22, v26
	s_mov_b64 vcc, s[6:7]
	v_mul_f32_e32 v29, v21, v25
	v_fma_f32 v16, -v18, v28, v19
	v_div_fixup_f32 v10, v14, v10, 1.0
	v_div_fmas_f32 v14, v15, v23, v27
	s_mov_b64 vcc, s[8:9]
	v_fma_f32 v40, -v20, v29, v21
	v_mul_f32_e32 v6, v6, v10
	v_div_fixup_f32 v10, v14, v11, 1.0
	v_div_fmas_f32 v11, v16, v24, v28
	v_fmac_f32_e32 v29, v40, v25
	v_mul_f32_e32 v7, v7, v10
	v_div_fixup_f32 v10, v11, v12, 1.0
	v_mul_f32_e32 v8, v8, v10
	v_fma_f32 v10, -v20, v29, v21
	s_mov_b64 vcc, s[10:11]
	v_div_fmas_f32 v10, v10, v25, v29
	v_div_fixup_f32 v10, v10, v13, 1.0
	v_mul_f32_e32 v9, v9, v10
	v_cvt_pk_bf16_f32 v6, v6, v7
	v_cvt_pk_bf16_f32 v7, v8, v9
	flat_store_dwordx2 v[30:31], v[6:7] offset:384
	s_nop 0
	s_nop 1
	v_mov_b32_e32 v6, v236
	v_mov_b32_e32 v7, v237
	v_mov_b32_e32 v8, v238
	v_mov_b32_e32 v9, v239
	v_mov_b32_e32 v10, v208
	v_mov_b32_e32 v11, v209
	v_mul_f32_e32 v2, v2, v6
	v_lshlrev_b32_e32 v6, 16, v10
	v_mul_f32_e32 v3, v3, v7
	v_and_b32_e32 v7, 0xffff0000, v10
	v_mul_f32_e32 v6, 0xbfb8aa3b, v6
	v_mul_f32_e32 v4, v4, v8
	v_lshlrev_b32_e32 v8, 16, v11
	v_mul_f32_e32 v7, 0xbfb8aa3b, v7
	v_exp_f32_e32 v6, v6
	v_mul_f32_e32 v5, v5, v9
	v_and_b32_e32 v9, 0xffff0000, v11
	v_mul_f32_e32 v8, 0xbfb8aa3b, v8
	v_exp_f32_e32 v7, v7
	v_mul_f32_e32 v9, 0xbfb8aa3b, v9
	v_exp_f32_e32 v8, v8
	v_exp_f32_e32 v9, v9
	v_add_f32_e32 v6, 1.0, v6
	v_add_f32_e32 v7, 1.0, v7
	v_div_scale_f32 v10, s[6:7], v6, v6, 1.0
	v_add_f32_e32 v8, 1.0, v8
	v_div_scale_f32 v12, s[6:7], v7, v7, 1.0
	v_rcp_f32_e32 v18, v10
	v_add_f32_e32 v9, 1.0, v9
	v_div_scale_f32 v14, s[8:9], v8, v8, 1.0
	v_rcp_f32_e32 v19, v12
	v_div_scale_f32 v16, s[10:11], v9, v9, 1.0
	v_rcp_f32_e32 v20, v14
	v_rcp_f32_e32 v21, v16
	v_fma_f32 v22, -v10, v18, 1.0
	v_div_scale_f32 v11, vcc, 1.0, v6, 1.0
	v_fma_f32 v23, -v12, v19, 1.0
	v_fmac_f32_e32 v18, v22, v18
	v_div_scale_f32 v13, s[6:7], 1.0, v7, 1.0
	v_fma_f32 v24, -v14, v20, 1.0
	v_fmac_f32_e32 v19, v23, v19
	v_mul_f32_e32 v22, v11, v18
	v_div_scale_f32 v15, s[8:9], 1.0, v8, 1.0
	v_fma_f32 v25, -v16, v21, 1.0
	v_fmac_f32_e32 v20, v24, v20
	v_mul_f32_e32 v23, v13, v19
	v_fma_f32 v26, -v10, v22, v11
	v_div_scale_f32 v17, s[10:11], 1.0, v9, 1.0
	v_fmac_f32_e32 v21, v25, v21
	v_mul_f32_e32 v24, v15, v20
	v_fma_f32 v27, -v12, v23, v13
	v_fmac_f32_e32 v22, v26, v18
	v_mul_f32_e32 v25, v17, v21
	v_fma_f32 v28, -v14, v24, v15
	v_fmac_f32_e32 v23, v27, v19
	v_fma_f32 v10, -v10, v22, v11
	v_fma_f32 v29, -v16, v25, v17
	v_fmac_f32_e32 v24, v28, v20
	v_fma_f32 v11, -v12, v23, v13
	v_div_fmas_f32 v10, v10, v18, v22
	s_mov_b64 vcc, s[6:7]
	v_fmac_f32_e32 v25, v29, v21
	v_fma_f32 v12, -v14, v24, v15
	v_div_fixup_f32 v6, v10, v6, 1.0
	v_div_fmas_f32 v10, v11, v19, v23
	s_mov_b64 vcc, s[8:9]
	v_fma_f32 v13, -v16, v25, v17
	v_mul_f32_e32 v2, v2, v6
	v_div_fixup_f32 v6, v10, v7, 1.0
	v_div_fmas_f32 v7, v12, v20, v24
	s_mov_b64 vcc, s[10:11]
	v_mul_f32_e32 v3, v3, v6
	v_div_fixup_f32 v6, v7, v8, 1.0
	v_div_fmas_f32 v7, v13, v21, v25
	v_mul_f32_e32 v4, v4, v6
	v_div_fixup_f32 v6, v7, v9, 1.0
	v_cvt_pk_bf16_f32 v2, v2, v3
	v_mul_f32_e32 v3, v5, v6
	s_mov_b64 s[6:7], 0
	v_cvt_pk_bf16_f32 v3, v4, v3
	flat_store_dwordx2 v[30:31], v[2:3] offset:448
	s_waitcnt lgkmcnt(0)
	s_barrier

; __device__ __forceinline__ unsigned cvt_pk_bf16(float lo, float hi) { unsigned r; asm volatile("v_cvt_pk_bf16_f32 %0, %1, %2" : "=v"(r) : "v"(lo), "v"(hi)); return r; }
;     __device__ __forceinline__ void operator()(const pg8::f32x4 (&acc)[2][2][4][2], const pg8::Unit& u, int wr, int wc, int fr, int fq) const {
;         const int row0 = NMETA + u.pm * 256 + wr * 64 + fr, col0 = u.pn * 256 + wc * 32 + 8 * fq;
; #pragma unroll
;         for (int ai = 0; ai < 2; ++ai)
; #pragma unroll
;             for (int m = 0; m < 4; ++m) { bf16_t* rowp = O + (size_t)(row0 + ai * 128 + m * 16) * DFF + col0;
; #pragma unroll
;                 for (int bj = 0; bj < 2; ++bj) { pg8::f32x4 v0 = acc[ai][bj][m][0], v1 = acc[ai][bj][m][1];
; #pragma unroll
;                     for (int i = 0; i < 4; ++i) { const float a = fmaxf(v0[i], 0.f), b = fmaxf(v1[i], 0.f); v0[i] = a * a; v1[i] = b * b; }
;                     u32x4 w; w.x = cvt_pk_bf16(v0[0], v0[1]); w.y = cvt_pk_bf16(v0[2], v0[3]); w.z = cvt_pk_bf16(v1[0], v1[1]); w.w = cvt_pk_bf16(v1[2], v1[3]);
;                     *(u32x4*)(rowp + bj * 128) = w; } }
.LBB0_1293:
	v_lshl_add_u32 v154, s42, 8, v1
	v_max_f32_e32 v122, v122, v122
	v_ashrrev_i32_e32 v155, 31, v154
	v_max_f32_e32 v122, 0, v122
	v_max_f32_e32 v123, v123, v123
	v_max_f32_e32 v124, v124, v124
	v_lshl_or_b32 v146, s68, 8, v148
	v_lshlrev_b64 v[156:157], 14, v[154:155]
	v_mul_f32_e32 v155, v122, v122
	v_max_f32_e32 v122, v127, v127
	v_max_f32_e32 v123, 0, v123
	v_max_f32_e32 v124, 0, v124
	v_ashrrev_i32_e32 v147, 31, v146
	v_max_f32_e32 v126, v126, v126
	v_max_f32_e32 v122, 0, v122
	v_mul_f32_e32 v127, v123, v123
	v_max_f32_e32 v123, v128, v128
	v_mul_f32_e32 v128, v124, v124
	v_max_f32_e32 v124, v129, v129
	v_max_f32_e32 v125, v125, v125
	v_lshl_add_u64 v[156:157], s[10:11], 0, v[156:157]
	v_lshlrev_b64 v[158:159], 1, v[146:147]
	v_max_f32_e32 v126, 0, v126
	v_mul_f32_e32 v122, v122, v122
	v_max_f32_e32 v123, 0, v123
	v_max_f32_e32 v124, 0, v124
	v_max_f32_e32 v125, 0, v125
	v_max_f32_e32 v114, v114, v114
	v_max_f32_e32 v115, v115, v115
	v_max_f32_e32 v116, v116, v116
	v_lshl_add_u64 v[146:147], v[156:157], 0, v[158:159]
	v_mul_f32_e32 v126, v126, v126
	v_mul_f32_e32 v123, v123, v123
	v_mul_f32_e32 v124, v124, v124
	v_mul_f32_e32 v125, v125, v125
	v_cvt_pk_bf16_f32 v122, v126, v122
	v_max_f32_e32 v114, 0, v114
	v_max_f32_e32 v115, 0, v115
	v_max_f32_e32 v116, 0, v116
	v_cvt_pk_bf16_f32 v123, v123, v124
	v_cvt_pk_bf16_f32 v124, v155, v127
	v_cvt_pk_bf16_f32 v125, v128, v125
	flat_store_dwordx4 v[146:147], v[122:125] nt
	v_max_f32_e32 v118, v118, v118
	v_max_f32_e32 v117, v117, v117
	v_mul_f32_e32 v122, v114, v114
	v_max_f32_e32 v114, v119, v119
	v_mul_f32_e32 v119, v115, v115
	v_max_f32_e32 v115, v120, v120
	v_mul_f32_e32 v120, v116, v116
	v_max_f32_e32 v116, v121, v121
	v_max_f32_e32 v114, 0, v114
	v_max_f32_e32 v115, 0, v115
	v_max_f32_e32 v116, 0, v116
	v_max_f32_e32 v118, 0, v118
	v_mul_f32_e32 v114, v114, v114
	v_mul_f32_e32 v115, v115, v115
	v_max_f32_e32 v117, 0, v117
	v_mul_f32_e32 v116, v116, v116
	v_max_f32_e32 v106, v106, v106
	v_mul_f32_e32 v118, v118, v118
	v_mul_f32_e32 v117, v117, v117
	v_cvt_pk_bf16_f32 v114, v118, v114
	v_cvt_pk_bf16_f32 v115, v115, v116
	v_cvt_pk_bf16_f32 v116, v122, v119
	v_max_f32_e32 v106, 0, v106
	v_max_f32_e32 v107, v107, v107
	v_max_f32_e32 v108, v108, v108
	v_cvt_pk_bf16_f32 v117, v120, v117
	flat_store_dwordx4 v[146:147], v[114:117] offset:256 nt
	v_max_f32_e32 v110, v110, v110
	v_max_f32_e32 v107, 0, v107
	v_mul_f32_e32 v116, v106, v106
	v_max_f32_e32 v106, v111, v111
	v_max_f32_e32 v108, 0, v108
	v_max_f32_e32 v110, 0, v110
	v_max_f32_e32 v106, 0, v106
	v_mul_f32_e32 v111, v107, v107
	v_max_f32_e32 v107, v112, v112
	v_mul_f32_e32 v112, v108, v108
	v_max_f32_e32 v108, v113, v113
	v_mul_f32_e32 v110, v110, v110
	v_mul_f32_e32 v106, v106, v106
	v_max_f32_e32 v107, 0, v107
	v_max_f32_e32 v108, 0, v108
	v_max_f32_e32 v109, v109, v109
	v_mul_f32_e32 v107, v107, v107
	v_max_f32_e32 v109, 0, v109
	v_mul_f32_e32 v108, v108, v108
	v_cvt_pk_bf16_f32 v106, v110, v106
	v_add_co_u32_e32 v110, vcc, s60, v146
	v_max_f32_e32 v98, v98, v98
	v_mul_f32_e32 v109, v109, v109
	v_cvt_pk_bf16_f32 v107, v107, v108
	v_cvt_pk_bf16_f32 v108, v116, v111
	v_addc_co_u32_e32 v111, vcc, 0, v147, vcc
	v_max_f32_e32 v98, 0, v98
	v_max_f32_e32 v99, v99, v99
	v_max_f32_e32 v100, v100, v100
	v_cvt_pk_bf16_f32 v109, v112, v109
	flat_store_dwordx4 v[110:111], v[106:109] nt
	v_max_f32_e32 v99, 0, v99
	v_max_f32_e32 v100, 0, v100
	v_mul_f32_e32 v106, v98, v98
	v_max_f32_e32 v98, v103, v103
	v_max_f32_e32 v102, v102, v102
	v_max_f32_e32 v98, 0, v98
	v_mul_f32_e32 v103, v99, v99
	v_max_f32_e32 v99, v104, v104
	v_mul_f32_e32 v104, v100, v100
	v_max_f32_e32 v100, v105, v105
	v_max_f32_e32 v101, v101, v101
	v_max_f32_e32 v102, 0, v102
	v_mul_f32_e32 v98, v98, v98
	v_max_f32_e32 v99, 0, v99
	v_max_f32_e32 v100, 0, v100
	v_max_f32_e32 v101, 0, v101
	v_lshl_add_u64 v[114:115], v[146:147], 0, s[18:19]
	v_mul_f32_e32 v102, v102, v102
	v_mul_f32_e32 v99, v99, v99
	v_mul_f32_e32 v100, v100, v100
	v_mul_f32_e32 v101, v101, v101
	v_cvt_pk_bf16_f32 v98, v102, v98
	v_max_f32_e32 v90, v90, v90
	v_cvt_pk_bf16_f32 v99, v99, v100
	v_cvt_pk_bf16_f32 v100, v106, v103
	v_cvt_pk_bf16_f32 v101, v104, v101
	flat_store_dwordx4 v[114:115], v[98:101] offset:256 nt
	v_max_f32_e32 v90, 0, v90
	v_max_f32_e32 v91, v91, v91
	v_or_b32_e32 v98, 32, v154
	v_max_f32_e32 v92, v92, v92
	v_ashrrev_i32_e32 v99, 31, v98
	v_mul_f32_e32 v100, v90, v90
	v_max_f32_e32 v90, v95, v95
	v_max_f32_e32 v91, 0, v91
	v_max_f32_e32 v92, 0, v92
	v_lshlrev_b64 v[98:99], 14, v[98:99]
	v_max_f32_e32 v94, v94, v94
	v_max_f32_e32 v90, 0, v90
	v_mul_f32_e32 v95, v91, v91
	v_max_f32_e32 v91, v96, v96
	v_mul_f32_e32 v96, v92, v92
	v_max_f32_e32 v92, v97, v97
	v_max_f32_e32 v93, v93, v93
	v_lshl_add_u64 v[98:99], s[10:11], 0, v[98:99]
	v_max_f32_e32 v94, 0, v94
	v_mul_f32_e32 v90, v90, v90
	v_max_f32_e32 v91, 0, v91
	v_max_f32_e32 v92, 0, v92
	v_max_f32_e32 v93, 0, v93
	v_max_f32_e32 v82, v82, v82
	v_max_f32_e32 v83, v83, v83
	v_max_f32_e32 v84, v84, v84
	v_lshl_add_u64 v[98:99], v[98:99], 0, v[158:159]
	v_mul_f32_e32 v94, v94, v94
	v_mul_f32_e32 v91, v91, v91
	v_mul_f32_e32 v92, v92, v92
	v_mul_f32_e32 v93, v93, v93
	v_cvt_pk_bf16_f32 v90, v94, v90
	v_max_f32_e32 v82, 0, v82
	v_max_f32_e32 v83, 0, v83
	v_max_f32_e32 v84, 0, v84
	v_cvt_pk_bf16_f32 v91, v91, v92
	v_cvt_pk_bf16_f32 v92, v100, v95
	v_cvt_pk_bf16_f32 v93, v96, v93
	flat_store_dwordx4 v[98:99], v[90:93] nt
	v_max_f32_e32 v86, v86, v86
	v_max_f32_e32 v85, v85, v85
	v_mul_f32_e32 v90, v82, v82
	v_max_f32_e32 v82, v87, v87
	v_mul_f32_e32 v87, v83, v83
	v_max_f32_e32 v83, v88, v88
	v_mul_f32_e32 v88, v84, v84
	v_max_f32_e32 v84, v89, v89
; __device__ __forceinline__ unsigned cvt_pk_bf16(float lo, float hi) { unsigned r; asm volatile("v_cvt_pk_bf16_f32 %0, %1, %2" : "=v"(r) : "v"(lo), "v"(hi)); return r; }
;     __device__ __forceinline__ void operator()(const pg8::f32x4 (&acc)[2][2][4][2], const pg8::Unit& u, int wr, int wc, int fr, int fq) const {
;         const int row0 = NMETA + u.pm * 256 + wr * 64 + fr, col0 = u.pn * 256 + wc * 32 + 8 * fq;
; #pragma unroll
;         for (int ai = 0; ai < 2; ++ai)
; #pragma unroll
;             for (int m = 0; m < 4; ++m) { bf16_t* rowp = O + (size_t)(row0 + ai * 128 + m * 16) * DFF + col0;
; #pragma unroll
;                 for (int bj = 0; bj < 2; ++bj) { pg8::f32x4 v0 = acc[ai][bj][m][0], v1 = acc[ai][bj][m][1];
; #pragma unroll
;                     for (int i = 0; i < 4; ++i) { const float a = fmaxf(v0[i], 0.f), b = fmaxf(v1[i], 0.f); v0[i] = a * a; v1[i] = b * b; }
;                     u32x4 w; w.x = cvt_pk_bf16(v0[0], v0[1]); w.y = cvt_pk_bf16(v0[2], v0[3]); w.z = cvt_pk_bf16(v1[0], v1[1]); w.w = cvt_pk_bf16(v1[2], v1[3]);
;                     *(u32x4*)(rowp + bj * 128) = w; } }
	v_max_f32_e32 v82, 0, v82
	v_max_f32_e32 v83, 0, v83
	v_max_f32_e32 v84, 0, v84
	v_max_f32_e32 v86, 0, v86
	v_mul_f32_e32 v82, v82, v82
	v_mul_f32_e32 v83, v83, v83
	v_max_f32_e32 v85, 0, v85
	v_mul_f32_e32 v84, v84, v84
	v_max_f32_e32 v74, v74, v74
	v_mul_f32_e32 v86, v86, v86
	v_mul_f32_e32 v85, v85, v85
	v_cvt_pk_bf16_f32 v82, v86, v82
	v_cvt_pk_bf16_f32 v83, v83, v84
	v_cvt_pk_bf16_f32 v84, v90, v87
	v_max_f32_e32 v74, 0, v74
	v_max_f32_e32 v75, v75, v75
	v_max_f32_e32 v76, v76, v76
	v_cvt_pk_bf16_f32 v85, v88, v85
	flat_store_dwordx4 v[98:99], v[82:85] offset:256 nt
	v_max_f32_e32 v78, v78, v78
	v_max_f32_e32 v75, 0, v75
	v_mul_f32_e32 v84, v74, v74
	v_max_f32_e32 v74, v79, v79
	v_max_f32_e32 v76, 0, v76
	v_max_f32_e32 v78, 0, v78
	v_max_f32_e32 v74, 0, v74
	v_mul_f32_e32 v79, v75, v75
	v_max_f32_e32 v75, v80, v80
	v_mul_f32_e32 v80, v76, v76
	v_max_f32_e32 v76, v81, v81
	v_mul_f32_e32 v78, v78, v78
	v_mul_f32_e32 v74, v74, v74
	v_max_f32_e32 v75, 0, v75
	v_max_f32_e32 v76, 0, v76
	v_max_f32_e32 v77, v77, v77
	v_mul_f32_e32 v75, v75, v75
	v_max_f32_e32 v77, 0, v77
	v_mul_f32_e32 v76, v76, v76
	v_cvt_pk_bf16_f32 v74, v78, v74
	v_add_co_u32_e32 v78, vcc, s61, v146
	v_max_f32_e32 v66, v66, v66
	v_max_f32_e32 v67, v67, v67
	v_max_f32_e32 v68, v68, v68
	v_mul_f32_e32 v77, v77, v77
	v_cvt_pk_bf16_f32 v75, v75, v76
	v_cvt_pk_bf16_f32 v76, v84, v79
	v_addc_co_u32_e32 v79, vcc, 0, v147, vcc
	v_max_f32_e32 v66, 0, v66
	v_max_f32_e32 v67, 0, v67
	v_max_f32_e32 v68, 0, v68
	v_cvt_pk_bf16_f32 v77, v80, v77
	flat_store_dwordx4 v[78:79], v[74:77] nt
	v_max_f32_e32 v70, v70, v70
	v_max_f32_e32 v69, v69, v69
	v_mul_f32_e32 v74, v66, v66
	v_max_f32_e32 v66, v71, v71
	v_mul_f32_e32 v71, v67, v67
	v_max_f32_e32 v67, v72, v72
	v_mul_f32_e32 v72, v68, v68
	v_max_f32_e32 v68, v73, v73
	v_max_f32_e32 v66, 0, v66
	v_max_f32_e32 v67, 0, v67
	v_max_f32_e32 v68, 0, v68
	v_max_f32_e32 v70, 0, v70
	v_mul_f32_e32 v66, v66, v66
	v_mul_f32_e32 v67, v67, v67
	v_max_f32_e32 v69, 0, v69
	v_mul_f32_e32 v68, v68, v68
	v_max_f32_e32 v58, v58, v58
	v_lshl_add_u64 v[82:83], v[146:147], 0, s[20:21]
	v_mul_f32_e32 v70, v70, v70
	v_mul_f32_e32 v69, v69, v69
	v_cvt_pk_bf16_f32 v66, v70, v66
	v_cvt_pk_bf16_f32 v67, v67, v68
	v_cvt_pk_bf16_f32 v68, v74, v71
	v_max_f32_e32 v58, 0, v58
	v_max_f32_e32 v59, v59, v59
	v_max_f32_e32 v60, v60, v60
	v_cvt_pk_bf16_f32 v69, v72, v69
	flat_store_dwordx4 v[82:83], v[66:69] offset:256 nt
	v_max_f32_e32 v62, v62, v62
	v_max_f32_e32 v59, 0, v59
	v_mul_f32_e32 v68, v58, v58
	v_max_f32_e32 v58, v63, v63
	v_max_f32_e32 v60, 0, v60
	v_max_f32_e32 v62, 0, v62
	v_max_f32_e32 v58, 0, v58
	v_mul_f32_e32 v63, v59, v59
	v_max_f32_e32 v59, v64, v64
	v_mul_f32_e32 v64, v60, v60
	v_max_f32_e32 v60, v65, v65
	v_mul_f32_e32 v62, v62, v62
	v_mul_f32_e32 v58, v58, v58
	v_max_f32_e32 v59, 0, v59
	v_max_f32_e32 v60, 0, v60
	v_max_f32_e32 v61, v61, v61
	v_mul_f32_e32 v59, v59, v59
	v_max_f32_e32 v61, 0, v61
	v_mul_f32_e32 v60, v60, v60
	v_cvt_pk_bf16_f32 v58, v62, v58
	v_add_co_u32_e32 v62, vcc, s62, v146
	v_max_f32_e32 v50, v50, v50
	v_max_f32_e32 v51, v51, v51
	v_max_f32_e32 v52, v52, v52
	v_mul_f32_e32 v61, v61, v61
	v_cvt_pk_bf16_f32 v59, v59, v60
	v_cvt_pk_bf16_f32 v60, v68, v63
	v_addc_co_u32_e32 v63, vcc, 0, v147, vcc
	v_max_f32_e32 v50, 0, v50
	v_max_f32_e32 v51, 0, v51
	v_max_f32_e32 v52, 0, v52
	v_cvt_pk_bf16_f32 v61, v64, v61
	flat_store_dwordx4 v[62:63], v[58:61] nt
	v_max_f32_e32 v54, v54, v54
	v_max_f32_e32 v53, v53, v53
	v_mul_f32_e32 v58, v50, v50
	v_max_f32_e32 v50, v55, v55
	v_mul_f32_e32 v55, v51, v51
	v_max_f32_e32 v51, v56, v56
	v_mul_f32_e32 v56, v52, v52
	v_max_f32_e32 v52, v57, v57
	v_max_f32_e32 v50, 0, v50
	v_max_f32_e32 v51, 0, v51
	v_max_f32_e32 v52, 0, v52
	v_max_f32_e32 v54, 0, v54
	v_mul_f32_e32 v50, v50, v50
	v_mul_f32_e32 v51, v51, v51
	v_max_f32_e32 v53, 0, v53
	v_mul_f32_e32 v52, v52, v52
	v_max_f32_e32 v42, v42, v42
	v_lshl_add_u64 v[66:67], v[146:147], 0, s[22:23]
	v_mul_f32_e32 v54, v54, v54
	v_mul_f32_e32 v53, v53, v53
	v_cvt_pk_bf16_f32 v50, v54, v50
	v_cvt_pk_bf16_f32 v51, v51, v52
	v_cvt_pk_bf16_f32 v52, v58, v55
	v_max_f32_e32 v42, 0, v42
	v_max_f32_e32 v43, v43, v43
	v_max_f32_e32 v44, v44, v44
	v_cvt_pk_bf16_f32 v53, v56, v53
	flat_store_dwordx4 v[66:67], v[50:53] offset:256 nt
	v_max_f32_e32 v46, v46, v46
	v_max_f32_e32 v43, 0, v43
	v_mul_f32_e32 v52, v42, v42
	v_max_f32_e32 v42, v47, v47
	v_max_f32_e32 v44, 0, v44
	v_max_f32_e32 v46, 0, v46
	v_max_f32_e32 v42, 0, v42
	v_mul_f32_e32 v47, v43, v43
	v_max_f32_e32 v43, v48, v48
	v_mul_f32_e32 v48, v44, v44
	v_max_f32_e32 v44, v49, v49
	v_mul_f32_e32 v46, v46, v46
	v_mul_f32_e32 v42, v42, v42
	v_max_f32_e32 v43, 0, v43
	v_max_f32_e32 v44, 0, v44
	v_max_f32_e32 v45, v45, v45
	v_mul_f32_e32 v43, v43, v43
	v_max_f32_e32 v45, 0, v45
	v_mul_f32_e32 v44, v44, v44
	v_cvt_pk_bf16_f32 v42, v46, v42
	v_add_co_u32_e32 v46, vcc, s63, v146
	v_max_f32_e32 v34, v34, v34
; __device__ __forceinline__ unsigned cvt_pk_bf16(float lo, float hi) { unsigned r; asm volatile("v_cvt_pk_bf16_f32 %0, %1, %2" : "=v"(r) : "v"(lo), "v"(hi)); return r; }
;     __device__ __forceinline__ void operator()(const pg8::f32x4 (&acc)[2][2][4][2], const pg8::Unit& u, int wr, int wc, int fr, int fq) const {
;         const int row0 = NMETA + u.pm * 256 + wr * 64 + fr, col0 = u.pn * 256 + wc * 32 + 8 * fq;
; #pragma unroll
;         for (int ai = 0; ai < 2; ++ai)
; #pragma unroll
;             for (int m = 0; m < 4; ++m) { bf16_t* rowp = O + (size_t)(row0 + ai * 128 + m * 16) * DFF + col0;
; #pragma unroll
;                 for (int bj = 0; bj < 2; ++bj) { pg8::f32x4 v0 = acc[ai][bj][m][0], v1 = acc[ai][bj][m][1];
; #pragma unroll
;                     for (int i = 0; i < 4; ++i) { const float a = fmaxf(v0[i], 0.f), b = fmaxf(v1[i], 0.f); v0[i] = a * a; v1[i] = b * b; }
;                     u32x4 w; w.x = cvt_pk_bf16(v0[0], v0[1]); w.y = cvt_pk_bf16(v0[2], v0[3]); w.z = cvt_pk_bf16(v1[0], v1[1]); w.w = cvt_pk_bf16(v1[2], v1[3]);
;                     *(u32x4*)(rowp + bj * 128) = w; } }
	v_max_f32_e32 v35, v35, v35
	v_max_f32_e32 v36, v36, v36
	v_mul_f32_e32 v45, v45, v45
	v_cvt_pk_bf16_f32 v43, v43, v44
	v_cvt_pk_bf16_f32 v44, v52, v47
	v_addc_co_u32_e32 v47, vcc, 0, v147, vcc
	v_max_f32_e32 v34, 0, v34
	v_max_f32_e32 v35, 0, v35
	v_max_f32_e32 v36, 0, v36
	v_cvt_pk_bf16_f32 v45, v48, v45
	flat_store_dwordx4 v[46:47], v[42:45] nt
	v_max_f32_e32 v38, v38, v38
	v_max_f32_e32 v37, v37, v37
	v_mul_f32_e32 v42, v34, v34
	v_max_f32_e32 v34, v39, v39
	v_mul_f32_e32 v39, v35, v35
	v_max_f32_e32 v35, v40, v40
	v_mul_f32_e32 v40, v36, v36
	v_max_f32_e32 v36, v41, v41
	v_max_f32_e32 v34, 0, v34
	v_max_f32_e32 v35, 0, v35
	v_max_f32_e32 v36, 0, v36
	v_max_f32_e32 v38, 0, v38
	v_mul_f32_e32 v34, v34, v34
	v_mul_f32_e32 v35, v35, v35
	v_max_f32_e32 v37, 0, v37
	v_mul_f32_e32 v36, v36, v36
	v_max_f32_e32 v26, v26, v26
	v_lshl_add_u64 v[50:51], v[146:147], 0, s[24:25]
	v_mul_f32_e32 v38, v38, v38
	v_mul_f32_e32 v37, v37, v37
	v_cvt_pk_bf16_f32 v34, v38, v34
	v_cvt_pk_bf16_f32 v35, v35, v36
	v_cvt_pk_bf16_f32 v36, v42, v39
	v_max_f32_e32 v26, 0, v26
	v_max_f32_e32 v27, v27, v27
	v_max_f32_e32 v28, v28, v28
	v_cvt_pk_bf16_f32 v37, v40, v37
	flat_store_dwordx4 v[50:51], v[34:37] offset:256 nt
	v_max_f32_e32 v30, v30, v30
	v_max_f32_e32 v27, 0, v27
	v_mul_f32_e32 v36, v26, v26
	v_max_f32_e32 v26, v31, v31
	v_max_f32_e32 v28, 0, v28
	v_max_f32_e32 v30, 0, v30
	v_max_f32_e32 v26, 0, v26
	v_mul_f32_e32 v31, v27, v27
	v_max_f32_e32 v27, v32, v32
	v_mul_f32_e32 v32, v28, v28
	v_max_f32_e32 v28, v33, v33
	v_mul_f32_e32 v30, v30, v30
	v_mul_f32_e32 v26, v26, v26
	v_max_f32_e32 v27, 0, v27
	v_max_f32_e32 v28, 0, v28
	v_max_f32_e32 v29, v29, v29
	v_mul_f32_e32 v27, v27, v27
	v_max_f32_e32 v29, 0, v29
	v_mul_f32_e32 v28, v28, v28
	v_cvt_pk_bf16_f32 v26, v30, v26
	v_add_co_u32_e32 v30, vcc, s64, v146
	v_max_f32_e32 v18, v18, v18
	v_max_f32_e32 v19, v19, v19
	v_max_f32_e32 v20, v20, v20
	v_mul_f32_e32 v29, v29, v29
	v_cvt_pk_bf16_f32 v27, v27, v28
	v_cvt_pk_bf16_f32 v28, v36, v31
	v_addc_co_u32_e32 v31, vcc, 0, v147, vcc
	v_max_f32_e32 v18, 0, v18
	v_max_f32_e32 v19, 0, v19
	v_max_f32_e32 v20, 0, v20
	v_cvt_pk_bf16_f32 v29, v32, v29
	flat_store_dwordx4 v[30:31], v[26:29] nt
	v_max_f32_e32 v22, v22, v22
	v_max_f32_e32 v21, v21, v21
	v_mul_f32_e32 v26, v18, v18
	v_max_f32_e32 v18, v23, v23
	v_mul_f32_e32 v23, v19, v19
	v_max_f32_e32 v19, v24, v24
	v_mul_f32_e32 v24, v20, v20
	v_max_f32_e32 v20, v25, v25
	v_max_f32_e32 v18, 0, v18
	v_max_f32_e32 v19, 0, v19
	v_max_f32_e32 v20, 0, v20
	v_max_f32_e32 v22, 0, v22
	v_mul_f32_e32 v18, v18, v18
	v_mul_f32_e32 v19, v19, v19
	v_max_f32_e32 v21, 0, v21
	v_mul_f32_e32 v20, v20, v20
	v_max_f32_e32 v10, v10, v10
	v_lshl_add_u64 v[34:35], v[146:147], 0, s[26:27]
	v_mul_f32_e32 v22, v22, v22
	v_mul_f32_e32 v21, v21, v21
	v_cvt_pk_bf16_f32 v18, v22, v18
	v_cvt_pk_bf16_f32 v19, v19, v20
	v_cvt_pk_bf16_f32 v20, v26, v23
	v_max_f32_e32 v10, 0, v10
	v_max_f32_e32 v11, v11, v11
	v_max_f32_e32 v12, v12, v12
	v_cvt_pk_bf16_f32 v21, v24, v21
	flat_store_dwordx4 v[34:35], v[18:21] offset:256 nt
	v_max_f32_e32 v14, v14, v14
	v_max_f32_e32 v11, 0, v11
	v_mul_f32_e32 v20, v10, v10
	v_max_f32_e32 v10, v15, v15
	v_max_f32_e32 v12, 0, v12
	v_max_f32_e32 v14, 0, v14
	v_max_f32_e32 v10, 0, v10
	v_mul_f32_e32 v15, v11, v11
	v_max_f32_e32 v11, v16, v16
	v_mul_f32_e32 v16, v12, v12
	v_max_f32_e32 v12, v17, v17
	v_mul_f32_e32 v14, v14, v14
	v_mul_f32_e32 v10, v10, v10
	v_max_f32_e32 v11, 0, v11
	v_max_f32_e32 v12, 0, v12
	v_max_f32_e32 v13, v13, v13
	v_mul_f32_e32 v11, v11, v11
	v_max_f32_e32 v13, 0, v13
	v_mul_f32_e32 v12, v12, v12
	v_cvt_pk_bf16_f32 v10, v14, v10
	v_add_co_u32_e32 v14, vcc, s65, v146
	v_max_f32_e32 v2, v2, v2
	v_max_f32_e32 v3, v3, v3
	v_max_f32_e32 v4, v4, v4
	v_mul_f32_e32 v13, v13, v13
	v_cvt_pk_bf16_f32 v11, v11, v12
	v_cvt_pk_bf16_f32 v12, v20, v15
	v_addc_co_u32_e32 v15, vcc, 0, v147, vcc
	v_max_f32_e32 v2, 0, v2
	v_max_f32_e32 v3, 0, v3
	v_max_f32_e32 v4, 0, v4
	v_cvt_pk_bf16_f32 v13, v16, v13
	flat_store_dwordx4 v[14:15], v[10:13] nt
	v_max_f32_e32 v5, v5, v5
	v_max_f32_e32 v6, v6, v6
	v_mul_f32_e32 v10, v2, v2
	v_max_f32_e32 v2, v7, v7
	v_mul_f32_e32 v7, v3, v3
	v_max_f32_e32 v3, v8, v8
	v_mul_f32_e32 v8, v4, v4
	v_max_f32_e32 v4, v9, v9
	v_max_f32_e32 v2, 0, v2
	v_max_f32_e32 v3, 0, v3
	v_max_f32_e32 v4, 0, v4
	v_max_f32_e32 v5, 0, v5
	v_lshl_add_u64 v[18:19], v[146:147], 0, s[28:29]
	v_max_f32_e32 v6, 0, v6
	v_mul_f32_e32 v2, v2, v2
	v_mul_f32_e32 v3, v3, v3
	v_mul_f32_e32 v4, v4, v4
	v_mul_f32_e32 v5, v5, v5
	s_andn2_b64 vcc, exec, s[6:7]
	s_mov_b64 s[6:7], -1
	v_mul_f32_e32 v6, v6, v6
	v_cvt_pk_bf16_f32 v2, v6, v2
	v_cvt_pk_bf16_f32 v3, v3, v4
	v_cvt_pk_bf16_f32 v4, v10, v7
	v_cvt_pk_bf16_f32 v5, v8, v5
	flat_store_dwordx4 v[18:19], v[2:5] offset:256 nt
	s_cbranch_vccnz .LBB0_1282
	s_andn2_b64 vcc, exec, s[12:13]
	s_cbranch_vccnz .LBB0_1281
	s_barrier
	s_branch .LBB0_1281

; __device__ __forceinline__ float bflo(unsigned w) { return __uint_as_float(w << 16); }
; __device__ __forceinline__ float bfhi(unsigned w) { return __uint_as_float(w & 0xffff0000u); }
; #define PACK_CARRY() (u32x4){cvt_pk_bf16(c0, c1), cvt_pk_bf16(c2, c3), cvt_pk_bf16(c4, c5), cvt_pk_bf16(c6, c7)}
; __device__ __forceinline__ void mlstm_scan_item(const Params& P, int item) {
;     ...
;         for (int j = 0; j < 16; ++j) { const int n = n0 + j; const float g = GM[n * 2], ml = GM[n * 2 + 1];
;             *(u32x4*)(p + (size_t)n * 32768) = PACK_CARRY();
;             if (hasn) np[(size_t)n * 128] = ncar;
;             if (wm) MPREV[n] = m;
;             const float mn = fmaxf(g + m, ml), sp = __expf(g + m - mn), sq = __expf(ml - mn);
;             c0 = sp * c0 + sq * bflo(cl[j].x); c1 = sp * c1 + sq * bfhi(cl[j].x); c2 = sp * c2 + sq * bflo(cl[j].y); c3 = sp * c3 + sq * bfhi(cl[j].y);
;             c4 = sp * c4 + sq * bflo(cl[j].z); c5 = sp * c5 + sq * bfhi(cl[j].z); c6 = sp * c6 + sq * bflo(cl[j].w); c7 = sp * c7 + sq * bfhi(cl[j].w);
;             ncar = sp * ncar + sq * nl[j]; m = mn; }
.LBB0_2090:
	s_or_b64 exec, exec, s[18:19]
	v_add_co_u32_e32 v16, vcc, 0x60000, v84
	v_add_f32_e32 v15, v42, v26
	v_addc_co_u32_e32 v17, vcc, 0, v85, vcc
	v_mov_b32_e32 v18, v240
	v_mov_b32_e32 v19, v241
	v_max_f32_e32 v16, v27, v27
	v_max_f32_e32 v40, v15, v16
	v_sub_f32_e32 v16, v27, v40
	v_sub_f32_e32 v15, v15, v40
	v_mul_f32_e32 v16, 0x3fb8aa3b, v16
	v_mul_f32_e32 v15, 0x3fb8aa3b, v15
	v_exp_f32_e32 v21, v16
	v_exp_f32_e32 v42, v15
	v_lshlrev_b32_e32 v43, 16, v10
	s_mov_b64 s[18:19], 0x1aee0000
	v_mul_f32_e32 v16, v21, v43
	v_pk_fma_f32 v[16:17], v[20:21], v[42:43], v[16:17] op_sel_hi:[1,1,0]
	v_and_b32_e32 v43, 0xffff0000, v10
	v_mov_b32_e32 v39, v21
	v_mul_f32_e32 v10, v21, v43
	v_pk_fma_f32 v[38:39], v[38:39], v[42:43], v[10:11] op_sel_hi:[1,1,0]
	v_lshlrev_b32_e32 v43, 16, v11
	v_mov_b32_e32 v37, v21
	v_mul_f32_e32 v10, v21, v43
	v_pk_fma_f32 v[28:29], v[36:37], v[42:43], v[10:11] op_sel_hi:[1,1,0]
	v_and_b32_e32 v43, 0xffff0000, v11
	v_mov_b32_e32 v35, v21
	v_mul_f32_e32 v10, v21, v43
	v_pk_fma_f32 v[34:35], v[34:35], v[42:43], v[10:11] op_sel_hi:[1,1,0]
	v_lshlrev_b32_e32 v43, 16, v12
	v_mov_b32_e32 v33, v21
	v_mul_f32_e32 v10, v21, v43
	v_pk_fma_f32 v[22:23], v[32:33], v[42:43], v[10:11] op_sel_hi:[1,1,0]
	v_and_b32_e32 v43, 0xffff0000, v12
	v_mov_b32_e32 v31, v21
	v_mul_f32_e32 v10, v21, v43
	v_pk_fma_f32 v[26:27], v[30:31], v[42:43], v[10:11] op_sel_hi:[1,1,0]
	v_lshlrev_b32_e32 v43, 16, v13
	v_mov_b32_e32 v25, v21
	v_mul_f32_e32 v10, v21, v43
	v_pk_fma_f32 v[10:11], v[24:25], v[42:43], v[10:11] op_sel_hi:[1,1,0]
	v_and_b32_e32 v43, 0xffff0000, v13
	v_mov_b32_e32 v15, v21
	v_mul_f32_e32 v12, v21, v43
	v_mul_f32_e32 v24, v104, v21
	v_lshl_add_u64 v[44:45], v[76:77], 0, s[18:19]
	v_pk_fma_f32 v[12:13], v[14:15], v[42:43], v[12:13] op_sel_hi:[1,1,0]
	v_fmac_f32_e32 v24, v41, v42
	v_cvt_pk_bf16_f32 v30, v16, v38
	v_cvt_pk_bf16_f32 v31, v28, v34
	v_cvt_pk_bf16_f32 v32, v22, v26
	v_cvt_pk_bf16_f32 v33, v10, v12
	flat_store_dwordx4 v[44:45], v[30:33]
	s_and_saveexec_b64 s[18:19], s[14:15]
	s_cbranch_execz .LBB0_2092
	v_add_co_u32_e32 v14, vcc, 0x101000, v80
	s_nop 1
	v_addc_co_u32_e32 v15, vcc, 0, v81, vcc
	flat_store_dword v[14:15], v24 offset:3072

; __device__ __forceinline__ float bflo(unsigned w) { return __uint_as_float(w << 16); }
; __device__ __forceinline__ float bfhi(unsigned w) { return __uint_as_float(w & 0xffff0000u); }
; #define PACK_CARRY() (u32x4){cvt_pk_bf16(c0, c1), cvt_pk_bf16(c2, c3), cvt_pk_bf16(c4, c5), cvt_pk_bf16(c6, c7)}
; __device__ __forceinline__ void mlstm_scan_item(const Params& P, int item) {
;     ...
;         for (int j = 0; j < 16; ++j) { const int n = n0 + j; const float g = GM[n * 2], ml = GM[n * 2 + 1];
;             *(u32x4*)(p + (size_t)n * 32768) = PACK_CARRY();
;             if (hasn) np[(size_t)n * 128] = ncar;
;             if (wm) MPREV[n] = m;
;             const float mn = fmaxf(g + m, ml), sp = __expf(g + m - mn), sq = __expf(ml - mn);
;             c0 = sp * c0 + sq * bflo(cl[j].x); c1 = sp * c1 + sq * bfhi(cl[j].x); c2 = sp * c2 + sq * bflo(cl[j].y); c3 = sp * c3 + sq * bfhi(cl[j].y);
;             c4 = sp * c4 + sq * bflo(cl[j].z); c5 = sp * c5 + sq * bfhi(cl[j].z); c6 = sp * c6 + sq * bflo(cl[j].w); c7 = sp * c7 + sq * bfhi(cl[j].w);
;             ncar = sp * ncar + sq * nl[j]; m = mn; }
.LBB0_2094:
	s_or_b64 exec, exec, s[18:19]
	v_mov_b32_e32 v14, v242
	v_mov_b32_e32 v15, v243
	v_add_f32_e32 v11, v40, v18
	v_max_f32_e32 v13, v19, v19
	v_max_f32_e32 v25, v11, v13
	v_sub_f32_e32 v11, v11, v25
	v_mul_f32_e32 v11, 0x3fb8aa3b, v11
	v_exp_f32_e32 v30, v11
	v_sub_f32_e32 v11, v19, v25
	v_mul_f32_e32 v11, 0x3fb8aa3b, v11
	v_exp_f32_e32 v17, v11
	v_lshlrev_b32_e32 v31, 16, v6
	v_lshl_add_u64 v[32:33], v[76:77], 0, s[52:53]
	v_pk_mul_f32 v[18:19], v[16:17], v[30:31]
	v_and_b32_e32 v31, 0xffff0000, v6
	v_mov_b32_e32 v39, v17
	v_pk_mul_f32 v[20:21], v[38:39], v[30:31]
	v_mov_b32_e32 v36, v18
	v_mov_b32_e32 v37, v20
	v_mov_b32_e32 v20, v19
	v_lshlrev_b32_e32 v31, 16, v7
	v_mov_b32_e32 v29, v17
	v_pk_add_f32 v[18:19], v[36:37], v[20:21]
	v_pk_mul_f32 v[20:21], v[28:29], v[30:31]
	v_and_b32_e32 v31, 0xffff0000, v7
	v_mov_b32_e32 v35, v17
	v_pk_mul_f32 v[6:7], v[34:35], v[30:31]
	v_lshlrev_b32_e32 v31, 16, v8
	v_mov_b32_e32 v23, v17
	v_mov_b32_e32 v28, v20
	v_mov_b32_e32 v29, v6
	v_mov_b32_e32 v6, v21
	v_pk_mul_f32 v[20:21], v[22:23], v[30:31]
	v_and_b32_e32 v31, 0xffff0000, v8
	v_mov_b32_e32 v27, v17
	v_pk_mul_f32 v[22:23], v[26:27], v[30:31]
	v_lshlrev_b32_e32 v31, 16, v9
	v_mov_b32_e32 v11, v17
	v_pk_mul_f32 v[10:11], v[10:11], v[30:31]
	v_and_b32_e32 v31, 0xffff0000, v9
	v_mov_b32_e32 v13, v17
	v_pk_mul_f32 v[8:9], v[12:13], v[30:31]
	v_mov_b32_e32 v26, v20
	v_mov_b32_e32 v27, v22
	v_mov_b32_e32 v22, v21
	v_mov_b32_e32 v12, v10
	v_mov_b32_e32 v13, v8
	v_mov_b32_e32 v8, v11
	v_mul_f32_e32 v78, v78, v17
	v_pk_add_f32 v[6:7], v[28:29], v[6:7]
	v_pk_add_f32 v[20:21], v[26:27], v[22:23]
	v_pk_add_f32 v[8:9], v[12:13], v[8:9]
	v_fmac_f32_e32 v78, v24, v30
	v_cvt_pk_bf16_f32 v10, v18, v19
	v_cvt_pk_bf16_f32 v11, v6, v7
	v_cvt_pk_bf16_f32 v12, v20, v21
	v_cvt_pk_bf16_f32 v13, v8, v9
	flat_store_dwordx4 v[32:33], v[10:13]
	s_and_saveexec_b64 s[18:19], s[14:15]
	s_cbranch_execz .LBB0_2096
	v_add_co_u32_e32 v10, vcc, 0x101000, v80
	s_nop 1
	v_addc_co_u32_e32 v11, vcc, 0, v81, vcc
	flat_store_dword v[10:11], v78 offset:3584

; __device__ __forceinline__ int crow(int r, int hi) { return (r & 3) + 8 * (r >> 2) + 4 * hi; }
; __device__ __forceinline__ int tsw(int row, int t) { return ((((t >> 1) + 4 * ((row >> 3) & 7)) & 31) << 1) | (t & 1); }
; __device__ __forceinline__ void mlstm_out_unit(const Params& P, int l, int h, int n, char* lds) {
;     ...
;     f32x16 a1[2] = {}, a2[2] = {};
; #pragma unroll
;     for (int ks = 0; ks < 4; ++ks) { const bf16x8 B = *(const bf16x8*)(VT + (32 * wid + r32) * 72 + tsw(32 * wid + r32, 16 * ks + 8 * hi));
; #pragma unroll
;         for (int ti = 0; ti < 2; ++ti) { const bf16x8 A = *(const bf16x8*)(Wl + (32 * ti + r32) * 72 + 16 * ks + 8 * hi);
;             a1[ti] = __builtin_amdgcn_mfma_f32_32x32x16_bf16(A, B, a1[ti], 0, 0, 0); } }
; #pragma unroll
;     for (int ks = 0; ks < 8; ++ks) {
; #pragma unroll
;         for (int ti = 0; ti < 2; ++ti) { const bf16x8 A = *(const bf16x8*)(Ql + (32 * ti + r32) * 136 + 16 * ks + 8 * hi);
;             a2[ti] = __builtin_amdgcn_mfma_f32_32x32x16_bf16(A, cfr[ks], a2[ti], 0, 0, 0); } }
;     __syncthreads();
; #pragma unroll
;     for (int ti = 0; ti < 2; ++ti)
; #pragma unroll
;         for (int r = 0; r < 16; ++r) { const int t = 32 * ti + fox::crow(r, hi);
;             Hb[t * 260 + 32 * wid + r32] = (a1[ti][r] + sil[t] * a2[ti][r]) * rden[t]; }
.LBB0_2398:
	s_or_b64 exec, exec, s[6:7]
	v_mul_lo_u32 v2, v18, s56
	v_add_u32_e32 v20, 0x100, v2
	v_lshlrev_b32_e32 v2, 1, v19
	v_mul_u32_u24_e32 v3, 0x90, v22
	v_add3_u32 v23, s58, v2, v3
	s_waitcnt lgkmcnt(0)
	ds_read_b128 v[2:5], v23
	v_add_u32_e32 v18, v18, v19
	v_and_b32_e32 v6, 56, v18
	v_lshl_add_u32 v6, v6, 1, v20
	ds_read_b128 v[24:27], v6 offset:34816
	ds_read_b128 v[28:31], v23 offset:32
	v_add_u32_e32 v19, 16, v18
	s_waitcnt lgkmcnt(0)
	v_mfma_f32_32x32x16_bf16 v[2:17], v[2:5], v[24:27], 0
	v_and_b32_e32 v19, 56, v19
	v_lshl_add_u32 v19, v19, 1, v20
	ds_read_b128 v[50:53], v19 offset:34816
	ds_read_b128 v[32:35], v23 offset:64
	ds_read_b128 v[54:57], v23 offset:4704
	v_bitop3_b32 v19, v18, 32, 56 bitop3:0x6c
	v_lshl_add_u32 v19, v19, 1, v20
	ds_read_b128 v[58:61], v19 offset:34816
	v_add_u32_e32 v18, 48, v18
	s_waitcnt lgkmcnt(0)
	v_mfma_f32_32x32x16_bf16 v[2:17], v[28:31], v[50:53], v[2:17]
	v_and_b32_e32 v18, 56, v18
	v_lshl_add_u32 v18, v18, 1, v20
	ds_read_b128 v[28:31], v23 offset:96
	ds_read_b128 v[114:117], v18 offset:34816
	v_mul_u32_u24_e32 v18, 0x110, v22
	v_add3_u32 v18, s3, v90, v18
	s_lshl_b32 s6, s8, 2
	v_mfma_f32_32x32x16_bf16 v[2:17], v[32:35], v[58:61], v[2:17]
	s_add_u32 s6, s42, s6
	s_addc_u32 s7, s43, 0
	s_lshl_b32 s9, s65, 7
	s_addk_i32 s9, 0x100
	s_add_i32 s10, s59, 0x100
	v_add_u32_e32 v20, s10, v90
	s_lshl_b32 s26, s8, 1
	s_waitcnt lgkmcnt(0)
	v_mfma_f32_32x32x16_bf16 v[2:17], v[28:31], v[114:117], v[2:17]
	ds_read_b128 v[28:31], v18
	ds_read_b128 v[118:121], v18 offset:32
	s_waitcnt vmcnt(0) lgkmcnt(0)
	v_mfma_f32_32x32x16_bf16 v[30:45], v[28:31], v[46:49], 0
	v_mfma_f32_32x32x16_bf16 v[30:45], v[118:121], v[86:89], v[30:45]
	ds_read_b128 v[118:121], v18 offset:64
	ds_read_b128 v[122:125], v18 offset:96
	s_waitcnt lgkmcnt(1)
	v_mfma_f32_32x32x16_bf16 v[30:45], v[118:121], v[82:85], v[30:45]
	ds_read_b128 v[118:121], v18 offset:128
	s_waitcnt lgkmcnt(1)
	v_mfma_f32_32x32x16_bf16 v[30:45], v[122:125], v[78:81], v[30:45]
	ds_read_b128 v[122:125], v23 offset:4608
	ds_read_b128 v[126:129], v23 offset:4640
	ds_read_b128 v[130:133], v23 offset:4672
	ds_read_b128 v[134:137], v18 offset:160
	s_waitcnt lgkmcnt(4)
	v_mfma_f32_32x32x16_bf16 v[30:45], v[118:121], v[74:77], v[30:45]
	ds_read_b128 v[118:121], v18 offset:8704
	ds_read_b128 v[138:141], v18 offset:8736
	ds_read_b128 v[142:145], v18 offset:8768
	ds_read_b128 v[146:149], v18 offset:8800
	ds_read_b128 v[150:153], v18 offset:8832
	ds_read_b128 v[154:157], v18 offset:8864
	ds_read_b128 v[158:161], v18 offset:192
	ds_read_b128 v[162:165], v18 offset:224
	s_waitcnt lgkmcnt(8)
	v_mfma_f32_32x32x16_bf16 v[30:45], v[134:137], v[70:73], v[30:45]
	ds_read_b128 v[134:137], v18 offset:8896
	ds_read_b128 v[166:169], v18 offset:8928
	v_lshl_add_u32 v18, v22, 2, s9
	s_add_i32 s9, s49, 0x100
	v_add_u32_e32 v19, s9, v90
	s_waitcnt lgkmcnt(0)
	s_barrier
	v_mfma_f32_32x32x16_bf16 v[30:45], v[158:161], v[66:69], v[30:45]
	ds_read_b32 v19, v19
	ds_read_b32 v20, v20
	v_mfma_f32_32x32x16_bf16 v[30:45], v[162:165], v[62:65], v[30:45]
	s_waitcnt lgkmcnt(1)
	s_nop 10
	v_fma_f32 v2, v30, v19, v2
	s_waitcnt lgkmcnt(0)
	v_mul_f32_e32 v2, v20, v2
	v_mad_u32_u24 v19, v21, s60, v18
	ds_write_b32 v19, v2
	v_lshl_or_b32 v2, v21, 2, 1
	v_lshlrev_b32_e32 v19, 2, v2
	v_add_u32_e32 v20, s9, v19
	v_add_u32_e32 v19, s10, v19
	ds_read_b32 v20, v20
	ds_read_b32 v19, v19
	v_mad_u32_u24 v2, v2, s61, v18
	s_waitcnt lgkmcnt(1)
	v_fma_f32 v3, v31, v20, v3
	s_waitcnt lgkmcnt(0)
	v_mul_f32_e32 v3, v19, v3
	ds_write_b32 v2, v3
	v_or_b32_e32 v3, 8, v90
	v_add_u32_e32 v18, s9, v3
	v_add_u32_e32 v3, s10, v3
	ds_read_b32 v18, v18
	ds_read_b32 v3, v3
	s_waitcnt lgkmcnt(1)
	v_fma_f32 v4, v32, v18, v4
	s_waitcnt lgkmcnt(0)
	v_mul_f32_e32 v3, v3, v4
	ds_write_b32 v2, v3 offset:1040
	v_or_b32_e32 v3, 12, v90
	v_add_u32_e32 v4, s9, v3
	v_add_u32_e32 v3, s10, v3
	ds_read_b32 v4, v4
	ds_read_b32 v3, v3
	s_waitcnt lgkmcnt(1)
	v_fma_f32 v4, v33, v4, v5
	s_waitcnt lgkmcnt(0)
	v_mul_f32_e32 v3, v3, v4
	ds_write_b32 v2, v3 offset:2080
	v_or_b32_e32 v3, 32, v90
	v_add_u32_e32 v4, s9, v3
	v_add_u32_e32 v3, s10, v3
	ds_read_b32 v4, v4
	ds_read_b32 v3, v3
	v_mfma_f32_32x32x16_bf16 v[18:33], v[122:125], v[24:27], 0
	s_waitcnt lgkmcnt(1)
	v_fma_f32 v4, v34, v4, v6
	s_waitcnt lgkmcnt(0)
	v_mul_f32_e32 v3, v3, v4
	ds_write_b32 v2, v3 offset:7280
	v_or_b32_e32 v3, 36, v90
	v_add_u32_e32 v4, s9, v3
	v_add_u32_e32 v3, s10, v3
	ds_read_b32 v4, v4
	ds_read_b32 v3, v3
	v_mfma_f32_32x32x16_bf16 v[18:33], v[126:129], v[50:53], v[18:33]
	v_add_u32_e32 v34, s64, v109
	s_waitcnt lgkmcnt(1)
	v_fma_f32 v4, v35, v4, v7
	s_waitcnt lgkmcnt(0)
	v_mul_f32_e32 v3, v3, v4
	ds_write_b32 v2, v3 offset:8320
	v_or_b32_e32 v3, 40, v90
	v_add_u32_e32 v4, s9, v3
	v_add_u32_e32 v3, s10, v3
	ds_read_b32 v4, v4
	ds_read_b32 v3, v3
	v_mfma_f32_32x32x16_bf16 v[18:33], v[130:133], v[58:61], v[18:33]
	s_waitcnt lgkmcnt(1)
	v_fma_f32 v4, v36, v4, v8
	s_waitcnt lgkmcnt(0)
	v_mul_f32_e32 v3, v3, v4
	ds_write_b32 v2, v3 offset:9360
	v_or_b32_e32 v3, 44, v90
	v_add_u32_e32 v4, s9, v3
	v_add_u32_e32 v3, s10, v3
	ds_read_b32 v4, v4
	ds_read_b32 v3, v3
	v_mfma_f32_32x32x16_bf16 v[18:33], v[54:57], v[114:117], v[18:33]
	s_waitcnt lgkmcnt(1)
	v_fma_f32 v4, v37, v4, v9
	s_waitcnt lgkmcnt(0)
	v_mul_f32_e32 v3, v3, v4
	ds_write_b32 v2, v3 offset:10400
	v_or_b32_e32 v3, 64, v90
	v_add_u32_e32 v4, s9, v3
	v_add_u32_e32 v3, s10, v3
	ds_read_b32 v4, v4
	ds_read_b32 v3, v3
	v_mfma_f32_32x32x16_bf16 v[46:61], v[118:121], v[46:49], 0
	s_waitcnt lgkmcnt(1)
	v_fma_f32 v4, v38, v4, v10
	s_waitcnt lgkmcnt(0)
; __device__ __forceinline__ int crow(int r, int hi) { return (r & 3) + 8 * (r >> 2) + 4 * hi; }
; __device__ __forceinline__ void mlstm_out_unit(const Params& P, int l, int h, int n, char* lds) {
;     ...
; #pragma unroll
;     for (int ti = 0; ti < 2; ++ti)
; #pragma unroll
;         for (int r = 0; r < 16; ++r) { const int t = 32 * ti + fox::crow(r, hi);
;             Hb[t * 260 + 32 * wid + r32] = (a1[ti][r] + sil[t] * a2[ti][r]) * rden[t]; }
;     __syncthreads();
;     {
;         const int t = tid >> 3, p = tid & 7; f32x4 hv[8]; float ss = 0.f;
	v_mul_f32_e32 v3, v3, v4
	ds_write_b32 v2, v3 offset:15600
	v_or_b32_e32 v3, 0x44, v90
	v_add_u32_e32 v4, s9, v3
	v_add_u32_e32 v3, s10, v3
	ds_read_b32 v4, v4
	ds_read_b32 v3, v3
	v_mfma_f32_32x32x16_bf16 v[46:61], v[138:141], v[86:89], v[46:61]
	s_waitcnt lgkmcnt(1)
	v_fma_f32 v4, v39, v4, v11
	s_waitcnt lgkmcnt(0)
	v_mul_f32_e32 v3, v3, v4
	ds_write_b32 v2, v3 offset:16640
	v_or_b32_e32 v3, 0x48, v90
	v_add_u32_e32 v4, s9, v3
	v_add_u32_e32 v3, s10, v3
	ds_read_b32 v4, v4
	ds_read_b32 v3, v3
	v_mfma_f32_32x32x16_bf16 v[46:61], v[142:145], v[82:85], v[46:61]
	v_mov_b64_e32 v[10:11], s[14:15]
	s_waitcnt lgkmcnt(1)
	v_fma_f32 v4, v40, v4, v12
	s_waitcnt lgkmcnt(0)
	v_mul_f32_e32 v3, v3, v4
	ds_write_b32 v2, v3 offset:17680
	v_or_b32_e32 v3, 0x4c, v90
	v_add_u32_e32 v4, s9, v3
	v_add_u32_e32 v3, s10, v3
	ds_read_b32 v4, v4
	ds_read_b32 v3, v3
	v_mfma_f32_32x32x16_bf16 v[46:61], v[146:149], v[78:81], v[46:61]
	s_waitcnt lgkmcnt(1)
	v_fma_f32 v4, v41, v4, v13
	s_waitcnt lgkmcnt(0)
	v_mul_f32_e32 v3, v3, v4
	ds_write_b32 v2, v3 offset:18720
	v_or_b32_e32 v3, 0x60, v90
	v_add_u32_e32 v4, s9, v3
	v_add_u32_e32 v3, s10, v3
	ds_read_b32 v4, v4
	ds_read_b32 v3, v3
	v_mfma_f32_32x32x16_bf16 v[46:61], v[150:153], v[74:77], v[46:61]
	s_waitcnt lgkmcnt(1)
	v_fma_f32 v4, v42, v4, v14
	s_waitcnt lgkmcnt(0)
	v_mul_f32_e32 v3, v3, v4
	ds_write_b32 v2, v3 offset:23920
	v_or_b32_e32 v3, 0x64, v90
	v_add_u32_e32 v4, s9, v3
	v_add_u32_e32 v3, s10, v3
	ds_read_b32 v4, v4
	ds_read_b32 v3, v3
	v_mfma_f32_32x32x16_bf16 v[46:61], v[154:157], v[70:73], v[46:61]
	s_waitcnt lgkmcnt(1)
	v_fma_f32 v4, v43, v4, v15
	s_waitcnt lgkmcnt(0)
	v_mul_f32_e32 v3, v3, v4
	ds_write_b32 v2, v3 offset:24960
	v_or_b32_e32 v3, 0x68, v90
	v_add_u32_e32 v4, s9, v3
	v_add_u32_e32 v3, s10, v3
	ds_read_b32 v4, v4
	ds_read_b32 v3, v3
	v_mfma_f32_32x32x16_bf16 v[46:61], v[134:137], v[66:69], v[46:61]
	s_waitcnt lgkmcnt(1)
	v_fma_f32 v4, v44, v4, v16
	s_waitcnt lgkmcnt(0)
	v_mul_f32_e32 v3, v3, v4
	ds_write_b32 v2, v3 offset:26000
	v_or_b32_e32 v3, 0x6c, v90
	v_add_u32_e32 v4, s9, v3
	v_add_u32_e32 v3, s10, v3
	ds_read_b32 v4, v4
	ds_read_b32 v3, v3
	v_mfma_f32_32x32x16_bf16 v[46:61], v[166:169], v[62:65], v[46:61]
	s_waitcnt lgkmcnt(1)
	v_fmac_f32_e32 v17, v45, v4
	s_waitcnt lgkmcnt(0)
	v_mul_f32_e32 v3, v3, v17
	ds_write_b32 v2, v3 offset:27040
	v_or_b32_e32 v3, 0x80, v90
	v_add_u32_e32 v4, s9, v3
	v_add_u32_e32 v3, s10, v3
	ds_read_b32 v4, v4
	ds_read_b32 v3, v3
	s_waitcnt lgkmcnt(1)
	s_nop 0
	v_fma_f32 v4, v46, v4, v18
	s_waitcnt lgkmcnt(0)
	v_mul_f32_e32 v3, v3, v4
	ds_write_b32 v2, v3 offset:32240
	v_or_b32_e32 v3, 0x84, v90
	v_add_u32_e32 v4, s9, v3
	v_add_u32_e32 v3, s10, v3
	ds_read_b32 v4, v4
	ds_read_b32 v3, v3
	s_waitcnt lgkmcnt(1)
	v_fma_f32 v4, v47, v4, v19
	s_waitcnt lgkmcnt(0)
	v_mul_f32_e32 v3, v3, v4
	ds_write_b32 v2, v3 offset:33280
	v_or_b32_e32 v3, 0x88, v90
	v_add_u32_e32 v4, s9, v3
	v_add_u32_e32 v3, s10, v3
	ds_read_b32 v4, v4
	ds_read_b32 v3, v3
	s_waitcnt lgkmcnt(1)
	v_fma_f32 v4, v48, v4, v20
	s_waitcnt lgkmcnt(0)
	v_mul_f32_e32 v3, v3, v4
	ds_write_b32 v2, v3 offset:34320
	v_or_b32_e32 v3, 0x8c, v90
	v_add_u32_e32 v4, s9, v3
	v_add_u32_e32 v3, s10, v3
	ds_read_b32 v4, v4
	ds_read_b32 v3, v3
	s_waitcnt lgkmcnt(1)
	v_fma_f32 v4, v49, v4, v21
	s_waitcnt lgkmcnt(0)
	v_mul_f32_e32 v3, v3, v4
	ds_write_b32 v2, v3 offset:35360
	v_or_b32_e32 v3, 0xa0, v90
	v_add_u32_e32 v4, s9, v3
	v_add_u32_e32 v3, s10, v3
	ds_read_b32 v4, v4
	ds_read_b32 v3, v3
	s_waitcnt lgkmcnt(1)
	v_fma_f32 v4, v50, v4, v22
	s_waitcnt lgkmcnt(0)
	v_mul_f32_e32 v3, v3, v4
	ds_write_b32 v2, v3 offset:40560
	v_or_b32_e32 v3, 0xa4, v90
	v_add_u32_e32 v4, s9, v3
	v_add_u32_e32 v3, s10, v3
	ds_read_b32 v4, v4
	ds_read_b32 v3, v3
	s_waitcnt lgkmcnt(1)
	v_fma_f32 v4, v51, v4, v23
	s_waitcnt lgkmcnt(0)
	v_mul_f32_e32 v3, v3, v4
	ds_write_b32 v2, v3 offset:41600
	v_or_b32_e32 v3, 0xa8, v90
	v_add_u32_e32 v4, s9, v3
	v_add_u32_e32 v3, s10, v3
	ds_read_b32 v4, v4
	ds_read_b32 v3, v3
	s_waitcnt lgkmcnt(1)
	v_fma_f32 v4, v52, v4, v24
	s_waitcnt lgkmcnt(0)
	v_mul_f32_e32 v3, v3, v4
	ds_write_b32 v2, v3 offset:42640
	v_or_b32_e32 v3, 0xac, v90
	v_add_u32_e32 v4, s9, v3
	v_add_u32_e32 v3, s10, v3
	ds_read_b32 v4, v4
	ds_read_b32 v3, v3
	s_waitcnt lgkmcnt(1)
	v_fma_f32 v4, v53, v4, v25
	s_waitcnt lgkmcnt(0)
	v_mul_f32_e32 v3, v3, v4
	ds_write_b32 v2, v3 offset:43680
	v_or_b32_e32 v3, 0xc0, v90
	v_add_u32_e32 v4, s9, v3
	v_add_u32_e32 v3, s10, v3
	ds_read_b32 v4, v4
	ds_read_b32 v3, v3
	s_waitcnt lgkmcnt(1)
	v_fma_f32 v4, v54, v4, v26
	s_waitcnt lgkmcnt(0)
	v_mul_f32_e32 v3, v3, v4
	ds_write_b32 v2, v3 offset:48880
	v_or_b32_e32 v3, 0xc4, v90
	v_add_u32_e32 v4, s9, v3
	v_add_u32_e32 v3, s10, v3
	ds_read_b32 v4, v4
	ds_read_b32 v3, v3
	s_waitcnt lgkmcnt(1)
	v_fma_f32 v4, v55, v4, v27
	s_waitcnt lgkmcnt(0)
	v_mul_f32_e32 v3, v3, v4
	ds_write_b32 v2, v3 offset:49920
	v_or_b32_e32 v3, 0xc8, v90
	v_add_u32_e32 v4, s9, v3
	v_add_u32_e32 v3, s10, v3
	ds_read_b32 v4, v4
	ds_read_b32 v3, v3
	s_waitcnt lgkmcnt(1)
	v_fma_f32 v4, v56, v4, v28
	s_waitcnt lgkmcnt(0)
	v_mul_f32_e32 v3, v3, v4
	ds_write_b32 v2, v3 offset:50960
	v_or_b32_e32 v3, 0xcc, v90
	v_add_u32_e32 v4, s9, v3
	v_add_u32_e32 v3, s10, v3
	ds_read_b32 v4, v4
	ds_read_b32 v3, v3
	s_waitcnt lgkmcnt(1)
	v_fma_f32 v4, v57, v4, v29
	s_waitcnt lgkmcnt(0)
	v_mul_f32_e32 v3, v3, v4
	ds_write_b32 v2, v3 offset:52000
	v_or_b32_e32 v3, 0xe0, v90
	v_add_u32_e32 v4, s9, v3
	v_add_u32_e32 v3, s10, v3
	ds_read_b32 v4, v4
	ds_read_b32 v3, v3
	s_waitcnt lgkmcnt(1)
	v_fma_f32 v4, v58, v4, v30
	s_waitcnt lgkmcnt(0)
	v_mul_f32_e32 v3, v3, v4
	ds_write_b32 v2, v3 offset:57200
	v_or_b32_e32 v3, 0xe4, v90
	v_add_u32_e32 v4, s9, v3
	v_add_u32_e32 v3, s10, v3
	ds_read_b32 v4, v4
	ds_read_b32 v3, v3
	s_waitcnt lgkmcnt(1)
	v_fma_f32 v4, v59, v4, v31
	s_waitcnt lgkmcnt(0)
	v_mul_f32_e32 v3, v3, v4
	ds_write_b32 v2, v3 offset:58240
	v_or_b32_e32 v3, 0xe8, v90
	v_add_u32_e32 v4, s9, v3
	v_add_u32_e32 v3, s10, v3
	ds_read_b32 v4, v4
	ds_read_b32 v3, v3
	s_waitcnt lgkmcnt(1)
	v_fma_f32 v4, v60, v4, v32
	s_waitcnt lgkmcnt(0)
	v_mul_f32_e32 v3, v3, v4
	ds_write_b32 v2, v3 offset:59280
	v_or_b32_e32 v3, 0xec, v90
	v_add_u32_e32 v4, s9, v3
	v_add_u32_e32 v3, s10, v3
	ds_read_b32 v4, v4
	ds_read_b32 v3, v3
	v_mad_i64_i32 v[10:11], s[10:11], v34, s50, v[10:11]
	v_lshl_add_u64 v[10:11], v[10:11], 0, s[26:27]
	s_waitcnt lgkmcnt(1)
	v_fmac_f32_e32 v33, v61, v4
	s_waitcnt lgkmcnt(0)
	v_mul_f32_e32 v3, v3, v33
	ds_write_b32 v2, v3 offset:60320
	v_mul_lo_u32 v2, v109, s61
	v_add3_u32 v35, s3, v2, v92
	s_waitcnt lgkmcnt(0)
	s_barrier
; __device__ __forceinline__ unsigned cvt_pk_bf16(float lo, float hi) { unsigned r; asm volatile("v_cvt_pk_bf16_f32 %0, %1, %2" : "=v"(r) : "v"(lo), "v"(hi)); return r; }
; __device__ __forceinline__ float bflo(unsigned w) { return __uint_as_float(w << 16); }
; __device__ __forceinline__ float bfhi(unsigned w) { return __uint_as_float(w & 0xffff0000u); }
; __device__ __forceinline__ float sigmoidf(float x) { return 1.f / (1.f + __expf(-x)); }
; __device__ __forceinline__ void mlstm_out_unit(const Params& P, int l, int h, int n, char* lds) {
;     ...
;         const int t = tid >> 3, p = tid & 7; f32x4 hv[8]; float ss = 0.f;
; #pragma unroll
;         for (int j = 0; j < 8; ++j) { hv[j] = *(const f32x4*)(Hb + t * 260 + 32 * j + 4 * p); ss += (hv[j][0] * hv[j][0] + hv[j][1] * hv[j][1]) + (hv[j][2] * hv[j][2] + hv[j][3] * hv[j][3]); }
;         ss += __shfl_xor(ss, 1); ss += __shfl_xor(ss, 2); ss += __shfl_xor(ss, 4);
;         const float rs = rsqrtf(ss * (1.f / 256.f) + RMS_EPS);
;         const size_t row = (size_t)(t0 + t);
; #pragma unroll
;         for (int j = 0; j < 8; ++j) { const int e = 32 * j + 4 * p; const f32x4 gn = *(const f32x4*)(mnorm + e);
;             const u32x2 mo = *(const u32x2*)(PROJ + row * PW + C_MO + h * 256 + e);
;             const float o0 = hv[j][0] * rs * gn[0] * sigmoidf(bflo(mo.x)), o1 = hv[j][1] * rs * gn[1] * sigmoidf(bfhi(mo.x));
;             const float o2 = hv[j][2] * rs * gn[2] * sigmoidf(bflo(mo.y)), o3 = hv[j][3] * rs * gn[3] * sigmoidf(bfhi(mo.y));
;             u32x2 w; w.x = cvt_pk_bf16(o0, o1); w.y = cvt_pk_bf16(o2, o3);
;             *(u32x2*)(MIX + row * DM + h * 256 + e) = w; }
	ds_read_b128 v[30:33], v35
	ds_read_b128 v[26:29], v35 offset:128
	ds_read_b128 v[22:25], v35 offset:256
	ds_read_b128 v[18:21], v35 offset:384
	v_lshlrev_b32_e32 v90, 3, v93
	s_waitcnt lgkmcnt(3)
	v_mov_b32_e32 v4, v31
	s_waitcnt lgkmcnt(2)
	v_mov_b32_e32 v5, v27
	v_mov_b32_e32 v2, v30
	v_mov_b32_e32 v3, v26
	v_pk_mul_f32 v[4:5], v[4:5], v[4:5]
	v_mov_b32_e32 v6, v33
	v_mov_b32_e32 v7, v29
	v_pk_fma_f32 v[2:3], v[2:3], v[2:3], v[4:5]
	v_mov_b32_e32 v4, v32
	v_mov_b32_e32 v5, v28
	v_pk_mul_f32 v[6:7], v[6:7], v[6:7]
	v_lshl_add_u64 v[42:43], v[10:11], 0, v[90:91]
	v_pk_fma_f32 v[4:5], v[4:5], v[4:5], v[6:7]
	s_waitcnt lgkmcnt(1)
	v_pk_mul_f32 v[6:7], v[22:23], v[22:23]
	v_pk_add_f32 v[2:3], v[2:3], v[4:5]
	v_pk_mul_f32 v[4:5], v[24:25], v[24:25]
	v_add_co_u32_e32 v10, vcc, s51, v42
	v_pk_mov_b32 v[8:9], v[6:7], v[4:5] op_sel:[1,0]
	v_mov_b32_e32 v7, v5
	v_addc_co_u32_e32 v11, vcc, 0, v43, vcc
	v_pk_add_f32 v[4:5], v[8:9], v[6:7]
	ds_read_b128 v[14:17], v35 offset:512
	ds_read_b128 v[6:9], v35 offset:640
	flat_load_dwordx2 v[44:45], v[10:11]
	global_load_dwordx2 v[196:197], v[10:11], off offset:64
	global_load_dwordx2 v[198:199], v[10:11], off offset:128
	global_load_dwordx2 v[200:201], v[10:11], off offset:192
	global_load_dwordx2 v[202:203], v[10:11], off offset:256
	global_load_dwordx2 v[204:205], v[10:11], off offset:320
	global_load_dwordx2 v[206:207], v[10:11], off offset:384
	global_load_dwordx2 v[208:209], v[10:11], off offset:448
	v_mov_b32_e32 v93, v91
	v_lshl_add_u64 v[46:47], s[6:7], 0, v[92:93]
	v_add_co_u32_e32 v10, vcc, s51, v46
	s_waitcnt lgkmcnt(0)
	v_mul_f32_e32 v12, v14, v14
	v_addc_co_u32_e32 v11, vcc, 0, v47, vcc
	flat_load_dwordx4 v[38:41], v[10:11]
	global_load_dwordx4 v[212:215], v[10:11], off offset:128
	global_load_dwordx4 v[216:219], v[10:11], off offset:256
	global_load_dwordx4 v[220:223], v[10:11], off offset:384
	global_load_dwordx4 v[224:227], v[10:11], off offset:512
	global_load_dwordx4 v[228:231], v[10:11], off offset:640
	global_load_dwordx4 v[232:235], v[10:11], off offset:768
	global_load_dwordx4 v[236:239], v[10:11], off offset:896
	v_mul_f32_e32 v13, v15, v15
	v_pk_add_f32 v[2:3], v[2:3], v[2:3] op_sel:[0,1] op_sel_hi:[1,0]
	v_pk_add_f32 v[4:5], v[4:5], v[4:5] op_sel:[0,1] op_sel_hi:[1,0]
	v_mov_b32_e32 v3, v12
	v_mov_b32_e32 v5, v13
	v_pk_add_f32 v[2:3], v[2:3], v[4:5]
	v_mul_f32_e32 v4, v19, v19
	v_mul_f32_e32 v10, v21, v21
	v_mul_f32_e32 v36, v16, v16
	v_mul_f32_e32 v37, v17, v17
	v_pk_fma_f32 v[4:5], v[18:19], v[18:19], v[4:5] op_sel_hi:[1,1,0]
	v_pk_fma_f32 v[10:11], v[20:21], v[20:21], v[10:11] op_sel_hi:[1,1,0]
	v_mov_b32_e32 v5, v36
	v_mov_b32_e32 v11, v37
	v_pk_add_f32 v[4:5], v[4:5], v[10:11]
	v_pk_mul_f32 v[48:49], v[8:9], v[8:9]
	v_pk_add_f32 v[36:37], v[2:3], v[4:5]
	ds_read_b128 v[10:13], v35 offset:768
	ds_read_b128 v[2:5], v35 offset:896
	v_pk_mul_f32 v[50:51], v[6:7], v[6:7]
	v_pk_add_f32 v[36:37], v[36:37], v[36:37] op_sel:[0,1] op_sel_hi:[1,0]
	v_pk_mov_b32 v[52:53], v[50:51], v[48:49] op_sel:[1,0]
	v_mov_b32_e32 v51, v49
	v_pk_add_f32 v[48:49], v[52:53], v[50:51]
	s_waitcnt lgkmcnt(0)
	v_mul_f32_e32 v35, v2, v2
	v_mul_f32_e32 v50, v3, v3
	v_pk_add_f32 v[48:49], v[48:49], v[48:49] op_sel:[0,1] op_sel_hi:[1,0]
	v_mov_b32_e32 v37, v35
	v_mov_b32_e32 v49, v50
	v_pk_add_f32 v[36:37], v[36:37], v[48:49]
	v_mul_f32_e32 v48, v11, v11
	v_mul_f32_e32 v51, v4, v4
	v_pk_fma_f32 v[48:49], v[10:11], v[10:11], v[48:49] op_sel_hi:[1,1,0]
	v_mul_f32_e32 v50, v13, v13
	v_mul_f32_e32 v52, v5, v5
	v_mov_b32_e32 v49, v51
	v_pk_fma_f32 v[50:51], v[12:13], v[12:13], v[50:51] op_sel_hi:[1,1,0]
	s_add_u32 s6, s40, s26
	v_mov_b32_e32 v51, v52
	v_pk_add_f32 v[48:49], v[48:49], v[50:51]
	s_addc_u32 s7, s41, 0
	v_pk_add_f32 v[36:37], v[36:37], v[48:49]
	s_nop 0
	v_add_f32_e32 v35, v36, v37
	ds_bpermute_b32 v36, v110, v35
	s_waitcnt lgkmcnt(0)
	v_add_f32_e32 v35, v35, v36
	ds_bpermute_b32 v36, v111, v35
	s_waitcnt lgkmcnt(0)
	v_add_f32_e32 v35, v35, v36
	ds_bpermute_b32 v36, v112, v35
	s_waitcnt lgkmcnt(0)
	v_add_f32_e32 v35, v35, v36
	v_fmamk_f32 v35, v35, 0x3b800000, v104
	v_mul_f32_e32 v36, 0x4b800000, v35
	v_cmp_gt_f32_e32 vcc, s62, v35
	s_waitcnt vmcnt(0)
	v_lshlrev_b32_e32 v37, 16, v44
	v_cndmask_b32_e32 v35, v35, v36, vcc
	v_rsq_f32_e32 v35, v35
	v_mul_f32_e32 v37, 0xbfb8aa3b, v37
	v_exp_f32_e32 v37, v37
	v_mul_f32_e32 v36, 0x45800000, v35
	v_cndmask_b32_e32 v36, v35, v36, vcc
	v_ashrrev_i32_e32 v35, 31, v34
	v_lshlrev_b64 v[34:35], 12, v[34:35]
	v_add_f32_e32 v37, 1.0, v37
	v_lshl_add_u64 v[48:49], s[6:7], 0, v[34:35]
	v_div_scale_f32 v50, s[6:7], v37, v37, 1.0
	v_rcp_f32_e32 v51, v50
	v_mul_f32_e32 v30, v30, v36
	v_mul_f32_e32 v30, v38, v30
	v_lshl_add_u64 v[34:35], v[42:43], 0, s[30:31]
	v_fma_f32 v38, -v50, v51, 1.0
	v_fmac_f32_e32 v51, v38, v51
	v_div_scale_f32 v38, vcc, 1.0, v37, 1.0
	v_mul_f32_e32 v42, v38, v51
	v_fma_f32 v43, -v50, v42, v38
	v_fmac_f32_e32 v42, v43, v51
	v_and_b32_e32 v43, 0xffff0000, v44
	v_mul_f32_e32 v43, 0xbfb8aa3b, v43
	v_exp_f32_e32 v43, v43
	v_fma_f32 v38, -v50, v42, v38
	v_div_fmas_f32 v38, v38, v51, v42
	v_div_fixup_f32 v37, v38, v37, 1.0
	v_add_f32_e32 v38, 1.0, v43
	v_div_scale_f32 v42, s[6:7], v38, v38, 1.0
	v_rcp_f32_e32 v43, v42
	v_mul_f32_e32 v30, v37, v30
	v_mul_f32_e32 v31, v31, v36
	v_mul_f32_e32 v31, v39, v31
	v_fma_f32 v37, -v42, v43, 1.0
	v_fmac_f32_e32 v43, v37, v43
	v_div_scale_f32 v37, vcc, 1.0, v38, 1.0
	v_mul_f32_e32 v39, v37, v43
	v_fma_f32 v44, -v42, v39, v37
	v_fmac_f32_e32 v39, v44, v43
	v_fma_f32 v37, -v42, v39, v37
	v_lshlrev_b32_e32 v42, 16, v45
	v_mul_f32_e32 v42, 0xbfb8aa3b, v42
	v_exp_f32_e32 v42, v42
	v_div_fmas_f32 v37, v37, v43, v39
; __device__ __forceinline__ unsigned cvt_pk_bf16(float lo, float hi) { unsigned r; asm volatile("v_cvt_pk_bf16_f32 %0, %1, %2" : "=v"(r) : "v"(lo), "v"(hi)); return r; }
; __device__ __forceinline__ float bflo(unsigned w) { return __uint_as_float(w << 16); }
; __device__ __forceinline__ float bfhi(unsigned w) { return __uint_as_float(w & 0xffff0000u); }
; __device__ __forceinline__ float sigmoidf(float x) { return 1.f / (1.f + __expf(-x)); }
; __device__ __forceinline__ void mlstm_out_unit(const Params& P, int l, int h, int n, char* lds) {
;     ...
;         for (int j = 0; j < 8; ++j) { const int e = 32 * j + 4 * p; const f32x4 gn = *(const f32x4*)(mnorm + e);
;             const u32x2 mo = *(const u32x2*)(PROJ + row * PW + C_MO + h * 256 + e);
;             const float o0 = hv[j][0] * rs * gn[0] * sigmoidf(bflo(mo.x)), o1 = hv[j][1] * rs * gn[1] * sigmoidf(bfhi(mo.x));
;             const float o2 = hv[j][2] * rs * gn[2] * sigmoidf(bflo(mo.y)), o3 = hv[j][3] * rs * gn[3] * sigmoidf(bfhi(mo.y));
;             u32x2 w; w.x = cvt_pk_bf16(o0, o1); w.y = cvt_pk_bf16(o2, o3);
;             *(u32x2*)(MIX + row * DM + h * 256 + e) = w; }
	v_div_fixup_f32 v37, v37, v38, 1.0
	v_mul_f32_e32 v31, v37, v31
	v_add_f32_e32 v38, 1.0, v42
	v_div_scale_f32 v39, s[6:7], v38, v38, 1.0
	v_rcp_f32_e32 v42, v39
	v_mul_f32_e32 v32, v32, v36
	v_mul_f32_e32 v32, v40, v32
	v_mul_f32_e32 v33, v33, v36
	v_fma_f32 v37, -v39, v42, 1.0
	v_fmac_f32_e32 v42, v37, v42
	v_div_scale_f32 v37, vcc, 1.0, v38, 1.0
	v_mul_f32_e32 v40, v37, v42
	v_fma_f32 v43, -v39, v40, v37
	v_fmac_f32_e32 v40, v43, v42
	v_fma_f32 v37, -v39, v40, v37
	v_and_b32_e32 v39, 0xffff0000, v45
	v_mul_f32_e32 v39, 0xbfb8aa3b, v39
	v_exp_f32_e32 v39, v39
	v_div_fmas_f32 v37, v37, v42, v40
	v_div_fixup_f32 v37, v37, v38, 1.0
	v_mul_f32_e32 v32, v37, v32
	v_add_f32_e32 v38, 1.0, v39
	v_div_scale_f32 v39, s[6:7], v38, v38, 1.0
	v_rcp_f32_e32 v40, v39
	v_mul_f32_e32 v33, v41, v33
	v_cvt_pk_bf16_f32 v30, v30, v31
	v_mul_f32_e32 v26, v26, v36
	v_fma_f32 v37, -v39, v40, 1.0
	v_fmac_f32_e32 v40, v37, v40
	v_div_scale_f32 v37, vcc, 1.0, v38, 1.0
	v_mul_f32_e32 v41, v37, v40
	v_fma_f32 v42, -v39, v41, v37
	v_fmac_f32_e32 v41, v42, v40
	v_fma_f32 v37, -v39, v41, v37
	v_div_fmas_f32 v37, v37, v40, v41
	v_div_fixup_f32 v37, v37, v38, 1.0
	v_lshl_add_u64 v[42:43], v[48:49], 0, v[90:91]
	v_mul_f32_e32 v33, v37, v33
	v_cvt_pk_bf16_f32 v31, v32, v33
	v_add_co_u32_e32 v32, vcc, s63, v42
	v_mul_f32_e32 v27, v27, v36
	s_nop 0
	v_addc_co_u32_e32 v33, vcc, 0, v43, vcc
	flat_store_dwordx2 v[32:33], v[30:31]
	v_lshl_add_u64 v[32:33], v[46:47], 0, s[30:31]
	v_mul_f32_e32 v28, v28, v36
	v_mul_f32_e32 v29, v29, v36
	v_mul_f32_e32 v22, v22, v36
	v_mul_f32_e32 v23, v23, v36
	v_mul_f32_e32 v24, v24, v36
	v_mul_f32_e32 v25, v25, v36
	v_mul_f32_e32 v18, v18, v36
	v_mul_f32_e32 v19, v19, v36
	v_mul_f32_e32 v20, v20, v36
	v_mul_f32_e32 v21, v21, v36
	v_mul_f32_e32 v14, v14, v36
	v_mul_f32_e32 v15, v15, v36
	v_mul_f32_e32 v16, v16, v36
	v_mul_f32_e32 v17, v17, v36
	v_mul_f32_e32 v6, v6, v36
	v_mul_f32_e32 v7, v7, v36
	v_mul_f32_e32 v8, v8, v36
	v_mul_f32_e32 v9, v9, v36
	v_mul_f32_e32 v10, v10, v36
	v_mul_f32_e32 v11, v11, v36
	v_mul_f32_e32 v12, v12, v36
	v_mul_f32_e32 v13, v13, v36
	v_mul_f32_e32 v2, v2, v36
	v_mul_f32_e32 v3, v3, v36
	v_mul_f32_e32 v4, v4, v36
	v_mul_f32_e32 v5, v5, v36
	s_nop 1
	v_mov_b32_e32 v44, v196
	v_mov_b32_e32 v45, v197
	v_mov_b32_e32 v38, v212
	v_mov_b32_e32 v39, v213
	v_mov_b32_e32 v40, v214
	v_mov_b32_e32 v41, v215
	v_lshlrev_b32_e32 v30, 16, v44
	v_mul_f32_e32 v30, 0xbfb8aa3b, v30
	v_exp_f32_e32 v30, v30
	v_mul_f32_e32 v26, v38, v26
	v_mul_f32_e32 v27, v39, v27
	v_mul_f32_e32 v28, v40, v28
	v_add_f32_e32 v37, 1.0, v30
	v_div_scale_f32 v46, s[6:7], v37, v37, 1.0
	v_rcp_f32_e32 v47, v46
	v_lshl_add_u64 v[30:31], v[42:43], 0, s[36:37]
	v_mul_f32_e32 v29, v41, v29
	v_fma_f32 v38, -v46, v47, 1.0
	v_fmac_f32_e32 v47, v38, v47
	v_div_scale_f32 v38, vcc, 1.0, v37, 1.0
	v_mul_f32_e32 v42, v38, v47
	v_fma_f32 v43, -v46, v42, v38
	v_fmac_f32_e32 v42, v43, v47
	v_and_b32_e32 v43, 0xffff0000, v44
	v_mul_f32_e32 v43, 0xbfb8aa3b, v43
	v_exp_f32_e32 v43, v43
	v_fma_f32 v38, -v46, v42, v38
	v_div_fmas_f32 v38, v38, v47, v42
	v_div_fixup_f32 v37, v38, v37, 1.0
	v_add_f32_e32 v38, 1.0, v43
	v_div_scale_f32 v42, s[6:7], v38, v38, 1.0
	v_rcp_f32_e32 v43, v42
	v_mul_f32_e32 v26, v37, v26
	v_fma_f32 v37, -v42, v43, 1.0
	v_fmac_f32_e32 v43, v37, v43
	v_div_scale_f32 v37, vcc, 1.0, v38, 1.0
	v_mul_f32_e32 v39, v37, v43
	v_fma_f32 v44, -v42, v39, v37
	v_fmac_f32_e32 v39, v44, v43
	v_fma_f32 v37, -v42, v39, v37
	v_lshlrev_b32_e32 v42, 16, v45
	v_mul_f32_e32 v42, 0xbfb8aa3b, v42
	v_exp_f32_e32 v42, v42
	v_div_fmas_f32 v37, v37, v43, v39
	v_div_fixup_f32 v37, v37, v38, 1.0
	v_mul_f32_e32 v27, v37, v27
	v_add_f32_e32 v38, 1.0, v42
	v_div_scale_f32 v39, s[6:7], v38, v38, 1.0
	v_rcp_f32_e32 v42, v39
	v_cvt_pk_bf16_f32 v26, v26, v27
	s_nop 0
	v_fma_f32 v37, -v39, v42, 1.0
	v_fmac_f32_e32 v42, v37, v42
	v_div_scale_f32 v37, vcc, 1.0, v38, 1.0
	v_mul_f32_e32 v40, v37, v42
	v_fma_f32 v43, -v39, v40, v37
	v_fmac_f32_e32 v40, v43, v42
	v_fma_f32 v37, -v39, v40, v37
	v_and_b32_e32 v39, 0xffff0000, v45
	v_mul_f32_e32 v39, 0xbfb8aa3b, v39
	v_exp_f32_e32 v39, v39
	v_div_fmas_f32 v37, v37, v42, v40
	v_div_fixup_f32 v37, v37, v38, 1.0
	v_mul_f32_e32 v28, v37, v28
	v_add_f32_e32 v38, 1.0, v39
	v_div_scale_f32 v39, s[6:7], v38, v38, 1.0
	v_rcp_f32_e32 v40, v39
	s_nop 0
	v_fma_f32 v37, -v39, v40, 1.0
	v_fmac_f32_e32 v40, v37, v40
	v_div_scale_f32 v37, vcc, 1.0, v38, 1.0
	v_mul_f32_e32 v41, v37, v40
	v_fma_f32 v42, -v39, v41, v37
	v_fmac_f32_e32 v41, v42, v40
	v_fma_f32 v37, -v39, v41, v37
	v_div_fmas_f32 v37, v37, v40, v41
	v_div_fixup_f32 v37, v37, v38, 1.0
	v_mul_f32_e32 v29, v37, v29
	v_cvt_pk_bf16_f32 v27, v28, v29
	flat_store_dwordx2 v[30:31], v[26:27] offset:64
	s_nop 0
	s_nop 1
	v_mov_b32_e32 v38, v198
	v_mov_b32_e32 v39, v199
	v_mov_b32_e32 v26, v216
	v_mov_b32_e32 v27, v217
	v_mov_b32_e32 v28, v218
	v_mov_b32_e32 v29, v219
	v_lshlrev_b32_e32 v37, 16, v38
	v_mul_f32_e32 v37, 0xbfb8aa3b, v37
	v_exp_f32_e32 v37, v37
	v_mul_f32_e32 v22, v26, v22
	v_and_b32_e32 v38, 0xffff0000, v38
	v_mul_f32_e32 v38, 0xbfb8aa3b, v38
	v_add_f32_e32 v37, 1.0, v37
	v_div_scale_f32 v40, s[6:7], v37, v37, 1.0
	v_rcp_f32_e32 v41, v40
	v_exp_f32_e32 v38, v38
	v_mul_f32_e32 v23, v27, v23
	v_mul_f32_e32 v24, v28, v24
	v_fma_f32 v26, -v40, v41, 1.0
	v_fmac_f32_e32 v41, v26, v41
	v_div_scale_f32 v26, vcc, 1.0, v37, 1.0
	v_mul_f32_e32 v42, v26, v41
	v_fma_f32 v43, -v40, v42, v26
	v_fmac_f32_e32 v42, v43, v41
	v_fma_f32 v26, -v40, v42, v26
	v_div_fmas_f32 v26, v26, v41, v42
	v_div_fixup_f32 v26, v26, v37, 1.0
	v_add_f32_e32 v37, 1.0, v38
	v_div_scale_f32 v38, s[6:7], v37, v37, 1.0
	v_rcp_f32_e32 v40, v38
; __device__ __forceinline__ unsigned cvt_pk_bf16(float lo, float hi) { unsigned r; asm volatile("v_cvt_pk_bf16_f32 %0, %1, %2" : "=v"(r) : "v"(lo), "v"(hi)); return r; }
; __device__ __forceinline__ float bflo(unsigned w) { return __uint_as_float(w << 16); }
; __device__ __forceinline__ float bfhi(unsigned w) { return __uint_as_float(w & 0xffff0000u); }
; __device__ __forceinline__ float sigmoidf(float x) { return 1.f / (1.f + __expf(-x)); }
; __device__ __forceinline__ void mlstm_out_unit(const Params& P, int l, int h, int n, char* lds) {
;     ...
;         for (int j = 0; j < 8; ++j) { const int e = 32 * j + 4 * p; const f32x4 gn = *(const f32x4*)(mnorm + e);
;             const u32x2 mo = *(const u32x2*)(PROJ + row * PW + C_MO + h * 256 + e);
;             const float o0 = hv[j][0] * rs * gn[0] * sigmoidf(bflo(mo.x)), o1 = hv[j][1] * rs * gn[1] * sigmoidf(bfhi(mo.x));
;             const float o2 = hv[j][2] * rs * gn[2] * sigmoidf(bflo(mo.y)), o3 = hv[j][3] * rs * gn[3] * sigmoidf(bfhi(mo.y));
;             u32x2 w; w.x = cvt_pk_bf16(o0, o1); w.y = cvt_pk_bf16(o2, o3);
;             *(u32x2*)(MIX + row * DM + h * 256 + e) = w; }
	v_mul_f32_e32 v22, v22, v26
	v_mul_f32_e32 v25, v29, v25
	v_fma_f32 v26, -v38, v40, 1.0
	v_fmac_f32_e32 v40, v26, v40
	v_div_scale_f32 v26, vcc, 1.0, v37, 1.0
	v_mul_f32_e32 v27, v26, v40
	v_fma_f32 v41, -v38, v27, v26
	v_fmac_f32_e32 v27, v41, v40
	v_fma_f32 v26, -v38, v27, v26
	v_lshlrev_b32_e32 v38, 16, v39
	v_mul_f32_e32 v38, 0xbfb8aa3b, v38
	v_exp_f32_e32 v38, v38
	v_div_fmas_f32 v26, v26, v40, v27
	v_div_fixup_f32 v26, v26, v37, 1.0
	v_mul_f32_e32 v23, v23, v26
	v_add_f32_e32 v27, 1.0, v38
	v_div_scale_f32 v37, s[6:7], v27, v27, 1.0
	v_rcp_f32_e32 v38, v37
	v_cvt_pk_bf16_f32 v22, v22, v23
	s_nop 0
	v_fma_f32 v26, -v37, v38, 1.0
	v_fmac_f32_e32 v38, v26, v38
	v_div_scale_f32 v26, vcc, 1.0, v27, 1.0
	v_mul_f32_e32 v28, v26, v38
	v_fma_f32 v40, -v37, v28, v26
	v_fmac_f32_e32 v28, v40, v38
	v_fma_f32 v26, -v37, v28, v26
	v_and_b32_e32 v37, 0xffff0000, v39
	v_mul_f32_e32 v37, 0xbfb8aa3b, v37
	v_exp_f32_e32 v37, v37
	v_div_fmas_f32 v26, v26, v38, v28
	v_div_fixup_f32 v26, v26, v27, 1.0
	v_mul_f32_e32 v24, v24, v26
	v_add_f32_e32 v27, 1.0, v37
	v_div_scale_f32 v28, s[6:7], v27, v27, 1.0
	v_rcp_f32_e32 v37, v28
	s_nop 0
	v_fma_f32 v26, -v28, v37, 1.0
	v_fmac_f32_e32 v37, v26, v37
	v_div_scale_f32 v26, vcc, 1.0, v27, 1.0
	v_mul_f32_e32 v29, v26, v37
	v_fma_f32 v38, -v28, v29, v26
	v_fmac_f32_e32 v29, v38, v37
	v_fma_f32 v26, -v28, v29, v26
	v_div_fmas_f32 v26, v26, v37, v29
	v_div_fixup_f32 v26, v26, v27, 1.0
	v_mul_f32_e32 v25, v25, v26
	v_cvt_pk_bf16_f32 v23, v24, v25
	flat_store_dwordx2 v[30:31], v[22:23] offset:128
	s_nop 0
	s_nop 1
	v_mov_b32_e32 v26, v200
	v_mov_b32_e32 v27, v201
	v_mov_b32_e32 v22, v220
	v_mov_b32_e32 v23, v221
	v_mov_b32_e32 v24, v222
	v_mov_b32_e32 v25, v223
	v_lshlrev_b32_e32 v28, 16, v26
	v_mul_f32_e32 v28, 0xbfb8aa3b, v28
	v_exp_f32_e32 v28, v28
	v_mul_f32_e32 v18, v18, v22
	v_and_b32_e32 v26, 0xffff0000, v26
	v_mul_f32_e32 v26, 0xbfb8aa3b, v26
	v_add_f32_e32 v22, 1.0, v28
	v_div_scale_f32 v28, s[6:7], v22, v22, 1.0
	v_rcp_f32_e32 v29, v28
	v_div_scale_f32 v37, vcc, 1.0, v22, 1.0
	v_exp_f32_e32 v26, v26
	v_fma_f32 v38, -v28, v29, 1.0
	v_fmac_f32_e32 v29, v38, v29
	v_mul_f32_e32 v38, v37, v29
	v_fma_f32 v39, -v28, v38, v37
	v_fmac_f32_e32 v38, v39, v29
	v_fma_f32 v28, -v28, v38, v37
	v_div_fmas_f32 v28, v28, v29, v38
	v_add_f32_e32 v26, 1.0, v26
	v_div_fixup_f32 v22, v28, v22, 1.0
	v_div_scale_f32 v28, s[6:7], v26, v26, 1.0
	v_rcp_f32_e32 v29, v28
	v_mul_f32_e32 v18, v18, v22
	v_mul_f32_e32 v19, v19, v23
	v_mul_f32_e32 v20, v20, v24
	v_fma_f32 v22, -v28, v29, 1.0
	v_fmac_f32_e32 v29, v22, v29
	v_div_scale_f32 v22, vcc, 1.0, v26, 1.0
	v_mul_f32_e32 v23, v22, v29
	v_fma_f32 v37, -v28, v23, v22
	v_fmac_f32_e32 v23, v37, v29
	v_fma_f32 v22, -v28, v23, v22
	v_lshlrev_b32_e32 v28, 16, v27
	v_mul_f32_e32 v28, 0xbfb8aa3b, v28
	v_exp_f32_e32 v28, v28
	v_div_fmas_f32 v22, v22, v29, v23
	v_div_fixup_f32 v22, v22, v26, 1.0
	v_mul_f32_e32 v19, v19, v22
	v_add_f32_e32 v23, 1.0, v28
	v_div_scale_f32 v26, s[6:7], v23, v23, 1.0
	v_rcp_f32_e32 v28, v26
	v_mul_f32_e32 v21, v21, v25
	v_cvt_pk_bf16_f32 v18, v18, v19
	v_fma_f32 v22, -v26, v28, 1.0
	v_fmac_f32_e32 v28, v22, v28
	v_div_scale_f32 v22, vcc, 1.0, v23, 1.0
	v_mul_f32_e32 v24, v22, v28
	v_fma_f32 v29, -v26, v24, v22
	v_fmac_f32_e32 v24, v29, v28
	v_fma_f32 v22, -v26, v24, v22
	v_and_b32_e32 v26, 0xffff0000, v27
	v_mul_f32_e32 v26, 0xbfb8aa3b, v26
	v_exp_f32_e32 v26, v26
	v_div_fmas_f32 v22, v22, v28, v24
	v_div_fixup_f32 v22, v22, v23, 1.0
	v_mul_f32_e32 v20, v20, v22
	v_add_f32_e32 v23, 1.0, v26
	v_div_scale_f32 v24, s[6:7], v23, v23, 1.0
	v_rcp_f32_e32 v26, v24
	s_nop 0
	v_fma_f32 v22, -v24, v26, 1.0
	v_fmac_f32_e32 v26, v22, v26
	v_div_scale_f32 v22, vcc, 1.0, v23, 1.0
	v_mul_f32_e32 v25, v22, v26
	v_fma_f32 v27, -v24, v25, v22
	v_fmac_f32_e32 v25, v27, v26
	v_fma_f32 v22, -v24, v25, v22
	v_div_fmas_f32 v22, v22, v26, v25
	v_div_fixup_f32 v22, v22, v23, 1.0
	v_mul_f32_e32 v21, v21, v22
	v_cvt_pk_bf16_f32 v19, v20, v21
	flat_store_dwordx2 v[30:31], v[18:19] offset:192
	s_nop 0
	s_nop 1
	v_mov_b32_e32 v22, v202
	v_mov_b32_e32 v23, v203
	v_mov_b32_e32 v18, v224
	v_mov_b32_e32 v19, v225
	v_mov_b32_e32 v20, v226
	v_mov_b32_e32 v21, v227
	v_lshlrev_b32_e32 v24, 16, v22
	v_and_b32_e32 v22, 0xffff0000, v22
	v_mul_f32_e32 v24, 0xbfb8aa3b, v24
	v_mul_f32_e32 v22, 0xbfb8aa3b, v22
	v_exp_f32_e32 v24, v24
	v_exp_f32_e32 v22, v22
	v_mul_f32_e32 v14, v14, v18
	v_mul_f32_e32 v15, v15, v19
	v_add_f32_e32 v18, 1.0, v24
	v_add_f32_e32 v19, 1.0, v22
	v_div_scale_f32 v22, s[6:7], v18, v18, 1.0
	v_rcp_f32_e32 v26, v22
	v_div_scale_f32 v24, vcc, 1.0, v18, 1.0
	v_div_scale_f32 v25, s[6:7], v19, v19, 1.0
	v_fma_f32 v29, -v22, v26, 1.0
	v_fmac_f32_e32 v26, v29, v26
	v_mul_f32_e32 v29, v24, v26
	v_fma_f32 v38, -v22, v29, v24
	v_rcp_f32_e32 v27, v25
	v_fmac_f32_e32 v29, v38, v26
	v_fma_f32 v22, -v22, v29, v24
	v_div_fmas_f32 v22, v22, v26, v29
	v_div_fixup_f32 v18, v22, v18, 1.0
	v_fma_f32 v37, -v25, v27, 1.0
	v_mul_f32_e32 v14, v14, v18
	v_lshlrev_b32_e32 v18, 16, v23
	v_div_scale_f32 v28, s[6:7], 1.0, v19, 1.0
	v_fmac_f32_e32 v27, v37, v27
	v_mul_f32_e32 v18, 0xbfb8aa3b, v18
	v_mul_f32_e32 v37, v28, v27
	v_exp_f32_e32 v18, v18
	v_fma_f32 v39, -v25, v37, v28
	v_fmac_f32_e32 v37, v39, v27
	v_fma_f32 v24, -v25, v37, v28
	s_mov_b64 vcc, s[6:7]
	v_div_fmas_f32 v22, v24, v27, v37
	v_add_f32_e32 v18, 1.0, v18
	v_div_fixup_f32 v19, v22, v19, 1.0
	v_div_scale_f32 v22, s[6:7], v18, v18, 1.0
	v_rcp_f32_e32 v24, v22
	v_mul_f32_e32 v15, v15, v19
	v_mul_f32_e32 v16, v16, v20
	v_mul_f32_e32 v17, v17, v21
	v_fma_f32 v19, -v22, v24, 1.0
	v_fmac_f32_e32 v24, v19, v24
	v_div_scale_f32 v19, vcc, 1.0, v18, 1.0
; __device__ __forceinline__ unsigned cvt_pk_bf16(float lo, float hi) { unsigned r; asm volatile("v_cvt_pk_bf16_f32 %0, %1, %2" : "=v"(r) : "v"(lo), "v"(hi)); return r; }
; __device__ __forceinline__ float bflo(unsigned w) { return __uint_as_float(w << 16); }
; __device__ __forceinline__ float bfhi(unsigned w) { return __uint_as_float(w & 0xffff0000u); }
; __device__ __forceinline__ float sigmoidf(float x) { return 1.f / (1.f + __expf(-x)); }
; __device__ __forceinline__ void mlstm_out_unit(const Params& P, int l, int h, int n, char* lds) {
;     ...
;         for (int j = 0; j < 8; ++j) { const int e = 32 * j + 4 * p; const f32x4 gn = *(const f32x4*)(mnorm + e);
;             const u32x2 mo = *(const u32x2*)(PROJ + row * PW + C_MO + h * 256 + e);
;             const float o0 = hv[j][0] * rs * gn[0] * sigmoidf(bflo(mo.x)), o1 = hv[j][1] * rs * gn[1] * sigmoidf(bfhi(mo.x));
;             const float o2 = hv[j][2] * rs * gn[2] * sigmoidf(bflo(mo.y)), o3 = hv[j][3] * rs * gn[3] * sigmoidf(bfhi(mo.y));
;             u32x2 w; w.x = cvt_pk_bf16(o0, o1); w.y = cvt_pk_bf16(o2, o3);
;             *(u32x2*)(MIX + row * DM + h * 256 + e) = w; }
	v_mul_f32_e32 v20, v19, v24
	v_fma_f32 v25, -v22, v20, v19
	v_fmac_f32_e32 v20, v25, v24
	v_fma_f32 v19, -v22, v20, v19
	v_and_b32_e32 v22, 0xffff0000, v23
	v_mul_f32_e32 v22, 0xbfb8aa3b, v22
	v_exp_f32_e32 v22, v22
	v_div_fmas_f32 v19, v19, v24, v20
	v_div_fixup_f32 v18, v19, v18, 1.0
	v_mul_f32_e32 v16, v16, v18
	v_add_f32_e32 v19, 1.0, v22
	v_div_scale_f32 v20, s[6:7], v19, v19, 1.0
	v_rcp_f32_e32 v22, v20
	v_cvt_pk_bf16_f32 v14, v14, v15
	s_nop 0
	v_fma_f32 v18, -v20, v22, 1.0
	v_fmac_f32_e32 v22, v18, v22
	v_div_scale_f32 v18, vcc, 1.0, v19, 1.0
	v_mul_f32_e32 v21, v18, v22
	v_fma_f32 v23, -v20, v21, v18
	v_fmac_f32_e32 v21, v23, v22
	v_fma_f32 v18, -v20, v21, v18
	v_div_fmas_f32 v18, v18, v22, v21
	v_div_fixup_f32 v18, v18, v19, 1.0
	v_mul_f32_e32 v17, v17, v18
	v_cvt_pk_bf16_f32 v15, v16, v17
	flat_store_dwordx2 v[30:31], v[14:15] offset:256
	s_nop 0
	s_nop 1
	v_mov_b32_e32 v14, v228
	v_mov_b32_e32 v15, v229
	v_mov_b32_e32 v16, v230
	v_mov_b32_e32 v17, v231
	v_mov_b32_e32 v18, v204
	v_mov_b32_e32 v19, v205
	v_mul_f32_e32 v6, v6, v14
	v_lshlrev_b32_e32 v14, 16, v18
	v_mul_f32_e32 v7, v7, v15
	v_and_b32_e32 v15, 0xffff0000, v18
	v_lshlrev_b32_e32 v18, 16, v19
	v_mul_f32_e32 v14, 0xbfb8aa3b, v14
	v_mul_f32_e32 v15, 0xbfb8aa3b, v15
	v_mul_f32_e32 v18, 0xbfb8aa3b, v18
	v_exp_f32_e32 v14, v14
	v_exp_f32_e32 v15, v15
	v_exp_f32_e32 v18, v18
	v_mul_f32_e32 v8, v8, v16
	v_add_f32_e32 v14, 1.0, v14
	v_add_f32_e32 v15, 1.0, v15
	v_add_f32_e32 v16, 1.0, v18
	v_div_scale_f32 v18, s[6:7], v14, v14, 1.0
	v_div_scale_f32 v21, s[6:7], v15, v15, 1.0
	v_rcp_f32_e32 v24, v18
	v_rcp_f32_e32 v25, v21
	v_div_scale_f32 v20, vcc, 1.0, v14, 1.0
	v_fma_f32 v28, -v18, v24, 1.0
	v_fma_f32 v29, -v21, v25, 1.0
	v_fmac_f32_e32 v24, v28, v24
	v_div_scale_f32 v22, s[6:7], 1.0, v15, 1.0
	v_fmac_f32_e32 v25, v29, v25
	v_mul_f32_e32 v28, v20, v24
	v_div_scale_f32 v23, s[8:9], v16, v16, 1.0
	v_mul_f32_e32 v29, v22, v25
	v_fma_f32 v38, -v18, v28, v20
	v_rcp_f32_e32 v26, v23
	v_fma_f32 v39, -v21, v29, v22
	v_fmac_f32_e32 v28, v38, v24
	v_fmac_f32_e32 v29, v39, v25
	v_fma_f32 v18, -v18, v28, v20
	v_fma_f32 v20, -v21, v29, v22
	v_div_fmas_f32 v18, v18, v24, v28
	s_mov_b64 vcc, s[6:7]
	v_div_fixup_f32 v14, v18, v14, 1.0
	v_div_fmas_f32 v18, v20, v25, v29
	v_fma_f32 v37, -v23, v26, 1.0
	v_mul_f32_e32 v6, v6, v14
	v_div_fixup_f32 v14, v18, v15, 1.0
	v_and_b32_e32 v15, 0xffff0000, v19
	v_div_scale_f32 v27, s[8:9], 1.0, v16, 1.0
	v_fmac_f32_e32 v26, v37, v26
	v_mul_f32_e32 v15, 0xbfb8aa3b, v15
	v_mul_f32_e32 v37, v27, v26
	v_exp_f32_e32 v15, v15
	v_mul_f32_e32 v7, v7, v14
	v_fma_f32 v14, -v23, v37, v27
	v_fmac_f32_e32 v37, v14, v26
	v_fma_f32 v14, -v23, v37, v27
	s_mov_b64 vcc, s[8:9]
	v_div_fmas_f32 v14, v14, v26, v37
	v_add_f32_e32 v15, 1.0, v15
	v_div_fixup_f32 v14, v14, v16, 1.0
	v_div_scale_f32 v16, s[6:7], v15, v15, 1.0
	v_rcp_f32_e32 v18, v16
	v_mul_f32_e32 v8, v8, v14
	v_mul_f32_e32 v9, v9, v17
	v_cvt_pk_bf16_f32 v6, v6, v7
	v_fma_f32 v14, -v16, v18, 1.0
	v_fmac_f32_e32 v18, v14, v18
	v_div_scale_f32 v14, vcc, 1.0, v15, 1.0
	v_mul_f32_e32 v17, v14, v18
	v_fma_f32 v19, -v16, v17, v14
	v_fmac_f32_e32 v17, v19, v18
	v_fma_f32 v14, -v16, v17, v14
	v_div_fmas_f32 v14, v14, v18, v17
	v_div_fixup_f32 v14, v14, v15, 1.0
	v_mul_f32_e32 v9, v9, v14
	v_cvt_pk_bf16_f32 v7, v8, v9
	flat_store_dwordx2 v[30:31], v[6:7] offset:320
	s_nop 0
	s_nop 1
	v_mov_b32_e32 v6, v232
	v_mov_b32_e32 v7, v233
	v_mov_b32_e32 v8, v234
	v_mov_b32_e32 v9, v235
	v_mov_b32_e32 v14, v206
	v_mov_b32_e32 v15, v207
	v_mul_f32_e32 v6, v10, v6
	v_lshlrev_b32_e32 v10, 16, v14
	v_mul_f32_e32 v7, v11, v7
	v_and_b32_e32 v11, 0xffff0000, v14
	v_mul_f32_e32 v10, 0xbfb8aa3b, v10
	v_mul_f32_e32 v8, v12, v8
	v_lshlrev_b32_e32 v12, 16, v15
	v_mul_f32_e32 v9, v13, v9
	v_and_b32_e32 v13, 0xffff0000, v15
	v_mul_f32_e32 v11, 0xbfb8aa3b, v11
	v_exp_f32_e32 v10, v10
	v_mul_f32_e32 v12, 0xbfb8aa3b, v12
	v_mul_f32_e32 v13, 0xbfb8aa3b, v13
	v_exp_f32_e32 v11, v11
	v_exp_f32_e32 v12, v12
	v_exp_f32_e32 v13, v13
	v_add_f32_e32 v10, 1.0, v10
	v_add_f32_e32 v11, 1.0, v11
	v_div_scale_f32 v14, s[6:7], v10, v10, 1.0
	v_add_f32_e32 v12, 1.0, v12
	v_add_f32_e32 v13, 1.0, v13
; __device__ __forceinline__ unsigned cvt_pk_bf16(float lo, float hi) { unsigned r; asm volatile("v_cvt_pk_bf16_f32 %0, %1, %2" : "=v"(r) : "v"(lo), "v"(hi)); return r; }
; __device__ __forceinline__ float bflo(unsigned w) { return __uint_as_float(w << 16); }
; __device__ __forceinline__ float bfhi(unsigned w) { return __uint_as_float(w & 0xffff0000u); }
; __device__ __forceinline__ float sigmoidf(float x) { return 1.f / (1.f + __expf(-x)); }
; __device__ __forceinline__ void mlstm_out_unit(const Params& P, int l, int h, int n, char* lds) {
;     ...
;         for (int j = 0; j < 8; ++j) { const int e = 32 * j + 4 * p; const f32x4 gn = *(const f32x4*)(mnorm + e);
;             const u32x2 mo = *(const u32x2*)(PROJ + row * PW + C_MO + h * 256 + e);
;             const float o0 = hv[j][0] * rs * gn[0] * sigmoidf(bflo(mo.x)), o1 = hv[j][1] * rs * gn[1] * sigmoidf(bfhi(mo.x));
;             const float o2 = hv[j][2] * rs * gn[2] * sigmoidf(bflo(mo.y)), o3 = hv[j][3] * rs * gn[3] * sigmoidf(bfhi(mo.y));
;             u32x2 w; w.x = cvt_pk_bf16(o0, o1); w.y = cvt_pk_bf16(o2, o3);
;             *(u32x2*)(MIX + row * DM + h * 256 + e) = w; }
;     }
;     __syncthreads();
	v_div_scale_f32 v16, s[6:7], v11, v11, 1.0
	v_rcp_f32_e32 v21, v14
	v_div_scale_f32 v18, s[8:9], v12, v12, 1.0
	v_div_scale_f32 v20, s[10:11], v13, v13, 1.0
	v_rcp_f32_e32 v22, v16
	v_rcp_f32_e32 v23, v18
	v_rcp_f32_e32 v24, v20
	v_fma_f32 v25, -v14, v21, 1.0
	v_div_scale_f32 v15, vcc, 1.0, v10, 1.0
	v_fma_f32 v26, -v16, v22, 1.0
	v_fmac_f32_e32 v21, v25, v21
	v_div_scale_f32 v17, s[6:7], 1.0, v11, 1.0
	v_fma_f32 v27, -v18, v23, 1.0
	v_fma_f32 v28, -v20, v24, 1.0
	v_fmac_f32_e32 v22, v26, v22
	v_mul_f32_e32 v25, v15, v21
	v_div_scale_f32 v19, s[8:9], 1.0, v12, 1.0
	v_fmac_f32_e32 v23, v27, v23
	v_fmac_f32_e32 v24, v28, v24
	v_mul_f32_e32 v26, v17, v22
	v_fma_f32 v28, -v14, v25, v15
	v_mul_f32_e32 v27, v19, v23
	v_fma_f32 v29, -v16, v26, v17
	v_fmac_f32_e32 v25, v28, v21
	v_fma_f32 v37, -v18, v27, v19
	v_fmac_f32_e32 v26, v29, v22
	v_fma_f32 v14, -v14, v25, v15
	v_fmac_f32_e32 v27, v37, v23
	v_fma_f32 v15, -v16, v26, v17
	v_div_fmas_f32 v14, v14, v21, v25
	s_mov_b64 vcc, s[6:7]
	v_fma_f32 v16, -v18, v27, v19
	v_div_fixup_f32 v10, v14, v10, 1.0
	v_div_fmas_f32 v14, v15, v22, v26
	s_mov_b64 vcc, s[8:9]
	v_mul_f32_e32 v6, v6, v10
	v_div_fixup_f32 v10, v14, v11, 1.0
	v_div_fmas_f32 v11, v16, v23, v27
	v_mul_f32_e32 v7, v7, v10
	v_div_fixup_f32 v10, v11, v12, 1.0
	v_mul_f32_e32 v8, v8, v10
	v_div_scale_f32 v10, vcc, 1.0, v13, 1.0
	v_mul_f32_e32 v11, v10, v24
	v_fma_f32 v12, -v20, v11, v10
	v_fmac_f32_e32 v11, v12, v24
	v_fma_f32 v10, -v20, v11, v10
	v_div_fmas_f32 v10, v10, v24, v11
	v_div_fixup_f32 v10, v10, v13, 1.0
	v_mul_f32_e32 v9, v9, v10
	v_cvt_pk_bf16_f32 v6, v6, v7
	v_cvt_pk_bf16_f32 v7, v8, v9
	flat_store_dwordx2 v[30:31], v[6:7] offset:384
	s_nop 0
	s_nop 1
	v_mov_b32_e32 v6, v236
	v_mov_b32_e32 v7, v237
	v_mov_b32_e32 v8, v238
	v_mov_b32_e32 v9, v239
	v_mov_b32_e32 v10, v208
	v_mov_b32_e32 v11, v209
	v_mul_f32_e32 v2, v2, v6
	v_lshlrev_b32_e32 v6, 16, v10
	v_mul_f32_e32 v3, v3, v7
	v_and_b32_e32 v7, 0xffff0000, v10
	v_mul_f32_e32 v6, 0xbfb8aa3b, v6
	v_mul_f32_e32 v4, v4, v8
	v_lshlrev_b32_e32 v8, 16, v11
	v_mul_f32_e32 v7, 0xbfb8aa3b, v7
	v_exp_f32_e32 v6, v6
	v_mul_f32_e32 v5, v5, v9
	v_and_b32_e32 v9, 0xffff0000, v11
	v_mul_f32_e32 v8, 0xbfb8aa3b, v8
	v_exp_f32_e32 v7, v7
	v_mul_f32_e32 v9, 0xbfb8aa3b, v9
	v_exp_f32_e32 v8, v8
	v_exp_f32_e32 v9, v9
	v_add_f32_e32 v6, 1.0, v6
	v_add_f32_e32 v7, 1.0, v7
	v_div_scale_f32 v10, s[6:7], v6, v6, 1.0
	v_add_f32_e32 v8, 1.0, v8
	v_div_scale_f32 v12, s[6:7], v7, v7, 1.0
	v_rcp_f32_e32 v18, v10
	v_add_f32_e32 v9, 1.0, v9
	v_div_scale_f32 v14, s[8:9], v8, v8, 1.0
	v_rcp_f32_e32 v19, v12
	v_div_scale_f32 v16, s[10:11], v9, v9, 1.0
	v_rcp_f32_e32 v20, v14
	v_rcp_f32_e32 v21, v16
	v_fma_f32 v22, -v10, v18, 1.0
	v_div_scale_f32 v11, vcc, 1.0, v6, 1.0
	v_fma_f32 v23, -v12, v19, 1.0
	v_fmac_f32_e32 v18, v22, v18
	v_div_scale_f32 v13, s[6:7], 1.0, v7, 1.0
	v_fma_f32 v24, -v14, v20, 1.0
	v_fmac_f32_e32 v19, v23, v19
	v_mul_f32_e32 v22, v11, v18
	v_div_scale_f32 v15, s[8:9], 1.0, v8, 1.0
	v_fma_f32 v25, -v16, v21, 1.0
	v_fmac_f32_e32 v20, v24, v20
	v_mul_f32_e32 v23, v13, v19
	v_fma_f32 v26, -v10, v22, v11
	v_div_scale_f32 v17, s[10:11], 1.0, v9, 1.0
	v_fmac_f32_e32 v21, v25, v21
	v_mul_f32_e32 v24, v15, v20
	v_fma_f32 v27, -v12, v23, v13
	v_fmac_f32_e32 v22, v26, v18
	v_mul_f32_e32 v25, v17, v21
	v_fma_f32 v28, -v14, v24, v15
	v_fmac_f32_e32 v23, v27, v19
	v_fma_f32 v10, -v10, v22, v11
	v_fma_f32 v29, -v16, v25, v17
	v_fmac_f32_e32 v24, v28, v20
	v_fma_f32 v11, -v12, v23, v13
	v_div_fmas_f32 v10, v10, v18, v22
	s_mov_b64 vcc, s[6:7]
	v_fmac_f32_e32 v25, v29, v21
	v_fma_f32 v12, -v14, v24, v15
	v_div_fixup_f32 v6, v10, v6, 1.0
	v_div_fmas_f32 v10, v11, v19, v23
	s_mov_b64 vcc, s[8:9]
	v_fma_f32 v13, -v16, v25, v17
	v_mul_f32_e32 v2, v2, v6
	v_div_fixup_f32 v6, v10, v7, 1.0
	v_div_fmas_f32 v7, v12, v20, v24
	s_mov_b64 vcc, s[10:11]
	v_mul_f32_e32 v3, v3, v6
	v_div_fixup_f32 v6, v7, v8, 1.0
	v_div_fmas_f32 v7, v13, v21, v25
	v_mul_f32_e32 v4, v4, v6
	v_div_fixup_f32 v6, v7, v9, 1.0
	v_cvt_pk_bf16_f32 v2, v2, v3
	v_mul_f32_e32 v3, v5, v6
	s_mov_b64 s[6:7], 0
	v_cvt_pk_bf16_f32 v3, v4, v3
	flat_store_dwordx2 v[30:31], v[2:3] offset:448
	s_waitcnt lgkmcnt(0)
	s_barrier

; __device__ __forceinline__ unsigned cvt_pk_bf16(float lo, float hi) { unsigned r; asm volatile("v_cvt_pk_bf16_f32 %0, %1, %2" : "=v"(r) : "v"(lo), "v"(hi)); return r; }
;     __device__ __forceinline__ void operator()(const pg8::f32x4 (&acc)[2][2][4][2], const pg8::Unit& u, int wr, int wc, int fr, int fq) const {
;         const int row0 = NMETA + u.pm * 256 + wr * 64 + fr, col0 = u.pn * 256 + wc * 32 + 8 * fq;
; #pragma unroll
;         for (int ai = 0; ai < 2; ++ai)
; #pragma unroll
;             for (int m = 0; m < 4; ++m) { bf16_t* rowp = O + (size_t)(row0 + ai * 128 + m * 16) * DFF + col0;
; #pragma unroll
;                 for (int bj = 0; bj < 2; ++bj) { pg8::f32x4 v0 = acc[ai][bj][m][0], v1 = acc[ai][bj][m][1];
; #pragma unroll
;                     for (int i = 0; i < 4; ++i) { const float a = fmaxf(v0[i], 0.f), b = fmaxf(v1[i], 0.f); v0[i] = a * a; v1[i] = b * b; }
;                     u32x4 w; w.x = cvt_pk_bf16(v0[0], v0[1]); w.y = cvt_pk_bf16(v0[2], v0[3]); w.z = cvt_pk_bf16(v1[0], v1[1]); w.w = cvt_pk_bf16(v1[2], v1[3]);
;                     *(u32x4*)(rowp + bj * 128) = w; } }
.LBB0_2721:
	v_lshl_add_u32 v154, s44, 8, v1
	v_max_f32_e32 v122, v122, v122
	v_ashrrev_i32_e32 v155, 31, v154
	v_max_f32_e32 v122, 0, v122
	v_max_f32_e32 v123, v123, v123
	v_max_f32_e32 v124, v124, v124
	v_lshl_or_b32 v146, s70, 8, v148
	v_lshlrev_b64 v[156:157], 14, v[154:155]
	v_mul_f32_e32 v155, v122, v122
	v_max_f32_e32 v122, v127, v127
	v_max_f32_e32 v123, 0, v123
	v_max_f32_e32 v124, 0, v124
	v_ashrrev_i32_e32 v147, 31, v146
	v_max_f32_e32 v126, v126, v126
	v_max_f32_e32 v122, 0, v122
	v_mul_f32_e32 v127, v123, v123
	v_max_f32_e32 v123, v128, v128
	v_mul_f32_e32 v128, v124, v124
	v_max_f32_e32 v124, v129, v129
	v_max_f32_e32 v125, v125, v125
	v_lshl_add_u64 v[156:157], s[12:13], 0, v[156:157]
	v_lshlrev_b64 v[158:159], 1, v[146:147]
	v_max_f32_e32 v126, 0, v126
	v_mul_f32_e32 v122, v122, v122
	v_max_f32_e32 v123, 0, v123
	v_max_f32_e32 v124, 0, v124
	v_max_f32_e32 v125, 0, v125
	v_max_f32_e32 v114, v114, v114
	v_max_f32_e32 v115, v115, v115
	v_max_f32_e32 v116, v116, v116
	v_lshl_add_u64 v[146:147], v[156:157], 0, v[158:159]
	v_mul_f32_e32 v126, v126, v126
	v_mul_f32_e32 v123, v123, v123
	v_mul_f32_e32 v124, v124, v124
	v_mul_f32_e32 v125, v125, v125
	v_cvt_pk_bf16_f32 v122, v126, v122
	v_max_f32_e32 v114, 0, v114
	v_max_f32_e32 v115, 0, v115
	v_max_f32_e32 v116, 0, v116
	v_cvt_pk_bf16_f32 v123, v123, v124
	v_cvt_pk_bf16_f32 v124, v155, v127
	v_cvt_pk_bf16_f32 v125, v128, v125
	flat_store_dwordx4 v[146:147], v[122:125] nt
	v_max_f32_e32 v118, v118, v118
	v_max_f32_e32 v117, v117, v117
	v_mul_f32_e32 v122, v114, v114
	v_max_f32_e32 v114, v119, v119
	v_mul_f32_e32 v119, v115, v115
	v_max_f32_e32 v115, v120, v120
	v_mul_f32_e32 v120, v116, v116
	v_max_f32_e32 v116, v121, v121
	v_max_f32_e32 v114, 0, v114
	v_max_f32_e32 v115, 0, v115
	v_max_f32_e32 v116, 0, v116
	v_max_f32_e32 v118, 0, v118
	v_mul_f32_e32 v114, v114, v114
	v_mul_f32_e32 v115, v115, v115
	v_max_f32_e32 v117, 0, v117
	v_mul_f32_e32 v116, v116, v116
	v_max_f32_e32 v106, v106, v106
	v_mul_f32_e32 v118, v118, v118
	v_mul_f32_e32 v117, v117, v117
	v_cvt_pk_bf16_f32 v114, v118, v114
	v_cvt_pk_bf16_f32 v115, v115, v116
	v_cvt_pk_bf16_f32 v116, v122, v119
	v_max_f32_e32 v106, 0, v106
	v_max_f32_e32 v107, v107, v107
	v_max_f32_e32 v108, v108, v108
	v_cvt_pk_bf16_f32 v117, v120, v117
	flat_store_dwordx4 v[146:147], v[114:117] offset:256 nt
	v_max_f32_e32 v110, v110, v110
	v_max_f32_e32 v107, 0, v107
	v_mul_f32_e32 v116, v106, v106
	v_max_f32_e32 v106, v111, v111
	v_max_f32_e32 v108, 0, v108
	v_max_f32_e32 v110, 0, v110
	v_max_f32_e32 v106, 0, v106
	v_mul_f32_e32 v111, v107, v107
	v_max_f32_e32 v107, v112, v112
	v_mul_f32_e32 v112, v108, v108
	v_max_f32_e32 v108, v113, v113
	v_mul_f32_e32 v110, v110, v110
	v_mul_f32_e32 v106, v106, v106
	v_max_f32_e32 v107, 0, v107
	v_max_f32_e32 v108, 0, v108
	v_max_f32_e32 v109, v109, v109
	v_mul_f32_e32 v107, v107, v107
	v_max_f32_e32 v109, 0, v109
	v_mul_f32_e32 v108, v108, v108
	v_cvt_pk_bf16_f32 v106, v110, v106
	v_add_co_u32_e32 v110, vcc, s62, v146
	v_max_f32_e32 v98, v98, v98
	v_mul_f32_e32 v109, v109, v109
	v_cvt_pk_bf16_f32 v107, v107, v108
	v_cvt_pk_bf16_f32 v108, v116, v111
	v_addc_co_u32_e32 v111, vcc, 0, v147, vcc
	v_max_f32_e32 v98, 0, v98
	v_max_f32_e32 v99, v99, v99
	v_max_f32_e32 v100, v100, v100
	v_cvt_pk_bf16_f32 v109, v112, v109
	flat_store_dwordx4 v[110:111], v[106:109] nt
	v_max_f32_e32 v99, 0, v99
	v_max_f32_e32 v100, 0, v100
	v_mul_f32_e32 v106, v98, v98
	v_max_f32_e32 v98, v103, v103
	v_max_f32_e32 v102, v102, v102
	v_max_f32_e32 v98, 0, v98
	v_mul_f32_e32 v103, v99, v99
	v_max_f32_e32 v99, v104, v104
	v_mul_f32_e32 v104, v100, v100
	v_max_f32_e32 v100, v105, v105
	v_max_f32_e32 v101, v101, v101
	v_max_f32_e32 v102, 0, v102
	v_mul_f32_e32 v98, v98, v98
	v_max_f32_e32 v99, 0, v99
	v_max_f32_e32 v100, 0, v100
	v_max_f32_e32 v101, 0, v101
	v_lshl_add_u64 v[114:115], v[146:147], 0, s[20:21]
	v_mul_f32_e32 v102, v102, v102
	v_mul_f32_e32 v99, v99, v99
	v_mul_f32_e32 v100, v100, v100
	v_mul_f32_e32 v101, v101, v101
	v_cvt_pk_bf16_f32 v98, v102, v98
	v_max_f32_e32 v90, v90, v90
	v_cvt_pk_bf16_f32 v99, v99, v100
	v_cvt_pk_bf16_f32 v100, v106, v103
	v_cvt_pk_bf16_f32 v101, v104, v101
	flat_store_dwordx4 v[114:115], v[98:101] offset:256 nt
	v_max_f32_e32 v90, 0, v90
	v_max_f32_e32 v91, v91, v91
	v_or_b32_e32 v98, 32, v154
	v_max_f32_e32 v92, v92, v92
	v_ashrrev_i32_e32 v99, 31, v98
	v_mul_f32_e32 v100, v90, v90
	v_max_f32_e32 v90, v95, v95
	v_max_f32_e32 v91, 0, v91
	v_max_f32_e32 v92, 0, v92
	v_lshlrev_b64 v[98:99], 14, v[98:99]
	v_max_f32_e32 v94, v94, v94
	v_max_f32_e32 v90, 0, v90
	v_mul_f32_e32 v95, v91, v91
	v_max_f32_e32 v91, v96, v96
	v_mul_f32_e32 v96, v92, v92
	v_max_f32_e32 v92, v97, v97
	v_max_f32_e32 v93, v93, v93
	v_lshl_add_u64 v[98:99], s[12:13], 0, v[98:99]
	v_max_f32_e32 v94, 0, v94
	v_mul_f32_e32 v90, v90, v90
	v_max_f32_e32 v91, 0, v91
	v_max_f32_e32 v92, 0, v92
	v_max_f32_e32 v93, 0, v93
	v_max_f32_e32 v82, v82, v82
	v_max_f32_e32 v83, v83, v83
	v_max_f32_e32 v84, v84, v84
	v_lshl_add_u64 v[98:99], v[98:99], 0, v[158:159]
	v_mul_f32_e32 v94, v94, v94
	v_mul_f32_e32 v91, v91, v91
	v_mul_f32_e32 v92, v92, v92
	v_mul_f32_e32 v93, v93, v93
	v_cvt_pk_bf16_f32 v90, v94, v90
	v_max_f32_e32 v82, 0, v82
	v_max_f32_e32 v83, 0, v83
	v_max_f32_e32 v84, 0, v84
	v_cvt_pk_bf16_f32 v91, v91, v92
	v_cvt_pk_bf16_f32 v92, v100, v95
	v_cvt_pk_bf16_f32 v93, v96, v93
	flat_store_dwordx4 v[98:99], v[90:93] nt
	v_max_f32_e32 v86, v86, v86
	v_max_f32_e32 v85, v85, v85
	v_mul_f32_e32 v90, v82, v82
	v_max_f32_e32 v82, v87, v87
	v_mul_f32_e32 v87, v83, v83
	v_max_f32_e32 v83, v88, v88
	v_mul_f32_e32 v88, v84, v84
	v_max_f32_e32 v84, v89, v89
; __device__ __forceinline__ unsigned cvt_pk_bf16(float lo, float hi) { unsigned r; asm volatile("v_cvt_pk_bf16_f32 %0, %1, %2" : "=v"(r) : "v"(lo), "v"(hi)); return r; }
;     __device__ __forceinline__ void operator()(const pg8::f32x4 (&acc)[2][2][4][2], const pg8::Unit& u, int wr, int wc, int fr, int fq) const {
;         const int row0 = NMETA + u.pm * 256 + wr * 64 + fr, col0 = u.pn * 256 + wc * 32 + 8 * fq;
; #pragma unroll
;         for (int ai = 0; ai < 2; ++ai)
; #pragma unroll
;             for (int m = 0; m < 4; ++m) { bf16_t* rowp = O + (size_t)(row0 + ai * 128 + m * 16) * DFF + col0;
; #pragma unroll
;                 for (int bj = 0; bj < 2; ++bj) { pg8::f32x4 v0 = acc[ai][bj][m][0], v1 = acc[ai][bj][m][1];
; #pragma unroll
;                     for (int i = 0; i < 4; ++i) { const float a = fmaxf(v0[i], 0.f), b = fmaxf(v1[i], 0.f); v0[i] = a * a; v1[i] = b * b; }
;                     u32x4 w; w.x = cvt_pk_bf16(v0[0], v0[1]); w.y = cvt_pk_bf16(v0[2], v0[3]); w.z = cvt_pk_bf16(v1[0], v1[1]); w.w = cvt_pk_bf16(v1[2], v1[3]);
;                     *(u32x4*)(rowp + bj * 128) = w; } }
	v_max_f32_e32 v82, 0, v82
	v_max_f32_e32 v83, 0, v83
	v_max_f32_e32 v84, 0, v84
	v_max_f32_e32 v86, 0, v86
	v_mul_f32_e32 v82, v82, v82
	v_mul_f32_e32 v83, v83, v83
	v_max_f32_e32 v85, 0, v85
	v_mul_f32_e32 v84, v84, v84
	v_max_f32_e32 v74, v74, v74
	v_mul_f32_e32 v86, v86, v86
	v_mul_f32_e32 v85, v85, v85
	v_cvt_pk_bf16_f32 v82, v86, v82
	v_cvt_pk_bf16_f32 v83, v83, v84
	v_cvt_pk_bf16_f32 v84, v90, v87
	v_max_f32_e32 v74, 0, v74
	v_max_f32_e32 v75, v75, v75
	v_max_f32_e32 v76, v76, v76
	v_cvt_pk_bf16_f32 v85, v88, v85
	flat_store_dwordx4 v[98:99], v[82:85] offset:256 nt
	v_max_f32_e32 v78, v78, v78
	v_max_f32_e32 v75, 0, v75
	v_mul_f32_e32 v84, v74, v74
	v_max_f32_e32 v74, v79, v79
	v_max_f32_e32 v76, 0, v76
	v_max_f32_e32 v78, 0, v78
	v_max_f32_e32 v74, 0, v74
	v_mul_f32_e32 v79, v75, v75
	v_max_f32_e32 v75, v80, v80
	v_mul_f32_e32 v80, v76, v76
	v_max_f32_e32 v76, v81, v81
	v_mul_f32_e32 v78, v78, v78
	v_mul_f32_e32 v74, v74, v74
	v_max_f32_e32 v75, 0, v75
	v_max_f32_e32 v76, 0, v76
	v_max_f32_e32 v77, v77, v77
	v_mul_f32_e32 v75, v75, v75
	v_max_f32_e32 v77, 0, v77
	v_mul_f32_e32 v76, v76, v76
	v_cvt_pk_bf16_f32 v74, v78, v74
	v_add_co_u32_e32 v78, vcc, s63, v146
	v_max_f32_e32 v66, v66, v66
	v_max_f32_e32 v67, v67, v67
	v_max_f32_e32 v68, v68, v68
	v_mul_f32_e32 v77, v77, v77
	v_cvt_pk_bf16_f32 v75, v75, v76
	v_cvt_pk_bf16_f32 v76, v84, v79
	v_addc_co_u32_e32 v79, vcc, 0, v147, vcc
	v_max_f32_e32 v66, 0, v66
	v_max_f32_e32 v67, 0, v67
	v_max_f32_e32 v68, 0, v68
	v_cvt_pk_bf16_f32 v77, v80, v77
	flat_store_dwordx4 v[78:79], v[74:77] nt
	v_max_f32_e32 v70, v70, v70
	v_max_f32_e32 v69, v69, v69
	v_mul_f32_e32 v74, v66, v66
	v_max_f32_e32 v66, v71, v71
	v_mul_f32_e32 v71, v67, v67
	v_max_f32_e32 v67, v72, v72
	v_mul_f32_e32 v72, v68, v68
	v_max_f32_e32 v68, v73, v73
	v_max_f32_e32 v66, 0, v66
	v_max_f32_e32 v67, 0, v67
	v_max_f32_e32 v68, 0, v68
	v_max_f32_e32 v70, 0, v70
	v_mul_f32_e32 v66, v66, v66
	v_mul_f32_e32 v67, v67, v67
	v_max_f32_e32 v69, 0, v69
	v_mul_f32_e32 v68, v68, v68
	v_max_f32_e32 v58, v58, v58
	v_lshl_add_u64 v[82:83], v[146:147], 0, s[22:23]
	v_mul_f32_e32 v70, v70, v70
	v_mul_f32_e32 v69, v69, v69
	v_cvt_pk_bf16_f32 v66, v70, v66
	v_cvt_pk_bf16_f32 v67, v67, v68
	v_cvt_pk_bf16_f32 v68, v74, v71
	v_max_f32_e32 v58, 0, v58
	v_max_f32_e32 v59, v59, v59
	v_max_f32_e32 v60, v60, v60
	v_cvt_pk_bf16_f32 v69, v72, v69
	flat_store_dwordx4 v[82:83], v[66:69] offset:256 nt
	v_max_f32_e32 v62, v62, v62
	v_max_f32_e32 v59, 0, v59
	v_mul_f32_e32 v68, v58, v58
	v_max_f32_e32 v58, v63, v63
	v_max_f32_e32 v60, 0, v60
	v_max_f32_e32 v62, 0, v62
	v_max_f32_e32 v58, 0, v58
	v_mul_f32_e32 v63, v59, v59
	v_max_f32_e32 v59, v64, v64
	v_mul_f32_e32 v64, v60, v60
	v_max_f32_e32 v60, v65, v65
	v_mul_f32_e32 v62, v62, v62
	v_mul_f32_e32 v58, v58, v58
	v_max_f32_e32 v59, 0, v59
	v_max_f32_e32 v60, 0, v60
	v_max_f32_e32 v61, v61, v61
	v_mul_f32_e32 v59, v59, v59
	v_max_f32_e32 v61, 0, v61
	v_mul_f32_e32 v60, v60, v60
	v_cvt_pk_bf16_f32 v58, v62, v58
	v_add_co_u32_e32 v62, vcc, s64, v146
	v_max_f32_e32 v50, v50, v50
	v_max_f32_e32 v51, v51, v51
	v_max_f32_e32 v52, v52, v52
	v_mul_f32_e32 v61, v61, v61
	v_cvt_pk_bf16_f32 v59, v59, v60
	v_cvt_pk_bf16_f32 v60, v68, v63
	v_addc_co_u32_e32 v63, vcc, 0, v147, vcc
	v_max_f32_e32 v50, 0, v50
	v_max_f32_e32 v51, 0, v51
	v_max_f32_e32 v52, 0, v52
	v_cvt_pk_bf16_f32 v61, v64, v61
	flat_store_dwordx4 v[62:63], v[58:61] nt
	v_max_f32_e32 v54, v54, v54
	v_max_f32_e32 v53, v53, v53
	v_mul_f32_e32 v58, v50, v50
	v_max_f32_e32 v50, v55, v55
	v_mul_f32_e32 v55, v51, v51
	v_max_f32_e32 v51, v56, v56
	v_mul_f32_e32 v56, v52, v52
	v_max_f32_e32 v52, v57, v57
	v_max_f32_e32 v50, 0, v50
	v_max_f32_e32 v51, 0, v51
	v_max_f32_e32 v52, 0, v52
	v_max_f32_e32 v54, 0, v54
	v_mul_f32_e32 v50, v50, v50
	v_mul_f32_e32 v51, v51, v51
	v_max_f32_e32 v53, 0, v53
	v_mul_f32_e32 v52, v52, v52
	v_max_f32_e32 v42, v42, v42
	v_lshl_add_u64 v[66:67], v[146:147], 0, s[24:25]
	v_mul_f32_e32 v54, v54, v54
	v_mul_f32_e32 v53, v53, v53
	v_cvt_pk_bf16_f32 v50, v54, v50
	v_cvt_pk_bf16_f32 v51, v51, v52
	v_cvt_pk_bf16_f32 v52, v58, v55
	v_max_f32_e32 v42, 0, v42
	v_max_f32_e32 v43, v43, v43
	v_max_f32_e32 v44, v44, v44
	v_cvt_pk_bf16_f32 v53, v56, v53
	flat_store_dwordx4 v[66:67], v[50:53] offset:256 nt
	v_max_f32_e32 v46, v46, v46
	v_max_f32_e32 v43, 0, v43
	v_mul_f32_e32 v52, v42, v42
	v_max_f32_e32 v42, v47, v47
	v_max_f32_e32 v44, 0, v44
	v_max_f32_e32 v46, 0, v46
	v_max_f32_e32 v42, 0, v42
	v_mul_f32_e32 v47, v43, v43
	v_max_f32_e32 v43, v48, v48
	v_mul_f32_e32 v48, v44, v44
	v_max_f32_e32 v44, v49, v49
	v_mul_f32_e32 v46, v46, v46
	v_mul_f32_e32 v42, v42, v42
	v_max_f32_e32 v43, 0, v43
	v_max_f32_e32 v44, 0, v44
	v_max_f32_e32 v45, v45, v45
	v_mul_f32_e32 v43, v43, v43
	v_max_f32_e32 v45, 0, v45
	v_mul_f32_e32 v44, v44, v44
	v_cvt_pk_bf16_f32 v42, v46, v42
	v_add_co_u32_e32 v46, vcc, s65, v146
	v_max_f32_e32 v34, v34, v34
; #define PG8_BAR __builtin_amdgcn_s_barrier()
; __device__ __forceinline__ unsigned cvt_pk_bf16(float lo, float hi) { unsigned r; asm volatile("v_cvt_pk_bf16_f32 %0, %1, %2" : "=v"(r) : "v"(lo), "v"(hi)); return r; }
; template <class Epi, class Sched, bool ALIGN_EPI = false, bool SP2 = false>
; __device__ __forceinline__ void gemm_phase(PG8_LAS unsigned char* lds, const Gemm g, const Sched& S, const Epi& E) {
;     ...
;         if (!has_next) break;
; #pragma unroll
;         for (int a = 0; a < 2; ++a)
; #pragma unroll
;             for (int b = 0; b < 2; ++b)
; #pragma unroll
;                 for (int m = 0; m < 4; ++m)
; #pragma unroll
;                     for (int n = 0; n < 2; ++n) acc[a][b][m][n] = (f32x4){0.f, 0.f, 0.f, 0.f};
;         cur = nxt; cA = nA; cB = nB; ++ui;
;         if constexpr (ALIGN_EPI) { if (wr == 1) PG8_BAR; }
;     __device__ __forceinline__ void operator()(const pg8::f32x4 (&acc)[2][2][4][2], const pg8::Unit& u, int wr, int wc, int fr, int fq) const {
;         const int row0 = NMETA + u.pm * 256 + wr * 64 + fr, col0 = u.pn * 256 + wc * 32 + 8 * fq;
; #pragma unroll
;         for (int ai = 0; ai < 2; ++ai)
; #pragma unroll
;             for (int m = 0; m < 4; ++m) { bf16_t* rowp = O + (size_t)(row0 + ai * 128 + m * 16) * DFF + col0;
; #pragma unroll
;                 for (int bj = 0; bj < 2; ++bj) { pg8::f32x4 v0 = acc[ai][bj][m][0], v1 = acc[ai][bj][m][1];
; #pragma unroll
;                     for (int i = 0; i < 4; ++i) { const float a = fmaxf(v0[i], 0.f), b = fmaxf(v1[i], 0.f); v0[i] = a * a; v1[i] = b * b; }
;                     u32x4 w; w.x = cvt_pk_bf16(v0[0], v0[1]); w.y = cvt_pk_bf16(v0[2], v0[3]); w.z = cvt_pk_bf16(v1[0], v1[1]); w.w = cvt_pk_bf16(v1[2], v1[3]);
;                     *(u32x4*)(rowp + bj * 128) = w; } }
	v_max_f32_e32 v35, v35, v35
	v_max_f32_e32 v36, v36, v36
	v_mul_f32_e32 v45, v45, v45
	v_cvt_pk_bf16_f32 v43, v43, v44
	v_cvt_pk_bf16_f32 v44, v52, v47
	v_addc_co_u32_e32 v47, vcc, 0, v147, vcc
	v_max_f32_e32 v34, 0, v34
	v_max_f32_e32 v35, 0, v35
	v_max_f32_e32 v36, 0, v36
	v_cvt_pk_bf16_f32 v45, v48, v45
	flat_store_dwordx4 v[46:47], v[42:45] nt
	v_max_f32_e32 v38, v38, v38
	v_max_f32_e32 v37, v37, v37
	v_mul_f32_e32 v42, v34, v34
	v_max_f32_e32 v34, v39, v39
	v_mul_f32_e32 v39, v35, v35
	v_max_f32_e32 v35, v40, v40
	v_mul_f32_e32 v40, v36, v36
	v_max_f32_e32 v36, v41, v41
	v_max_f32_e32 v34, 0, v34
	v_max_f32_e32 v35, 0, v35
	v_max_f32_e32 v36, 0, v36
	v_max_f32_e32 v38, 0, v38
	v_mul_f32_e32 v34, v34, v34
	v_mul_f32_e32 v35, v35, v35
	v_max_f32_e32 v37, 0, v37
	v_mul_f32_e32 v36, v36, v36
	v_max_f32_e32 v26, v26, v26
	v_lshl_add_u64 v[50:51], v[146:147], 0, s[26:27]
	v_mul_f32_e32 v38, v38, v38
	v_mul_f32_e32 v37, v37, v37
	v_cvt_pk_bf16_f32 v34, v38, v34
	v_cvt_pk_bf16_f32 v35, v35, v36
	v_cvt_pk_bf16_f32 v36, v42, v39
	v_max_f32_e32 v26, 0, v26
	v_max_f32_e32 v27, v27, v27
	v_max_f32_e32 v28, v28, v28
	v_cvt_pk_bf16_f32 v37, v40, v37
	flat_store_dwordx4 v[50:51], v[34:37] offset:256 nt
	v_max_f32_e32 v30, v30, v30
	v_max_f32_e32 v27, 0, v27
	v_mul_f32_e32 v36, v26, v26
	v_max_f32_e32 v26, v31, v31
	v_max_f32_e32 v28, 0, v28
	v_max_f32_e32 v30, 0, v30
	v_max_f32_e32 v26, 0, v26
	v_mul_f32_e32 v31, v27, v27
	v_max_f32_e32 v27, v32, v32
	v_mul_f32_e32 v32, v28, v28
	v_max_f32_e32 v28, v33, v33
	v_mul_f32_e32 v30, v30, v30
	v_mul_f32_e32 v26, v26, v26
	v_max_f32_e32 v27, 0, v27
	v_max_f32_e32 v28, 0, v28
	v_max_f32_e32 v29, v29, v29
	v_mul_f32_e32 v27, v27, v27
	v_max_f32_e32 v29, 0, v29
	v_mul_f32_e32 v28, v28, v28
	v_cvt_pk_bf16_f32 v26, v30, v26
	v_add_co_u32_e32 v30, vcc, s66, v146
	v_max_f32_e32 v18, v18, v18
	v_max_f32_e32 v19, v19, v19
	v_max_f32_e32 v20, v20, v20
	v_mul_f32_e32 v29, v29, v29
	v_cvt_pk_bf16_f32 v27, v27, v28
	v_cvt_pk_bf16_f32 v28, v36, v31
	v_addc_co_u32_e32 v31, vcc, 0, v147, vcc
	v_max_f32_e32 v18, 0, v18
	v_max_f32_e32 v19, 0, v19
	v_max_f32_e32 v20, 0, v20
	v_cvt_pk_bf16_f32 v29, v32, v29
	flat_store_dwordx4 v[30:31], v[26:29] nt
	v_max_f32_e32 v22, v22, v22
	v_max_f32_e32 v21, v21, v21
	v_mul_f32_e32 v26, v18, v18
	v_max_f32_e32 v18, v23, v23
	v_mul_f32_e32 v23, v19, v19
	v_max_f32_e32 v19, v24, v24
	v_mul_f32_e32 v24, v20, v20
	v_max_f32_e32 v20, v25, v25
	v_max_f32_e32 v18, 0, v18
	v_max_f32_e32 v19, 0, v19
	v_max_f32_e32 v20, 0, v20
	v_max_f32_e32 v22, 0, v22
	v_mul_f32_e32 v18, v18, v18
	v_mul_f32_e32 v19, v19, v19
	v_max_f32_e32 v21, 0, v21
	v_mul_f32_e32 v20, v20, v20
	v_max_f32_e32 v10, v10, v10
	v_lshl_add_u64 v[34:35], v[146:147], 0, s[28:29]
	v_mul_f32_e32 v22, v22, v22
	v_mul_f32_e32 v21, v21, v21
	v_cvt_pk_bf16_f32 v18, v22, v18
	v_cvt_pk_bf16_f32 v19, v19, v20
	v_cvt_pk_bf16_f32 v20, v26, v23
	v_max_f32_e32 v10, 0, v10
	v_max_f32_e32 v11, v11, v11
	v_max_f32_e32 v12, v12, v12
	v_cvt_pk_bf16_f32 v21, v24, v21
	flat_store_dwordx4 v[34:35], v[18:21] offset:256 nt
	v_max_f32_e32 v14, v14, v14
	v_max_f32_e32 v11, 0, v11
	v_mul_f32_e32 v20, v10, v10
	v_max_f32_e32 v10, v15, v15
	v_max_f32_e32 v12, 0, v12
	v_max_f32_e32 v14, 0, v14
	v_max_f32_e32 v10, 0, v10
	v_mul_f32_e32 v15, v11, v11
	v_max_f32_e32 v11, v16, v16
	v_mul_f32_e32 v16, v12, v12
	v_max_f32_e32 v12, v17, v17
	v_mul_f32_e32 v14, v14, v14
	v_mul_f32_e32 v10, v10, v10
	v_max_f32_e32 v11, 0, v11
	v_max_f32_e32 v12, 0, v12
	v_max_f32_e32 v13, v13, v13
	v_mul_f32_e32 v11, v11, v11
	v_max_f32_e32 v13, 0, v13
	v_mul_f32_e32 v12, v12, v12
	v_cvt_pk_bf16_f32 v10, v14, v10
	v_add_co_u32_e32 v14, vcc, s67, v146
	v_max_f32_e32 v2, v2, v2
	v_max_f32_e32 v3, v3, v3
	v_max_f32_e32 v4, v4, v4
	v_mul_f32_e32 v13, v13, v13
	v_cvt_pk_bf16_f32 v11, v11, v12
	v_cvt_pk_bf16_f32 v12, v20, v15
	v_addc_co_u32_e32 v15, vcc, 0, v147, vcc
	v_max_f32_e32 v2, 0, v2
	v_max_f32_e32 v3, 0, v3
	v_max_f32_e32 v4, 0, v4
	v_cvt_pk_bf16_f32 v13, v16, v13
	flat_store_dwordx4 v[14:15], v[10:13] nt
	v_max_f32_e32 v5, v5, v5
	v_max_f32_e32 v6, v6, v6
	v_mul_f32_e32 v10, v2, v2
	v_max_f32_e32 v2, v7, v7
	v_mul_f32_e32 v7, v3, v3
	v_max_f32_e32 v3, v8, v8
	v_mul_f32_e32 v8, v4, v4
	v_max_f32_e32 v4, v9, v9
	v_max_f32_e32 v2, 0, v2
	v_max_f32_e32 v3, 0, v3
	v_max_f32_e32 v4, 0, v4
	v_max_f32_e32 v5, 0, v5
	v_lshl_add_u64 v[18:19], v[146:147], 0, s[30:31]
	v_max_f32_e32 v6, 0, v6
	v_mul_f32_e32 v2, v2, v2
	v_mul_f32_e32 v3, v3, v3
	v_mul_f32_e32 v4, v4, v4
	v_mul_f32_e32 v5, v5, v5
	s_andn2_b64 vcc, exec, s[6:7]
	s_mov_b64 s[6:7], -1
	v_mul_f32_e32 v6, v6, v6
	v_cvt_pk_bf16_f32 v2, v6, v2
	v_cvt_pk_bf16_f32 v3, v3, v4
	v_cvt_pk_bf16_f32 v4, v10, v7
	v_cvt_pk_bf16_f32 v5, v8, v5
	flat_store_dwordx4 v[18:19], v[2:5] offset:256 nt
	s_cbranch_vccnz .LBB0_2710
	s_andn2_b64 vcc, exec, s[14:15]
	s_cbranch_vccnz .LBB0_2709
	s_barrier
	s_branch .LBB0_2709
